# K-loop LDS-DMA issue rebalanced 2/6/2/6 to 4/4/4/4 (SA(0,0) to phase3, SA(1,0) to next phase1), waits 8/6/8/6
# speedup vs baseline: 1.0009x; 1.0009x over previous
; #define PG8_STAGE(bufoff, gbase, voff) do { _Pragma("unroll") for (int _i = 0; _i < 2; ++_i) \
;         __builtin_amdgcn_global_load_lds((const unsigned*)((const char*)(gbase) + (voff)[_i]), (LAS unsigned*)(lds + (bufoff) + ldsw + _i * 8192), 16, 0, 0); } while (0)
; #define PG8_WAIT_V(n) asm volatile("s_waitcnt vmcnt(" #n ")" ::: "memory")
; #define PG8_BAR __builtin_amdgcn_s_barrier()
; template <class Epi, bool ALIGN_EPI>
; DI void gemm_phase(LAS unsigned char* lds, const Sched& S, const Epi& E, int tid) {
;     const int wid = __builtin_amdgcn_readfirstlane(tid >> 6), lane = tid & 63, wr = wid >> 2, wc = wid & 3, fr = lane & 15, fq = lane >> 4;
;     const int lda = S.lda, ldb = S.ldb;
;     unsigned voffA[2], voffB[2];
; #pragma unroll
;     for (int i = 0; i < 2; ++i) { int R, C; stage_rc(tid * 16 + i * 8192, R, C); const int Rb = (R & ~31) + perm32(R & 31);
;         voffA[i] = (unsigned)(R * lda + C) * 2u; voffB[i] = (unsigned)(Rb * ldb + C) * 2u; }
;     const size_t kstep = (size_t)(BK * 2);
;     const size_t hstepA = (size_t)HALF * lda * 2, hstepB = (size_t)HALF * ldb * 2;
;     const unsigned ldsw = (unsigned)wid * 1024u;
;     const int aoff = lds_byte(wr * 64 + fr, fq * 8), boff = lds_byte(wc * 32 + fr, fq * 8);
;     ...
;     Unit cur, nxt; int ui = 0;
;     if (!S.next(0, cur)) return;
;     f32x4 acc[2][2][4][2];
; #pragma unroll
;     for (int a = 0; a < 2; ++a)
; #pragma unroll
;         for (int b = 0; b < 2; ++b)
; #pragma unroll
;             for (int m = 0; m < 4; ++m)
; #pragma unroll
;                 for (int n = 0; n < 2; ++n) acc[a][b][m][n] = (f32x4){0.f, 0.f, 0.f, 0.f};
;     bf16x8 At[4][2], B0[2][2], B1[2][2];
;     const char* cA = cur.a; const char* cB = cur.b;
;     PG8_STAGE(PG8_SB(0, 0), cB, voffB); PG8_STAGE(PG8_SB(0, 1), cB + hstepB, voffB); PG8_STAGE(PG8_SA(0, 0), cA, voffA); PG8_STAGE(PG8_SA(0, 1), cA + hstepA, voffA);
;     if (wr == 1) PG8_BAR;
;     PG8_WAIT_V(2); PG8_BAR;
;     PG8_STAGE(PG8_SB(1, 0), cB + kstep, voffB); PG8_STAGE(PG8_SA(1, 0), cA + kstep, voffA); PG8_STAGE(PG8_SB(1, 1), cB + hstepB + kstep, voffB);
;     PG8_WAIT_V(6); PG8_BAR;
.LBB0_319:
	s_add_u32 s4, s96, 0x16b00000
	s_addc_u32 s5, s97, 0
	s_lshl_b32 s9, s9, 5
	s_and_b32 s9, s9, 0x60
	s_add_i32 m0, s17, 0x18000
	v_lshl_add_u64 v[10:11], v[10:11], 0, s[84:85]
	s_lshl_b32 s12, s8, 13
	s_lshl_b32 s13, s9, 7
	s_waitcnt vmcnt(2)
	s_barrier
	global_load_lds_dwordx4 v[10:11], off
	v_lshl_add_u64 v[8:9], v[8:9], 0, s[84:85]
	s_add_i32 m0, s17, 0x1a000
	s_add_i32 s39, s17, 0x8000
	s_add_i32 s40, s17, 0xa000
	global_load_lds_dwordx4 v[8:9], off
	v_lshl_add_u64 v[4:5], v[4:5], 0, s[84:85]
	s_mov_b32 m0, s39
	s_add_u32 s10, s24, 0x40080
	v_mov_b64_e32 v[230:231], v[4:5]
	global_load_lds_dwordx4 v[4:5], off
	v_lshl_add_u64 v[4:5], v[6:7], 0, s[84:85]
	s_mov_b32 m0, s40
	s_addc_u32 s11, s25, 0
	v_mov_b64_e32 v[232:233], v[4:5]
	global_load_lds_dwordx4 v[4:5], off
	s_add_i32 m0, s17, 0x1c000
	v_lshl_add_u64 v[4:5], s[10:11], 0, v[136:137]
	global_load_lds_dwordx4 v[4:5], off
	v_lshl_add_u64 v[4:5], s[10:11], 0, v[132:133]
	s_add_i32 m0, s17, 0x1e000
	s_sext_i32_i16 s43, s6
	global_load_lds_dwordx4 v[4:5], off
	v_lshrrev_b32_e32 v5, 1, v0
	v_and_b32_e32 v5, 24, v5
	s_lshl_b32 s6, s8, 8
	v_and_b32_e32 v4, 15, v0
	v_lshlrev_b32_e32 v6, 1, v5
	s_add_i32 s6, s6, 0
	v_lshl_or_b32 v3, s8, 6, v4
	v_lshl_or_b32 v6, v4, 6, v6
	v_lshlrev_b32_e32 v4, 2, v4
	s_add_i32 s6, s6, 0x20000
	v_and_b32_e32 v7, 32, v4
	v_add_u32_e32 v145, s6, v4
	v_lshlrev_b32_e32 v4, 14, v16
	v_and_b32_e32 v4, 0xffff8000, v4
	v_or_b32_e32 v146, s9, v5
	v_lshl_add_u32 v4, v15, 11, v4
	v_and_b32_e32 v5, 1, v16
	v_lshl_or_b32 v4, v5, 6, v4
	v_lshl_add_u32 v140, v17, 1, v4
	v_lshlrev_b32_e32 v4, 14, v12
	v_and_b32_e32 v4, 0xffff8000, v4
	s_waitcnt vmcnt(6)
	v_lshl_add_u32 v4, v13, 11, v4
	v_and_b32_e32 v5, 1, v12
	v_bitop3_b32 v8, v6, s12, v7 bitop3:0xde
	s_cmpk_lt_u32 s7, 0x100
	v_lshl_or_b32 v4, v5, 6, v4
	v_bitop3_b32 v144, s13, v6, v7 bitop3:0xf6
	s_cselect_b64 s[6:7], -1, 0
	v_mov_b32_e32 v141, v2
	v_lshl_add_u32 v142, v14, 1, v4
	v_mov_b32_e32 v143, v2
	s_mov_b32 s44, 0
	v_add_u32_e32 v147, 0, v8
	s_mov_b32 s41, 0
	s_barrier
	s_waitcnt vmcnt(0)
	s_branch .LBB0_322

; #define PG8_STAGE(bufoff, gbase, voff) do { _Pragma("unroll") for (int _i = 0; _i < 2; ++_i) \
;         __builtin_amdgcn_global_load_lds((const unsigned*)((const char*)(gbase) + (voff)[_i]), (LAS unsigned*)(lds + (bufoff) + ldsw + _i * 8192), 16, 0, 0); } while (0)
; #define PG8_LDA(dst, b, h) do { _Pragma("unroll") for (int m = 0; m < 4; ++m) _Pragma("unroll") for (int k = 0; k < 2; ++k) dst[m][k] = *(const LAS bf16x8*)(lds + PG8_SA(b, h) + aoff + m * 2048 + k * 1024); } while (0)
; #define PG8_LDB(dst, b, h) do { _Pragma("unroll") for (int n = 0; n < 2; ++n) _Pragma("unroll") for (int k = 0; k < 2; ++k) dst[n][k] = *(const LAS bf16x8*)(lds + PG8_SB(b, h) + boff + n * 2048 + k * 1024); } while (0)
; #define PG8_MMA(ai, bj, At, Bt) do { __builtin_amdgcn_s_setprio(1); _Pragma("unroll") for (int m = 0; m < 4; ++m) _Pragma("unroll") for (int n = 0; n < 2; ++n) _Pragma("unroll") for (int k = 0; k < 2; ++k) \
;         acc[ai][bj][m][n] = __builtin_amdgcn_mfma_f32_16x16x32_bf16(Bt[n][k], At[m][k], acc[ai][bj][m][n], 0, 0, 0); __builtin_amdgcn_s_setprio(0); } while (0)
; #define PG8_WAIT_V(n) asm volatile("s_waitcnt vmcnt(" #n ")" ::: "memory")
; #define PG8_WAIT_L(n) asm volatile("s_waitcnt lgkmcnt(" #n ")" ::: "memory")
; #define PG8_BAR __builtin_amdgcn_s_barrier()
; #define PG8_SCHED __builtin_amdgcn_sched_barrier(0)
; template <class Epi, bool ALIGN_EPI>
; DI void gemm_phase(LAS unsigned char* lds, const Sched& S, const Epi& E, int tid) {
;     ...
;         for (int t = 0; t < nt; t += 2) {
;             const bool last = (t == nt - 2);
;             const char* a1 = cA + (size_t)(t + 1) * kstep;
;             const char* a2 = last ? nA : cA + (size_t)(t + 2) * kstep; const char* b2 = last ? nB : cB + (size_t)(t + 2) * kstep;
;             const char* a3 = a2 + kstep; const char* b3 = b2 + kstep;
;             PG8_LDB(B0, 0, 0); PG8_LDB(B1, 0, 1); PG8_SCHED; PG8_LDA(At, 0, 0); PG8_STAGE(PG8_SA(1, 1), a1 + hstepA, voffA);
;             PG8_WAIT_V(8); PG8_WAIT_L(0); PG8_BAR; PG8_MMA(0, 0, At, B0); PG8_MMA(0, 1, At, B1); PG8_BAR; PG8_SCHED;
;             PG8_LDA(At, 0, 1); PG8_STAGE(PG8_SB(0, 0), b2, voffB); PG8_STAGE(PG8_SB(0, 1), b2 + hstepB, voffB); PG8_STAGE(PG8_SA(0, 0), a2, voffA);
;             PG8_WAIT_V(8); PG8_WAIT_L(0); PG8_BAR; PG8_MMA(1, 0, At, B0); PG8_MMA(1, 1, At, B1); PG8_BAR; PG8_SCHED;
.LBB0_325:
	s_add_u32 s24, s22, 0xfffc0080
	s_addc_u32 s25, s23, -1
	s_add_i32 s48, 0, 0x10000
	s_cmp_eq_u32 s47, 12
	s_cselect_b32 s27, s19, s25
	s_cselect_b32 s26, s18, s24
	v_add_u32_e32 v161, s48, v144
	s_cselect_b32 s25, s21, s46
	s_cselect_b32 s24, s20, s45
	s_add_i32 s50, 0, 0x14000
	ds_read_b128 v[148:151], v161
	ds_read_b128 v[152:155], v161 offset:1024
	ds_read_b128 v[156:159], v161 offset:2048
	ds_read_b128 v[162:165], v161 offset:3072
	v_add_u32_e32 v161, s50, v144
	ds_read_b128 v[166:169], v161
	ds_read_b128 v[170:173], v161 offset:1024
	ds_read_b128 v[174:177], v161 offset:2048
	ds_read_b128 v[178:181], v161 offset:3072
	v_lshl_add_u64 v[194:195], s[22:23], 0, v[140:141]
	s_mov_b32 m0, s39
	s_nop 0
	global_load_lds_dwordx4 v[230:231], off
	s_mov_b32 m0, s40
	s_nop 0
	global_load_lds_dwordx4 v[232:233], off
	s_add_i32 m0, s17, 0xc000
	ds_read_b128 v[182:185], v147
	ds_read_b128 v[186:189], v147 offset:1024
	ds_read_b128 v[190:193], v147 offset:2048
	ds_read_b128 v[202:205], v147 offset:3072
	ds_read_b128 v[206:209], v147 offset:4096
	ds_read_b128 v[210:213], v147 offset:5120
	ds_read_b128 v[214:217], v147 offset:6144
	ds_read_b128 v[218:221], v147 offset:7168
	global_load_lds_dwordx4 v[194:195], off
	v_lshl_add_u64 v[194:195], s[22:23], 0, v[142:143]
	s_add_i32 m0, s17, 0xe000
	s_nop 0
	global_load_lds_dwordx4 v[194:195], off
	s_waitcnt vmcnt(8)
	s_waitcnt lgkmcnt(0)
	s_barrier
	s_setprio 1
	s_waitcnt lgkmcnt(0)
	v_mfma_f32_16x16x32_bf16 v[128:131], v[148:151], v[182:185], v[128:131]
	v_mfma_f32_16x16x32_bf16 v[124:127], v[156:159], v[182:185], v[124:127]
	v_mfma_f32_16x16x32_bf16 v[112:115], v[148:151], v[190:193], v[112:115]
	v_mfma_f32_16x16x32_bf16 v[108:111], v[156:159], v[190:193], v[108:111]
	v_mfma_f32_16x16x32_bf16 v[96:99], v[148:151], v[206:209], v[96:99]
	v_mfma_f32_16x16x32_bf16 v[92:95], v[156:159], v[206:209], v[92:95]
	v_mfma_f32_16x16x32_bf16 v[80:83], v[148:151], v[214:217], v[80:83]
	v_mfma_f32_16x16x32_bf16 v[76:79], v[156:159], v[214:217], v[76:79]
	v_mfma_f32_16x16x32_bf16 v[128:131], v[152:155], v[186:189], v[128:131]
	v_mfma_f32_16x16x32_bf16 v[124:127], v[162:165], v[186:189], v[124:127]
	v_mfma_f32_16x16x32_bf16 v[112:115], v[152:155], v[202:205], v[112:115]
	v_mfma_f32_16x16x32_bf16 v[108:111], v[162:165], v[202:205], v[108:111]
	v_mfma_f32_16x16x32_bf16 v[96:99], v[152:155], v[210:213], v[96:99]
	v_mfma_f32_16x16x32_bf16 v[92:95], v[162:165], v[210:213], v[92:95]
	v_mfma_f32_16x16x32_bf16 v[80:83], v[152:155], v[218:221], v[80:83]
	v_mfma_f32_16x16x32_bf16 v[76:79], v[162:165], v[218:221], v[76:79]
	s_setprio 0
	s_setprio 1
	v_mfma_f32_16x16x32_bf16 v[120:123], v[166:169], v[182:185], v[120:123]
	v_mfma_f32_16x16x32_bf16 v[116:119], v[174:177], v[182:185], v[116:119]
	v_mfma_f32_16x16x32_bf16 v[104:107], v[166:169], v[190:193], v[104:107]
	v_mfma_f32_16x16x32_bf16 v[100:103], v[174:177], v[190:193], v[100:103]
	v_mfma_f32_16x16x32_bf16 v[88:91], v[166:169], v[206:209], v[88:91]
	v_mfma_f32_16x16x32_bf16 v[84:87], v[174:177], v[206:209], v[84:87]
	v_mfma_f32_16x16x32_bf16 v[72:75], v[166:169], v[214:217], v[72:75]
	v_mfma_f32_16x16x32_bf16 v[68:71], v[174:177], v[214:217], v[68:71]
	v_mfma_f32_16x16x32_bf16 v[120:123], v[170:173], v[186:189], v[120:123]
	v_mfma_f32_16x16x32_bf16 v[116:119], v[178:181], v[186:189], v[116:119]
	v_mfma_f32_16x16x32_bf16 v[104:107], v[170:173], v[202:205], v[104:107]
	v_mfma_f32_16x16x32_bf16 v[100:103], v[178:181], v[202:205], v[100:103]
	v_mfma_f32_16x16x32_bf16 v[88:91], v[170:173], v[210:213], v[88:91]
	v_mfma_f32_16x16x32_bf16 v[84:87], v[178:181], v[210:213], v[84:87]
	v_mfma_f32_16x16x32_bf16 v[72:75], v[170:173], v[218:221], v[72:75]
	v_mfma_f32_16x16x32_bf16 v[68:71], v[178:181], v[218:221], v[68:71]
	s_setprio 0
	s_barrier
	s_add_i32 s48, s48, s28
	v_lshl_add_u64 v[194:195], s[24:25], 0, v[136:137]
	s_mov_b32 m0, s48
	ds_read_b128 v[182:185], v147 offset:16384
	ds_read_b128 v[186:189], v147 offset:17408
	ds_read_b128 v[190:193], v147 offset:18432
	ds_read_b128 v[202:205], v147 offset:19456
	ds_read_b128 v[206:209], v147 offset:20480
	ds_read_b128 v[210:213], v147 offset:21504
	ds_read_b128 v[214:217], v147 offset:22528
	ds_read_b128 v[218:221], v147 offset:23552
	global_load_lds_dwordx4 v[194:195], off
	s_add_i32 m0, s48, 0x2000
	s_add_u32 s48, s24, 0x40000
	v_lshl_add_u64 v[222:223], s[24:25], 0, v[132:133]
	s_addc_u32 s49, s25, 0
	s_add_i32 s50, s50, s28
	global_load_lds_dwordx4 v[222:223], off
	v_lshl_add_u64 v[224:225], s[48:49], 0, v[136:137]
	s_mov_b32 m0, s50
	v_lshl_add_u64 v[226:227], s[26:27], 0, v[134:135]
	global_load_lds_dwordx4 v[224:225], off
	v_lshl_add_u64 v[224:225], s[48:49], 0, v[132:133]
	s_add_i32 m0, s50, 0x2000
	s_nop 0
	global_load_lds_dwordx4 v[224:225], off
	v_lshl_add_u64 v[224:225], s[26:27], 0, v[138:139]
	s_waitcnt vmcnt(6)
	s_waitcnt lgkmcnt(0)
	s_barrier
; #define PG8_STAGE(bufoff, gbase, voff) do { _Pragma("unroll") for (int _i = 0; _i < 2; ++_i) \
;         __builtin_amdgcn_global_load_lds((const unsigned*)((const char*)(gbase) + (voff)[_i]), (LAS unsigned*)(lds + (bufoff) + ldsw + _i * 8192), 16, 0, 0); } while (0)
; #define PG8_LDA(dst, b, h) do { _Pragma("unroll") for (int m = 0; m < 4; ++m) _Pragma("unroll") for (int k = 0; k < 2; ++k) dst[m][k] = *(const LAS bf16x8*)(lds + PG8_SA(b, h) + aoff + m * 2048 + k * 1024); } while (0)
; #define PG8_LDB(dst, b, h) do { _Pragma("unroll") for (int n = 0; n < 2; ++n) _Pragma("unroll") for (int k = 0; k < 2; ++k) dst[n][k] = *(const LAS bf16x8*)(lds + PG8_SB(b, h) + boff + n * 2048 + k * 1024); } while (0)
; #define PG8_MMA(ai, bj, At, Bt) do { __builtin_amdgcn_s_setprio(1); _Pragma("unroll") for (int m = 0; m < 4; ++m) _Pragma("unroll") for (int n = 0; n < 2; ++n) _Pragma("unroll") for (int k = 0; k < 2; ++k) \
;         acc[ai][bj][m][n] = __builtin_amdgcn_mfma_f32_16x16x32_bf16(Bt[n][k], At[m][k], acc[ai][bj][m][n], 0, 0, 0); __builtin_amdgcn_s_setprio(0); } while (0)
; #define PG8_WAIT_V(n) asm volatile("s_waitcnt vmcnt(" #n ")" ::: "memory")
; #define PG8_WAIT_L(n) asm volatile("s_waitcnt lgkmcnt(" #n ")" ::: "memory")
; #define PG8_BAR __builtin_amdgcn_s_barrier()
; #define PG8_SCHED __builtin_amdgcn_sched_barrier(0)
; template <class Epi, bool ALIGN_EPI>
; DI void gemm_phase(LAS unsigned char* lds, const Sched& S, const Epi& E, int tid) {
;     ...
;             PG8_WAIT_V(8); PG8_WAIT_L(0); PG8_BAR; PG8_MMA(0, 0, At, B0); PG8_MMA(0, 1, At, B1); PG8_BAR; PG8_SCHED;
;             PG8_LDA(At, 0, 1); PG8_STAGE(PG8_SB(0, 0), b2, voffB); PG8_STAGE(PG8_SB(0, 1), b2 + hstepB, voffB); PG8_STAGE(PG8_SA(0, 0), a2, voffA);
;             PG8_WAIT_V(8); PG8_WAIT_L(0); PG8_BAR; PG8_MMA(1, 0, At, B0); PG8_MMA(1, 1, At, B1); PG8_BAR; PG8_SCHED;
;             PG8_LDB(B0, 1, 0); PG8_LDB(B1, 1, 1); PG8_SCHED; PG8_LDA(At, 1, 0); PG8_STAGE(PG8_SA(0, 1), a2 + hstepA, voffA);
;             PG8_WAIT_V(8); PG8_WAIT_L(0); PG8_BAR; PG8_MMA(0, 0, At, B0); PG8_MMA(0, 1, At, B1); PG8_BAR; PG8_SCHED;
;             PG8_LDA(At, 1, 1); PG8_STAGE(PG8_SB(1, 0), b3, voffB); PG8_STAGE(PG8_SB(1, 1), b3 + hstepB, voffB); PG8_STAGE(PG8_SA(1, 0), a3, voffA);
	s_setprio 1
	s_waitcnt lgkmcnt(0)
	v_mfma_f32_16x16x32_bf16 v[64:67], v[148:151], v[182:185], v[64:67]
	v_mfma_f32_16x16x32_bf16 v[60:63], v[156:159], v[182:185], v[60:63]
	v_mfma_f32_16x16x32_bf16 v[48:51], v[148:151], v[190:193], v[48:51]
	v_mfma_f32_16x16x32_bf16 v[44:47], v[156:159], v[190:193], v[44:47]
	v_mfma_f32_16x16x32_bf16 v[32:35], v[148:151], v[206:209], v[32:35]
	v_mfma_f32_16x16x32_bf16 v[28:31], v[156:159], v[206:209], v[28:31]
	v_mfma_f32_16x16x32_bf16 v[16:19], v[148:151], v[214:217], v[16:19]
	v_mfma_f32_16x16x32_bf16 v[12:15], v[156:159], v[214:217], v[12:15]
	v_mfma_f32_16x16x32_bf16 v[64:67], v[152:155], v[186:189], v[64:67]
	v_mfma_f32_16x16x32_bf16 v[60:63], v[162:165], v[186:189], v[60:63]
	v_mfma_f32_16x16x32_bf16 v[48:51], v[152:155], v[202:205], v[48:51]
	v_mfma_f32_16x16x32_bf16 v[44:47], v[162:165], v[202:205], v[44:47]
	v_mfma_f32_16x16x32_bf16 v[32:35], v[152:155], v[210:213], v[32:35]
	v_mfma_f32_16x16x32_bf16 v[28:31], v[162:165], v[210:213], v[28:31]
	v_mfma_f32_16x16x32_bf16 v[16:19], v[152:155], v[218:221], v[16:19]
	v_mfma_f32_16x16x32_bf16 v[12:15], v[162:165], v[218:221], v[12:15]
	s_setprio 0
	s_setprio 1
	v_mfma_f32_16x16x32_bf16 v[56:59], v[166:169], v[182:185], v[56:59]
	v_mfma_f32_16x16x32_bf16 v[52:55], v[174:177], v[182:185], v[52:55]
	v_mfma_f32_16x16x32_bf16 v[40:43], v[166:169], v[190:193], v[40:43]
	v_mfma_f32_16x16x32_bf16 v[36:39], v[174:177], v[190:193], v[36:39]
	v_mfma_f32_16x16x32_bf16 v[24:27], v[166:169], v[206:209], v[24:27]
	v_mfma_f32_16x16x32_bf16 v[20:23], v[174:177], v[206:209], v[20:23]
	v_mfma_f32_16x16x32_bf16 v[8:11], v[166:169], v[214:217], v[8:11]
	v_mfma_f32_16x16x32_bf16 v[4:7], v[174:177], v[214:217], v[4:7]
	v_mfma_f32_16x16x32_bf16 v[56:59], v[170:173], v[186:189], v[56:59]
	v_mfma_f32_16x16x32_bf16 v[52:55], v[178:181], v[186:189], v[52:55]
	v_mfma_f32_16x16x32_bf16 v[40:43], v[170:173], v[202:205], v[40:43]
	v_mfma_f32_16x16x32_bf16 v[36:39], v[178:181], v[202:205], v[36:39]
	v_mfma_f32_16x16x32_bf16 v[24:27], v[170:173], v[210:213], v[24:27]
	v_mfma_f32_16x16x32_bf16 v[20:23], v[178:181], v[210:213], v[20:23]
	v_mfma_f32_16x16x32_bf16 v[8:11], v[170:173], v[218:221], v[8:11]
	v_mfma_f32_16x16x32_bf16 v[4:7], v[178:181], v[218:221], v[4:7]
	s_setprio 0
	s_barrier
	s_add_i32 s48, 0, 0x18000
	v_add_u32_e32 v161, s48, v144
	s_add_i32 s49, 0, 0x1c000
	ds_read_b128 v[148:151], v161
	ds_read_b128 v[152:155], v161 offset:1024
	ds_read_b128 v[156:159], v161 offset:2048
	ds_read_b128 v[162:165], v161 offset:3072
	v_add_u32_e32 v161, s49, v144
	ds_read_b128 v[166:169], v161
	ds_read_b128 v[170:173], v161 offset:1024
	ds_read_b128 v[174:177], v161 offset:2048
	ds_read_b128 v[178:181], v161 offset:3072
	s_add_u32 s26, s26, 0x40000
	s_addc_u32 s27, s27, 0
	s_mov_b32 m0, s17
	s_nop 0
	global_load_lds_dwordx4 v[224:225], off
	s_mov_b32 m0, s36
	s_nop 0
	global_load_lds_dwordx4 v[226:227], off
	s_mov_b32 m0, s37
	v_lshl_add_u64 v[228:229], s[26:27], 0, v[138:139]
	ds_read_b128 v[182:185], v147 offset:32768
	ds_read_b128 v[186:189], v147 offset:33792
	ds_read_b128 v[190:193], v147 offset:34816
	ds_read_b128 v[202:205], v147 offset:35840
	ds_read_b128 v[206:209], v147 offset:36864
	ds_read_b128 v[210:213], v147 offset:37888
	ds_read_b128 v[214:217], v147 offset:38912
	ds_read_b128 v[218:221], v147 offset:39936
	global_load_lds_dwordx4 v[228:229], off
	v_lshl_add_u64 v[228:229], s[26:27], 0, v[134:135]
	s_mov_b32 m0, s38
	s_nop 0
	global_load_lds_dwordx4 v[228:229], off
	s_waitcnt vmcnt(8)
	s_waitcnt lgkmcnt(0)
	s_barrier
	s_setprio 1
	s_waitcnt lgkmcnt(0)
	v_mfma_f32_16x16x32_bf16 v[128:131], v[148:151], v[182:185], v[128:131]
	v_mfma_f32_16x16x32_bf16 v[124:127], v[156:159], v[182:185], v[124:127]
	v_mfma_f32_16x16x32_bf16 v[112:115], v[148:151], v[190:193], v[112:115]
	v_mfma_f32_16x16x32_bf16 v[108:111], v[156:159], v[190:193], v[108:111]
	v_mfma_f32_16x16x32_bf16 v[96:99], v[148:151], v[206:209], v[96:99]
	v_mfma_f32_16x16x32_bf16 v[92:95], v[156:159], v[206:209], v[92:95]
	v_mfma_f32_16x16x32_bf16 v[80:83], v[148:151], v[214:217], v[80:83]
	v_mfma_f32_16x16x32_bf16 v[76:79], v[156:159], v[214:217], v[76:79]
	v_mfma_f32_16x16x32_bf16 v[128:131], v[152:155], v[186:189], v[128:131]
	v_mfma_f32_16x16x32_bf16 v[124:127], v[162:165], v[186:189], v[124:127]
	v_mfma_f32_16x16x32_bf16 v[112:115], v[152:155], v[202:205], v[112:115]
	v_mfma_f32_16x16x32_bf16 v[108:111], v[162:165], v[202:205], v[108:111]
	v_mfma_f32_16x16x32_bf16 v[96:99], v[152:155], v[210:213], v[96:99]
	v_mfma_f32_16x16x32_bf16 v[92:95], v[162:165], v[210:213], v[92:95]
	v_mfma_f32_16x16x32_bf16 v[80:83], v[152:155], v[218:221], v[80:83]
	v_mfma_f32_16x16x32_bf16 v[76:79], v[162:165], v[218:221], v[76:79]
	s_setprio 0
	s_setprio 1
	v_mfma_f32_16x16x32_bf16 v[120:123], v[166:169], v[182:185], v[120:123]
	v_mfma_f32_16x16x32_bf16 v[116:119], v[174:177], v[182:185], v[116:119]
	v_mfma_f32_16x16x32_bf16 v[104:107], v[166:169], v[190:193], v[104:107]
	v_mfma_f32_16x16x32_bf16 v[100:103], v[174:177], v[190:193], v[100:103]
	v_mfma_f32_16x16x32_bf16 v[88:91], v[166:169], v[206:209], v[88:91]
	v_mfma_f32_16x16x32_bf16 v[84:87], v[174:177], v[206:209], v[84:87]
	v_mfma_f32_16x16x32_bf16 v[72:75], v[166:169], v[214:217], v[72:75]
	v_mfma_f32_16x16x32_bf16 v[68:71], v[174:177], v[214:217], v[68:71]
	v_mfma_f32_16x16x32_bf16 v[120:123], v[170:173], v[186:189], v[120:123]
	v_mfma_f32_16x16x32_bf16 v[116:119], v[178:181], v[186:189], v[116:119]
	v_mfma_f32_16x16x32_bf16 v[104:107], v[170:173], v[202:205], v[104:107]
	v_mfma_f32_16x16x32_bf16 v[100:103], v[178:181], v[202:205], v[100:103]
	v_mfma_f32_16x16x32_bf16 v[88:91], v[170:173], v[210:213], v[88:91]
	v_mfma_f32_16x16x32_bf16 v[84:87], v[178:181], v[210:213], v[84:87]
	v_mfma_f32_16x16x32_bf16 v[72:75], v[170:173], v[218:221], v[72:75]
	v_mfma_f32_16x16x32_bf16 v[68:71], v[178:181], v[218:221], v[68:71]
	s_setprio 0
	s_barrier
; #define PG8_STAGE(bufoff, gbase, voff) do { _Pragma("unroll") for (int _i = 0; _i < 2; ++_i) \
;         __builtin_amdgcn_global_load_lds((const unsigned*)((const char*)(gbase) + (voff)[_i]), (LAS unsigned*)(lds + (bufoff) + ldsw + _i * 8192), 16, 0, 0); } while (0)
; #define PG8_LDA(dst, b, h) do { _Pragma("unroll") for (int m = 0; m < 4; ++m) _Pragma("unroll") for (int k = 0; k < 2; ++k) dst[m][k] = *(const LAS bf16x8*)(lds + PG8_SA(b, h) + aoff + m * 2048 + k * 1024); } while (0)
; #define PG8_MMA(ai, bj, At, Bt) do { __builtin_amdgcn_s_setprio(1); _Pragma("unroll") for (int m = 0; m < 4; ++m) _Pragma("unroll") for (int n = 0; n < 2; ++n) _Pragma("unroll") for (int k = 0; k < 2; ++k) \
;         acc[ai][bj][m][n] = __builtin_amdgcn_mfma_f32_16x16x32_bf16(Bt[n][k], At[m][k], acc[ai][bj][m][n], 0, 0, 0); __builtin_amdgcn_s_setprio(0); } while (0)
; #define PG8_WAIT_V(n) asm volatile("s_waitcnt vmcnt(" #n ")" ::: "memory")
; #define PG8_WAIT_L(n) asm volatile("s_waitcnt lgkmcnt(" #n ")" ::: "memory")
; #define PG8_BAR __builtin_amdgcn_s_barrier()
; #define PG8_SCHED __builtin_amdgcn_sched_barrier(0)
; template <class Epi, bool ALIGN_EPI>
; DI void gemm_phase(LAS unsigned char* lds, const Sched& S, const Epi& E, int tid) {
;     ...
;     for (;;) {
;         const bool has_next = S.next(ui + 1, nxt);
;         const char* nA = has_next ? nxt.a : cA; const char* nB = has_next ? nxt.b : cB;
;         const int nt = cur.nt;
;         for (int t = 0; t < nt; t += 2) {
;     ...
;             PG8_LDA(At, 1, 1); PG8_STAGE(PG8_SB(1, 0), b3, voffB); PG8_STAGE(PG8_SB(1, 1), b3 + hstepB, voffB); PG8_STAGE(PG8_SA(1, 0), a3, voffA);
;             PG8_WAIT_V(8); PG8_WAIT_L(0); PG8_BAR; PG8_MMA(1, 0, At, B0); PG8_MMA(1, 1, At, B1); PG8_BAR; PG8_SCHED;
;         }
	s_add_i32 s26, s48, s28
	v_lshl_add_u64 v[194:195], v[194:195], 0, s[84:85]
	s_mov_b32 m0, s26
	ds_read_b128 v[182:185], v147 offset:49152
	ds_read_b128 v[186:189], v147 offset:50176
	ds_read_b128 v[190:193], v147 offset:51200
	ds_read_b128 v[202:205], v147 offset:52224
	ds_read_b128 v[206:209], v147 offset:53248
	ds_read_b128 v[210:213], v147 offset:54272
	ds_read_b128 v[214:217], v147 offset:55296
	ds_read_b128 v[218:221], v147 offset:56320
	global_load_lds_dwordx4 v[194:195], off
	s_add_i32 m0, s26, 0x2000
	s_add_u32 s24, s24, 0x40080
	v_lshl_add_u64 v[194:195], v[222:223], 0, s[84:85]
	s_addc_u32 s25, s25, 0
	s_add_i32 s26, s49, s28
	global_load_lds_dwordx4 v[194:195], off
	v_lshl_add_u64 v[194:195], s[24:25], 0, v[136:137]
	s_mov_b32 m0, s26
	s_nop 0
	global_load_lds_dwordx4 v[194:195], off
	v_lshl_add_u64 v[194:195], s[24:25], 0, v[132:133]
	s_add_i32 m0, s26, 0x2000
	s_nop 0
	global_load_lds_dwordx4 v[194:195], off
	v_lshl_add_u64 v[230:231], v[224:225], 0, s[84:85]
	v_lshl_add_u64 v[232:233], v[226:227], 0, s[84:85]
	s_waitcnt vmcnt(6)
	s_waitcnt lgkmcnt(0)
	s_barrier
	s_setprio 1
	s_waitcnt lgkmcnt(0)
	v_mfma_f32_16x16x32_bf16 v[64:67], v[148:151], v[182:185], v[64:67]
	v_mfma_f32_16x16x32_bf16 v[60:63], v[156:159], v[182:185], v[60:63]
	v_mfma_f32_16x16x32_bf16 v[48:51], v[148:151], v[190:193], v[48:51]
	v_mfma_f32_16x16x32_bf16 v[44:47], v[156:159], v[190:193], v[44:47]
	v_mfma_f32_16x16x32_bf16 v[32:35], v[148:151], v[206:209], v[32:35]
	v_mfma_f32_16x16x32_bf16 v[28:31], v[156:159], v[206:209], v[28:31]
	v_mfma_f32_16x16x32_bf16 v[16:19], v[148:151], v[214:217], v[16:19]
	v_mfma_f32_16x16x32_bf16 v[12:15], v[156:159], v[214:217], v[12:15]
	v_mfma_f32_16x16x32_bf16 v[64:67], v[152:155], v[186:189], v[64:67]
	v_mfma_f32_16x16x32_bf16 v[60:63], v[162:165], v[186:189], v[60:63]
	v_mfma_f32_16x16x32_bf16 v[48:51], v[152:155], v[202:205], v[48:51]
	v_mfma_f32_16x16x32_bf16 v[44:47], v[162:165], v[202:205], v[44:47]
	v_mfma_f32_16x16x32_bf16 v[32:35], v[152:155], v[210:213], v[32:35]
	v_mfma_f32_16x16x32_bf16 v[28:31], v[162:165], v[210:213], v[28:31]
	v_mfma_f32_16x16x32_bf16 v[16:19], v[152:155], v[218:221], v[16:19]
	v_mfma_f32_16x16x32_bf16 v[12:15], v[162:165], v[218:221], v[12:15]
	s_setprio 0
	s_setprio 1
	v_mfma_f32_16x16x32_bf16 v[56:59], v[166:169], v[182:185], v[56:59]
	v_mfma_f32_16x16x32_bf16 v[52:55], v[174:177], v[182:185], v[52:55]
	v_mfma_f32_16x16x32_bf16 v[40:43], v[166:169], v[190:193], v[40:43]
	v_mfma_f32_16x16x32_bf16 v[36:39], v[174:177], v[190:193], v[36:39]
	v_mfma_f32_16x16x32_bf16 v[24:27], v[166:169], v[206:209], v[24:27]
	v_mfma_f32_16x16x32_bf16 v[20:23], v[174:177], v[206:209], v[20:23]
	v_mfma_f32_16x16x32_bf16 v[8:11], v[166:169], v[214:217], v[8:11]
	v_mfma_f32_16x16x32_bf16 v[4:7], v[174:177], v[214:217], v[4:7]
	v_mfma_f32_16x16x32_bf16 v[56:59], v[170:173], v[186:189], v[56:59]
	v_mfma_f32_16x16x32_bf16 v[52:55], v[178:181], v[186:189], v[52:55]
	v_mfma_f32_16x16x32_bf16 v[40:43], v[170:173], v[202:205], v[40:43]
	v_mfma_f32_16x16x32_bf16 v[36:39], v[178:181], v[202:205], v[36:39]
	v_mfma_f32_16x16x32_bf16 v[24:27], v[170:173], v[210:213], v[24:27]
	v_mfma_f32_16x16x32_bf16 v[20:23], v[178:181], v[210:213], v[20:23]
	v_mfma_f32_16x16x32_bf16 v[8:11], v[170:173], v[218:221], v[8:11]
	v_mfma_f32_16x16x32_bf16 v[4:7], v[178:181], v[218:221], v[4:7]
	s_setprio 0
	s_barrier
	s_add_i32 s47, s47, 2
	s_add_u32 s22, s22, 0x100
	s_addc_u32 s23, s23, 0
	s_add_u32 s45, s45, 0x100
	s_addc_u32 s46, s46, 0
	s_cmp_gt_u32 s47, 13
	s_cbranch_scc0 .LBB0_325
	s_and_b64 vcc, exec, s[6:7]
	s_cbranch_vccz .LBB0_328
	s_barrier

; #define PG8_STAGE(bufoff, gbase, voff) do { _Pragma("unroll") for (int _i = 0; _i < 2; ++_i) \
;         __builtin_amdgcn_global_load_lds((const unsigned*)((const char*)(gbase) + (voff)[_i]), (LAS unsigned*)(lds + (bufoff) + ldsw + _i * 8192), 16, 0, 0); } while (0)
; #define PG8_WAIT_V(n) asm volatile("s_waitcnt vmcnt(" #n ")" ::: "memory")
; #define PG8_BAR __builtin_amdgcn_s_barrier()
; template <class Epi, bool ALIGN_EPI>
; DI void gemm_phase(LAS unsigned char* lds, const Sched& S, const Epi& E, int tid) {
;     const int wid = __builtin_amdgcn_readfirstlane(tid >> 6), lane = tid & 63, wr = wid >> 2, wc = wid & 3, fr = lane & 15, fq = lane >> 4;
;     const int lda = S.lda, ldb = S.ldb;
;     unsigned voffA[2], voffB[2];
; #pragma unroll
;     for (int i = 0; i < 2; ++i) { int R, C; stage_rc(tid * 16 + i * 8192, R, C); const int Rb = (R & ~31) + perm32(R & 31);
;         voffA[i] = (unsigned)(R * lda + C) * 2u; voffB[i] = (unsigned)(Rb * ldb + C) * 2u; }
;     const size_t kstep = (size_t)(BK * 2);
;     const size_t hstepA = (size_t)HALF * lda * 2, hstepB = (size_t)HALF * ldb * 2;
;     const unsigned ldsw = (unsigned)wid * 1024u;
;     const int aoff = lds_byte(wr * 64 + fr, fq * 8), boff = lds_byte(wc * 32 + fr, fq * 8);
;     ...
;     Unit cur, nxt; int ui = 0;
;     if (!S.next(0, cur)) return;
;     f32x4 acc[2][2][4][2];
; #pragma unroll
;     for (int a = 0; a < 2; ++a)
; #pragma unroll
;         for (int b = 0; b < 2; ++b)
; #pragma unroll
;             for (int m = 0; m < 4; ++m)
; #pragma unroll
;                 for (int n = 0; n < 2; ++n) acc[a][b][m][n] = (f32x4){0.f, 0.f, 0.f, 0.f};
;     bf16x8 At[4][2], B0[2][2], B1[2][2];
;     const char* cA = cur.a; const char* cB = cur.b;
;     PG8_STAGE(PG8_SB(0, 0), cB, voffB); PG8_STAGE(PG8_SB(0, 1), cB + hstepB, voffB); PG8_STAGE(PG8_SA(0, 0), cA, voffA); PG8_STAGE(PG8_SA(0, 1), cA + hstepA, voffA);
;     if (wr == 1) PG8_BAR;
;     PG8_WAIT_V(2); PG8_BAR;
;     PG8_STAGE(PG8_SB(1, 0), cB + kstep, voffB); PG8_STAGE(PG8_SA(1, 0), cA + kstep, voffA); PG8_STAGE(PG8_SB(1, 1), cB + hstepB + kstep, voffB);
;     PG8_WAIT_V(6); PG8_BAR;
.LBB0_399:
	v_bfe_u32 v21, v0, 4, 2
	v_and_b32_e32 v20, 15, v0
	v_lshlrev_b32_e32 v23, 4, v21
	v_lshl_or_b32 v3, s3, 6, v20
	v_lshl_or_b32 v20, v20, 6, v23
	v_lshlrev_b32_e32 v23, 2, v0
	s_and_b32 s43, s2, 3
	s_lshl_b32 s2, s3, 13
	v_and_b32_e32 v23, 32, v23
	s_add_i32 m0, s39, 0x18000
	v_lshl_add_u64 v[10:11], v[10:11], 0, s[84:85]
	v_bitop3_b32 v24, v20, s2, v23 bitop3:0xde
	s_lshl_b32 s2, s43, 12
	s_waitcnt vmcnt(2)
	s_barrier
	global_load_lds_dwordx4 v[10:11], off
	v_lshl_add_u64 v[8:9], v[8:9], 0, s[84:85]
	s_add_i32 m0, s39, 0x1a000
	s_add_i32 s44, s39, 0x8000
	s_add_i32 s45, s39, 0xa000
	v_bitop3_b32 v161, s2, v20, v23 bitop3:0xf6
	global_load_lds_dwordx4 v[8:9], off
	v_lshl_add_u64 v[4:5], v[4:5], 0, s[84:85]
	s_mov_b32 m0, s44
	s_add_u32 s2, s22, 0x104080
	v_mov_b64_e32 v[230:231], v[4:5]
	global_load_lds_dwordx4 v[4:5], off
	v_lshl_add_u64 v[4:5], v[6:7], 0, s[84:85]
	s_mov_b32 m0, s45
	s_addc_u32 s3, s23, 0
	v_mov_b64_e32 v[232:233], v[4:5]
	global_load_lds_dwordx4 v[4:5], off
	s_add_i32 m0, s39, 0x1c000
	v_lshl_add_u64 v[4:5], s[2:3], 0, v[164:165]
	global_load_lds_dwordx4 v[4:5], off
	v_lshl_add_u64 v[4:5], s[2:3], 0, v[168:169]
	s_add_i32 m0, s39, 0x1e000
	s_movk_i32 s14, 0x1040
	global_load_lds_dwordx4 v[4:5], off
	s_cmpk_lt_u32 s6, 0x100
	v_lshrrev_b32_e32 v5, 1, v12
	v_mul_lo_u32 v4, v14, s14
	s_mov_b32 s15, 0x10400
	s_cselect_b64 s[6:7], -1, 0
	s_add_u32 s47, s96, 0x1ff00000
	v_mad_u64_u32 v[4:5], s[12:13], v5, s15, v[4:5]
	s_addc_u32 s48, s97, 0
	v_or_b32_e32 v4, v4, v13
	s_add_u32 s8, s96, 0xff00000
	v_add_lshl_u32 v4, v4, v15, 1
	v_mov_b32_e32 v5, v2
	s_mov_b64 s[16:17], 0x104080
	s_mul_i32 s10, s90, 0x480000
	s_addc_u32 s9, s97, 0
	v_lshl_add_u64 v[170:171], v[4:5], 0, s[16:17]
	v_lshrrev_b32_e32 v5, 1, v16
	v_mul_lo_u32 v4, v18, s14
	s_add_u32 s10, s96, s10
	v_mad_u64_u32 v[4:5], s[12:13], v5, s15, v[4:5]
	s_waitcnt vmcnt(6)
	s_addc_u32 s11, s97, 0
	v_or_b32_e32 v4, v4, v17
	v_lshlrev_b32_e32 v22, 3, v21
	s_add_u32 s10, s10, 0x24220000
	v_add_lshl_u32 v4, v4, v19, 1
	v_mov_b32_e32 v5, v2
	v_lshl_or_b32 v192, s43, 5, v22
	s_mov_b32 s46, 0
	v_cmp_eq_u32_e64 s[2:3], 0, v21
	s_addc_u32 s11, s11, 0
	v_lshl_add_u64 v[172:173], v[4:5], 0, s[16:17]
	v_add_u32_e32 v193, 0, v24
	s_barrier
	s_branch .LBB0_402

; #define PG8_STAGE(bufoff, gbase, voff) do { _Pragma("unroll") for (int _i = 0; _i < 2; ++_i) \
;         __builtin_amdgcn_global_load_lds((const unsigned*)((const char*)(gbase) + (voff)[_i]), (LAS unsigned*)(lds + (bufoff) + ldsw + _i * 8192), 16, 0, 0); } while (0)
; #define PG8_LDA(dst, b, h) do { _Pragma("unroll") for (int m = 0; m < 4; ++m) _Pragma("unroll") for (int k = 0; k < 2; ++k) dst[m][k] = *(const LAS bf16x8*)(lds + PG8_SA(b, h) + aoff + m * 2048 + k * 1024); } while (0)
; #define PG8_LDB(dst, b, h) do { _Pragma("unroll") for (int n = 0; n < 2; ++n) _Pragma("unroll") for (int k = 0; k < 2; ++k) dst[n][k] = *(const LAS bf16x8*)(lds + PG8_SB(b, h) + boff + n * 2048 + k * 1024); } while (0)
; #define PG8_MMA(ai, bj, At, Bt) do { __builtin_amdgcn_s_setprio(1); _Pragma("unroll") for (int m = 0; m < 4; ++m) _Pragma("unroll") for (int n = 0; n < 2; ++n) _Pragma("unroll") for (int k = 0; k < 2; ++k) \
;         acc[ai][bj][m][n] = __builtin_amdgcn_mfma_f32_16x16x32_bf16(Bt[n][k], At[m][k], acc[ai][bj][m][n], 0, 0, 0); __builtin_amdgcn_s_setprio(0); } while (0)
; #define PG8_WAIT_V(n) asm volatile("s_waitcnt vmcnt(" #n ")" ::: "memory")
; #define PG8_WAIT_L(n) asm volatile("s_waitcnt lgkmcnt(" #n ")" ::: "memory")
; #define PG8_BAR __builtin_amdgcn_s_barrier()
; #define PG8_SCHED __builtin_amdgcn_sched_barrier(0)
; template <class Epi, bool ALIGN_EPI>
; DI void gemm_phase(LAS unsigned char* lds, const Sched& S, const Epi& E, int tid) {
;     ...
;         for (int t = 0; t < nt; t += 2) {
;             const bool last = (t == nt - 2);
;             const char* a1 = cA + (size_t)(t + 1) * kstep;
;             const char* a2 = last ? nA : cA + (size_t)(t + 2) * kstep; const char* b2 = last ? nB : cB + (size_t)(t + 2) * kstep;
;             const char* a3 = a2 + kstep; const char* b3 = b2 + kstep;
;             PG8_LDB(B0, 0, 0); PG8_LDB(B1, 0, 1); PG8_SCHED; PG8_LDA(At, 0, 0); PG8_STAGE(PG8_SA(1, 1), a1 + hstepA, voffA);
;             PG8_WAIT_V(8); PG8_WAIT_L(0); PG8_BAR; PG8_MMA(0, 0, At, B0); PG8_MMA(0, 1, At, B1); PG8_BAR; PG8_SCHED;
;             PG8_LDA(At, 0, 1); PG8_STAGE(PG8_SB(0, 0), b2, voffB); PG8_STAGE(PG8_SB(0, 1), b2 + hstepB, voffB); PG8_STAGE(PG8_SA(0, 0), a2, voffA);
;             PG8_WAIT_V(8); PG8_WAIT_L(0); PG8_BAR; PG8_MMA(1, 0, At, B0); PG8_MMA(1, 1, At, B1); PG8_BAR; PG8_SCHED;
.LBB0_412:
	s_add_i32 s63, s24, 2
	s_add_u32 s22, s20, 0x100
	s_addc_u32 s23, s21, 0
	s_add_i32 s64, 0, 0x10000
	s_cmp_eq_u32 s60, s24
	s_cselect_b32 s27, s56, s23
	s_cselect_b32 s26, s57, s22
	s_cselect_b32 s25, s58, s62
	s_cselect_b32 s24, s59, s61
	s_add_i32 s65, 0, 0x14000
	v_add_u32_e32 v144, s64, v161
	v_add_u32_e32 v174, s65, v161
	ds_read_b128 v[132:135], v144
	ds_read_b128 v[136:139], v144 offset:1024
	ds_read_b128 v[140:143], v144 offset:2048
	ds_read_b128 v[144:147], v144 offset:3072
	ds_read_b128 v[148:151], v174
	ds_read_b128 v[152:155], v174 offset:1024
	ds_read_b128 v[156:159], v174 offset:2048
	ds_read_b128 v[174:177], v174 offset:3072
	v_lshl_add_u64 v[190:191], s[20:21], 0, v[170:171]
	s_mov_b32 m0, s44
	s_nop 0
	global_load_lds_dwordx4 v[230:231], off
	s_mov_b32 m0, s45
	s_nop 0
	global_load_lds_dwordx4 v[232:233], off
	s_add_i32 m0, s39, 0xc000
	ds_read_b128 v[178:181], v193
	ds_read_b128 v[182:185], v193 offset:1024
	ds_read_b128 v[186:189], v193 offset:2048
	ds_read_b128 v[202:205], v193 offset:3072
	ds_read_b128 v[206:209], v193 offset:4096
	ds_read_b128 v[210:213], v193 offset:5120
	ds_read_b128 v[214:217], v193 offset:6144
	ds_read_b128 v[218:221], v193 offset:7168
	global_load_lds_dwordx4 v[190:191], off
	v_lshl_add_u64 v[190:191], s[20:21], 0, v[172:173]
	s_add_i32 m0, s39, 0xe000
	s_nop 0
	global_load_lds_dwordx4 v[190:191], off
	s_waitcnt vmcnt(8)
	s_waitcnt lgkmcnt(0)
	s_barrier
	s_setprio 1
	s_waitcnt lgkmcnt(0)
	v_mfma_f32_16x16x32_bf16 v[128:131], v[132:135], v[178:181], v[128:131]
	v_mfma_f32_16x16x32_bf16 v[124:127], v[140:143], v[178:181], v[124:127]
	v_mfma_f32_16x16x32_bf16 v[112:115], v[132:135], v[186:189], v[112:115]
	v_mfma_f32_16x16x32_bf16 v[108:111], v[140:143], v[186:189], v[108:111]
	v_mfma_f32_16x16x32_bf16 v[96:99], v[132:135], v[206:209], v[96:99]
	v_mfma_f32_16x16x32_bf16 v[92:95], v[140:143], v[206:209], v[92:95]
	v_mfma_f32_16x16x32_bf16 v[80:83], v[132:135], v[214:217], v[80:83]
	v_mfma_f32_16x16x32_bf16 v[76:79], v[140:143], v[214:217], v[76:79]
	v_mfma_f32_16x16x32_bf16 v[128:131], v[136:139], v[182:185], v[128:131]
	v_mfma_f32_16x16x32_bf16 v[124:127], v[144:147], v[182:185], v[124:127]
	v_mfma_f32_16x16x32_bf16 v[112:115], v[136:139], v[202:205], v[112:115]
	v_mfma_f32_16x16x32_bf16 v[108:111], v[144:147], v[202:205], v[108:111]
	v_mfma_f32_16x16x32_bf16 v[96:99], v[136:139], v[210:213], v[96:99]
	v_mfma_f32_16x16x32_bf16 v[92:95], v[144:147], v[210:213], v[92:95]
	v_mfma_f32_16x16x32_bf16 v[80:83], v[136:139], v[218:221], v[80:83]
	v_mfma_f32_16x16x32_bf16 v[76:79], v[144:147], v[218:221], v[76:79]
	s_setprio 0
	s_setprio 1
	v_mfma_f32_16x16x32_bf16 v[120:123], v[148:151], v[178:181], v[120:123]
	v_mfma_f32_16x16x32_bf16 v[116:119], v[156:159], v[178:181], v[116:119]
	v_mfma_f32_16x16x32_bf16 v[104:107], v[148:151], v[186:189], v[104:107]
	v_mfma_f32_16x16x32_bf16 v[100:103], v[156:159], v[186:189], v[100:103]
	v_mfma_f32_16x16x32_bf16 v[88:91], v[148:151], v[206:209], v[88:91]
	v_mfma_f32_16x16x32_bf16 v[84:87], v[156:159], v[206:209], v[84:87]
	v_mfma_f32_16x16x32_bf16 v[72:75], v[148:151], v[214:217], v[72:75]
	v_mfma_f32_16x16x32_bf16 v[68:71], v[156:159], v[214:217], v[68:71]
	v_mfma_f32_16x16x32_bf16 v[120:123], v[152:155], v[182:185], v[120:123]
	v_mfma_f32_16x16x32_bf16 v[116:119], v[174:177], v[182:185], v[116:119]
	v_mfma_f32_16x16x32_bf16 v[104:107], v[152:155], v[202:205], v[104:107]
	v_mfma_f32_16x16x32_bf16 v[100:103], v[174:177], v[202:205], v[100:103]
	v_mfma_f32_16x16x32_bf16 v[88:91], v[152:155], v[210:213], v[88:91]
	v_mfma_f32_16x16x32_bf16 v[84:87], v[174:177], v[210:213], v[84:87]
	v_mfma_f32_16x16x32_bf16 v[72:75], v[152:155], v[218:221], v[72:75]
	v_mfma_f32_16x16x32_bf16 v[68:71], v[174:177], v[218:221], v[68:71]
	s_setprio 0
	s_barrier
	s_add_i32 s20, s64, s38
	v_lshl_add_u64 v[190:191], s[24:25], 0, v[164:165]
	s_mov_b32 m0, s20
	ds_read_b128 v[178:181], v193 offset:16384
	ds_read_b128 v[182:185], v193 offset:17408
	ds_read_b128 v[186:189], v193 offset:18432
	ds_read_b128 v[202:205], v193 offset:19456
	ds_read_b128 v[206:209], v193 offset:20480
	ds_read_b128 v[210:213], v193 offset:21504
	ds_read_b128 v[214:217], v193 offset:22528
	ds_read_b128 v[218:221], v193 offset:23552
	global_load_lds_dwordx4 v[190:191], off
	s_add_i32 m0, s20, 0x2000
	s_add_u32 s20, s24, 0x104000
	v_lshl_add_u64 v[194:195], s[24:25], 0, v[168:169]
	s_addc_u32 s21, s25, 0
	s_add_i32 s64, s65, s38
	global_load_lds_dwordx4 v[194:195], off
	v_lshl_add_u64 v[222:223], s[20:21], 0, v[164:165]
	s_mov_b32 m0, s64
	v_lshl_add_u64 v[224:225], s[26:27], 0, v[166:167]
	global_load_lds_dwordx4 v[222:223], off
	v_lshl_add_u64 v[222:223], s[20:21], 0, v[168:169]
	s_add_i32 m0, s64, 0x2000
	s_nop 0
	global_load_lds_dwordx4 v[222:223], off
	v_lshl_add_u64 v[222:223], s[26:27], 0, v[162:163]
	s_waitcnt vmcnt(6)
	s_waitcnt lgkmcnt(0)
	s_barrier
; #define PG8_STAGE(bufoff, gbase, voff) do { _Pragma("unroll") for (int _i = 0; _i < 2; ++_i) \
;         __builtin_amdgcn_global_load_lds((const unsigned*)((const char*)(gbase) + (voff)[_i]), (LAS unsigned*)(lds + (bufoff) + ldsw + _i * 8192), 16, 0, 0); } while (0)
; #define PG8_LDA(dst, b, h) do { _Pragma("unroll") for (int m = 0; m < 4; ++m) _Pragma("unroll") for (int k = 0; k < 2; ++k) dst[m][k] = *(const LAS bf16x8*)(lds + PG8_SA(b, h) + aoff + m * 2048 + k * 1024); } while (0)
; #define PG8_LDB(dst, b, h) do { _Pragma("unroll") for (int n = 0; n < 2; ++n) _Pragma("unroll") for (int k = 0; k < 2; ++k) dst[n][k] = *(const LAS bf16x8*)(lds + PG8_SB(b, h) + boff + n * 2048 + k * 1024); } while (0)
; #define PG8_MMA(ai, bj, At, Bt) do { __builtin_amdgcn_s_setprio(1); _Pragma("unroll") for (int m = 0; m < 4; ++m) _Pragma("unroll") for (int n = 0; n < 2; ++n) _Pragma("unroll") for (int k = 0; k < 2; ++k) \
;         acc[ai][bj][m][n] = __builtin_amdgcn_mfma_f32_16x16x32_bf16(Bt[n][k], At[m][k], acc[ai][bj][m][n], 0, 0, 0); __builtin_amdgcn_s_setprio(0); } while (0)
; #define PG8_WAIT_V(n) asm volatile("s_waitcnt vmcnt(" #n ")" ::: "memory")
; #define PG8_WAIT_L(n) asm volatile("s_waitcnt lgkmcnt(" #n ")" ::: "memory")
; #define PG8_BAR __builtin_amdgcn_s_barrier()
; #define PG8_SCHED __builtin_amdgcn_sched_barrier(0)
; template <class Epi, bool ALIGN_EPI>
; DI void gemm_phase(LAS unsigned char* lds, const Sched& S, const Epi& E, int tid) {
;     ...
;             PG8_WAIT_V(8); PG8_WAIT_L(0); PG8_BAR; PG8_MMA(0, 0, At, B0); PG8_MMA(0, 1, At, B1); PG8_BAR; PG8_SCHED;
;             PG8_LDA(At, 0, 1); PG8_STAGE(PG8_SB(0, 0), b2, voffB); PG8_STAGE(PG8_SB(0, 1), b2 + hstepB, voffB); PG8_STAGE(PG8_SA(0, 0), a2, voffA);
;             PG8_WAIT_V(8); PG8_WAIT_L(0); PG8_BAR; PG8_MMA(1, 0, At, B0); PG8_MMA(1, 1, At, B1); PG8_BAR; PG8_SCHED;
;             PG8_LDB(B0, 1, 0); PG8_LDB(B1, 1, 1); PG8_SCHED; PG8_LDA(At, 1, 0); PG8_STAGE(PG8_SA(0, 1), a2 + hstepA, voffA);
;             PG8_WAIT_V(8); PG8_WAIT_L(0); PG8_BAR; PG8_MMA(0, 0, At, B0); PG8_MMA(0, 1, At, B1); PG8_BAR; PG8_SCHED;
;             PG8_LDA(At, 1, 1); PG8_STAGE(PG8_SB(1, 0), b3, voffB); PG8_STAGE(PG8_SB(1, 1), b3 + hstepB, voffB); PG8_STAGE(PG8_SA(1, 0), a3, voffA);
	s_setprio 1
	s_waitcnt lgkmcnt(0)
	v_mfma_f32_16x16x32_bf16 v[64:67], v[132:135], v[178:181], v[64:67]
	v_mfma_f32_16x16x32_bf16 v[60:63], v[140:143], v[178:181], v[60:63]
	v_mfma_f32_16x16x32_bf16 v[48:51], v[132:135], v[186:189], v[48:51]
	v_mfma_f32_16x16x32_bf16 v[44:47], v[140:143], v[186:189], v[44:47]
	v_mfma_f32_16x16x32_bf16 v[32:35], v[132:135], v[206:209], v[32:35]
	v_mfma_f32_16x16x32_bf16 v[28:31], v[140:143], v[206:209], v[28:31]
	v_mfma_f32_16x16x32_bf16 v[16:19], v[132:135], v[214:217], v[16:19]
	v_mfma_f32_16x16x32_bf16 v[12:15], v[140:143], v[214:217], v[12:15]
	v_mfma_f32_16x16x32_bf16 v[64:67], v[136:139], v[182:185], v[64:67]
	v_mfma_f32_16x16x32_bf16 v[60:63], v[144:147], v[182:185], v[60:63]
	v_mfma_f32_16x16x32_bf16 v[48:51], v[136:139], v[202:205], v[48:51]
	v_mfma_f32_16x16x32_bf16 v[44:47], v[144:147], v[202:205], v[44:47]
	v_mfma_f32_16x16x32_bf16 v[32:35], v[136:139], v[210:213], v[32:35]
	v_mfma_f32_16x16x32_bf16 v[28:31], v[144:147], v[210:213], v[28:31]
	v_mfma_f32_16x16x32_bf16 v[16:19], v[136:139], v[218:221], v[16:19]
	v_mfma_f32_16x16x32_bf16 v[12:15], v[144:147], v[218:221], v[12:15]
	s_setprio 0
	s_setprio 1
	v_mfma_f32_16x16x32_bf16 v[56:59], v[148:151], v[178:181], v[56:59]
	v_mfma_f32_16x16x32_bf16 v[52:55], v[156:159], v[178:181], v[52:55]
	v_mfma_f32_16x16x32_bf16 v[40:43], v[148:151], v[186:189], v[40:43]
	v_mfma_f32_16x16x32_bf16 v[36:39], v[156:159], v[186:189], v[36:39]
	v_mfma_f32_16x16x32_bf16 v[24:27], v[148:151], v[206:209], v[24:27]
	v_mfma_f32_16x16x32_bf16 v[20:23], v[156:159], v[206:209], v[20:23]
	v_mfma_f32_16x16x32_bf16 v[8:11], v[148:151], v[214:217], v[8:11]
	v_mfma_f32_16x16x32_bf16 v[4:7], v[156:159], v[214:217], v[4:7]
	v_mfma_f32_16x16x32_bf16 v[56:59], v[152:155], v[182:185], v[56:59]
	v_mfma_f32_16x16x32_bf16 v[52:55], v[174:177], v[182:185], v[52:55]
	v_mfma_f32_16x16x32_bf16 v[40:43], v[152:155], v[202:205], v[40:43]
	v_mfma_f32_16x16x32_bf16 v[36:39], v[174:177], v[202:205], v[36:39]
	v_mfma_f32_16x16x32_bf16 v[24:27], v[152:155], v[210:213], v[24:27]
	v_mfma_f32_16x16x32_bf16 v[20:23], v[174:177], v[210:213], v[20:23]
	v_mfma_f32_16x16x32_bf16 v[8:11], v[152:155], v[218:221], v[8:11]
	v_mfma_f32_16x16x32_bf16 v[4:7], v[174:177], v[218:221], v[4:7]
	s_setprio 0
	s_barrier
	s_add_i32 s64, 0, 0x18000
	s_add_i32 s65, 0, 0x1c000
	v_add_u32_e32 v144, s64, v161
	v_add_u32_e32 v174, s65, v161
	ds_read_b128 v[132:135], v144
	ds_read_b128 v[136:139], v144 offset:1024
	ds_read_b128 v[140:143], v144 offset:2048
	ds_read_b128 v[144:147], v144 offset:3072
	ds_read_b128 v[148:151], v174
	ds_read_b128 v[152:155], v174 offset:1024
	ds_read_b128 v[156:159], v174 offset:2048
	ds_read_b128 v[174:177], v174 offset:3072
	s_add_u32 s20, s26, 0x104000
	s_addc_u32 s21, s27, 0
	s_mov_b32 m0, s39
	s_nop 0
	global_load_lds_dwordx4 v[222:223], off
	s_mov_b32 m0, s40
	s_nop 0
	global_load_lds_dwordx4 v[224:225], off
	s_mov_b32 m0, s41
	v_lshl_add_u64 v[226:227], s[20:21], 0, v[162:163]
	ds_read_b128 v[178:181], v193 offset:32768
	ds_read_b128 v[182:185], v193 offset:33792
	ds_read_b128 v[186:189], v193 offset:34816
	ds_read_b128 v[202:205], v193 offset:35840
	ds_read_b128 v[206:209], v193 offset:36864
	ds_read_b128 v[210:213], v193 offset:37888
	ds_read_b128 v[214:217], v193 offset:38912
	ds_read_b128 v[218:221], v193 offset:39936
	global_load_lds_dwordx4 v[226:227], off
	v_lshl_add_u64 v[226:227], s[20:21], 0, v[166:167]
	s_mov_b32 m0, s42
	s_nop 0
	global_load_lds_dwordx4 v[226:227], off
	s_waitcnt vmcnt(8)
	s_waitcnt lgkmcnt(0)
	s_barrier
	s_setprio 1
	s_waitcnt lgkmcnt(0)
	v_mfma_f32_16x16x32_bf16 v[128:131], v[132:135], v[178:181], v[128:131]
	v_mfma_f32_16x16x32_bf16 v[124:127], v[140:143], v[178:181], v[124:127]
	v_mfma_f32_16x16x32_bf16 v[112:115], v[132:135], v[186:189], v[112:115]
	v_mfma_f32_16x16x32_bf16 v[108:111], v[140:143], v[186:189], v[108:111]
	v_mfma_f32_16x16x32_bf16 v[96:99], v[132:135], v[206:209], v[96:99]
	v_mfma_f32_16x16x32_bf16 v[92:95], v[140:143], v[206:209], v[92:95]
	v_mfma_f32_16x16x32_bf16 v[80:83], v[132:135], v[214:217], v[80:83]
	v_mfma_f32_16x16x32_bf16 v[76:79], v[140:143], v[214:217], v[76:79]
	v_mfma_f32_16x16x32_bf16 v[128:131], v[136:139], v[182:185], v[128:131]
	v_mfma_f32_16x16x32_bf16 v[124:127], v[144:147], v[182:185], v[124:127]
	v_mfma_f32_16x16x32_bf16 v[112:115], v[136:139], v[202:205], v[112:115]
	v_mfma_f32_16x16x32_bf16 v[108:111], v[144:147], v[202:205], v[108:111]
	v_mfma_f32_16x16x32_bf16 v[96:99], v[136:139], v[210:213], v[96:99]
	v_mfma_f32_16x16x32_bf16 v[92:95], v[144:147], v[210:213], v[92:95]
	v_mfma_f32_16x16x32_bf16 v[80:83], v[136:139], v[218:221], v[80:83]
	v_mfma_f32_16x16x32_bf16 v[76:79], v[144:147], v[218:221], v[76:79]
	s_setprio 0
	s_setprio 1
	v_mfma_f32_16x16x32_bf16 v[120:123], v[148:151], v[178:181], v[120:123]
	v_mfma_f32_16x16x32_bf16 v[116:119], v[156:159], v[178:181], v[116:119]
	v_mfma_f32_16x16x32_bf16 v[104:107], v[148:151], v[186:189], v[104:107]
	v_mfma_f32_16x16x32_bf16 v[100:103], v[156:159], v[186:189], v[100:103]
	v_mfma_f32_16x16x32_bf16 v[88:91], v[148:151], v[206:209], v[88:91]
	v_mfma_f32_16x16x32_bf16 v[84:87], v[156:159], v[206:209], v[84:87]
	v_mfma_f32_16x16x32_bf16 v[72:75], v[148:151], v[214:217], v[72:75]
	v_mfma_f32_16x16x32_bf16 v[68:71], v[156:159], v[214:217], v[68:71]
	v_mfma_f32_16x16x32_bf16 v[120:123], v[152:155], v[182:185], v[120:123]
	v_mfma_f32_16x16x32_bf16 v[116:119], v[174:177], v[182:185], v[116:119]
	v_mfma_f32_16x16x32_bf16 v[104:107], v[152:155], v[202:205], v[104:107]
	v_mfma_f32_16x16x32_bf16 v[100:103], v[174:177], v[202:205], v[100:103]
	v_mfma_f32_16x16x32_bf16 v[88:91], v[152:155], v[210:213], v[88:91]
	v_mfma_f32_16x16x32_bf16 v[84:87], v[174:177], v[210:213], v[84:87]
	v_mfma_f32_16x16x32_bf16 v[72:75], v[152:155], v[218:221], v[72:75]
	v_mfma_f32_16x16x32_bf16 v[68:71], v[174:177], v[218:221], v[68:71]
	s_setprio 0
	s_barrier
; #define PG8_STAGE(bufoff, gbase, voff) do { _Pragma("unroll") for (int _i = 0; _i < 2; ++_i) \
;         __builtin_amdgcn_global_load_lds((const unsigned*)((const char*)(gbase) + (voff)[_i]), (LAS unsigned*)(lds + (bufoff) + ldsw + _i * 8192), 16, 0, 0); } while (0)
; #define PG8_LDA(dst, b, h) do { _Pragma("unroll") for (int m = 0; m < 4; ++m) _Pragma("unroll") for (int k = 0; k < 2; ++k) dst[m][k] = *(const LAS bf16x8*)(lds + PG8_SA(b, h) + aoff + m * 2048 + k * 1024); } while (0)
; #define PG8_MMA(ai, bj, At, Bt) do { __builtin_amdgcn_s_setprio(1); _Pragma("unroll") for (int m = 0; m < 4; ++m) _Pragma("unroll") for (int n = 0; n < 2; ++n) _Pragma("unroll") for (int k = 0; k < 2; ++k) \
;         acc[ai][bj][m][n] = __builtin_amdgcn_mfma_f32_16x16x32_bf16(Bt[n][k], At[m][k], acc[ai][bj][m][n], 0, 0, 0); __builtin_amdgcn_s_setprio(0); } while (0)
; #define PG8_WAIT_V(n) asm volatile("s_waitcnt vmcnt(" #n ")" ::: "memory")
; #define PG8_WAIT_L(n) asm volatile("s_waitcnt lgkmcnt(" #n ")" ::: "memory")
; #define PG8_BAR __builtin_amdgcn_s_barrier()
; #define PG8_SCHED __builtin_amdgcn_sched_barrier(0)
; template <class Epi, bool ALIGN_EPI>
; DI void gemm_phase(LAS unsigned char* lds, const Sched& S, const Epi& E, int tid) {
;     ...
;     for (;;) {
;         const bool has_next = S.next(ui + 1, nxt);
;         const char* nA = has_next ? nxt.a : cA; const char* nB = has_next ? nxt.b : cB;
;         const int nt = cur.nt;
;         for (int t = 0; t < nt; t += 2) {
;     ...
;             PG8_LDA(At, 1, 1); PG8_STAGE(PG8_SB(1, 0), b3, voffB); PG8_STAGE(PG8_SB(1, 1), b3 + hstepB, voffB); PG8_STAGE(PG8_SA(1, 0), a3, voffA);
;             PG8_WAIT_V(8); PG8_WAIT_L(0); PG8_BAR; PG8_MMA(1, 0, At, B0); PG8_MMA(1, 1, At, B1); PG8_BAR; PG8_SCHED;
;         }
	s_add_i32 s20, s64, s38
	v_lshl_add_u64 v[190:191], v[190:191], 0, s[84:85]
	s_mov_b32 m0, s20
	ds_read_b128 v[178:181], v193 offset:49152
	ds_read_b128 v[182:185], v193 offset:50176
	ds_read_b128 v[186:189], v193 offset:51200
	ds_read_b128 v[202:205], v193 offset:52224
	ds_read_b128 v[206:209], v193 offset:53248
	ds_read_b128 v[210:213], v193 offset:54272
	ds_read_b128 v[214:217], v193 offset:55296
	ds_read_b128 v[218:221], v193 offset:56320
	global_load_lds_dwordx4 v[190:191], off
	s_add_i32 m0, s20, 0x2000
	s_add_u32 s20, s24, 0x104080
	v_lshl_add_u64 v[190:191], v[194:195], 0, s[84:85]
	s_addc_u32 s21, s25, 0
	s_add_i32 s24, s65, s38
	global_load_lds_dwordx4 v[190:191], off
	v_lshl_add_u64 v[190:191], s[20:21], 0, v[164:165]
	s_mov_b32 m0, s24
	s_nop 0
	global_load_lds_dwordx4 v[190:191], off
	v_lshl_add_u64 v[190:191], s[20:21], 0, v[168:169]
	s_add_i32 m0, s24, 0x2000
	s_nop 0
	global_load_lds_dwordx4 v[190:191], off
	v_lshl_add_u64 v[230:231], v[222:223], 0, s[84:85]
	v_lshl_add_u64 v[232:233], v[224:225], 0, s[84:85]
	s_waitcnt vmcnt(6)
	s_waitcnt lgkmcnt(0)
	s_barrier
	s_setprio 1
	s_waitcnt lgkmcnt(0)
	v_mfma_f32_16x16x32_bf16 v[64:67], v[132:135], v[178:181], v[64:67]
	v_mfma_f32_16x16x32_bf16 v[60:63], v[140:143], v[178:181], v[60:63]
	v_mfma_f32_16x16x32_bf16 v[48:51], v[132:135], v[186:189], v[48:51]
	v_mfma_f32_16x16x32_bf16 v[44:47], v[140:143], v[186:189], v[44:47]
	v_mfma_f32_16x16x32_bf16 v[32:35], v[132:135], v[206:209], v[32:35]
	v_mfma_f32_16x16x32_bf16 v[28:31], v[140:143], v[206:209], v[28:31]
	v_mfma_f32_16x16x32_bf16 v[16:19], v[132:135], v[214:217], v[16:19]
	v_mfma_f32_16x16x32_bf16 v[12:15], v[140:143], v[214:217], v[12:15]
	v_mfma_f32_16x16x32_bf16 v[64:67], v[136:139], v[182:185], v[64:67]
	v_mfma_f32_16x16x32_bf16 v[60:63], v[144:147], v[182:185], v[60:63]
	v_mfma_f32_16x16x32_bf16 v[48:51], v[136:139], v[202:205], v[48:51]
	v_mfma_f32_16x16x32_bf16 v[44:47], v[144:147], v[202:205], v[44:47]
	v_mfma_f32_16x16x32_bf16 v[32:35], v[136:139], v[210:213], v[32:35]
	v_mfma_f32_16x16x32_bf16 v[28:31], v[144:147], v[210:213], v[28:31]
	v_mfma_f32_16x16x32_bf16 v[16:19], v[136:139], v[218:221], v[16:19]
	v_mfma_f32_16x16x32_bf16 v[12:15], v[144:147], v[218:221], v[12:15]
	s_setprio 0
	s_setprio 1
	v_mfma_f32_16x16x32_bf16 v[56:59], v[148:151], v[178:181], v[56:59]
	v_mfma_f32_16x16x32_bf16 v[52:55], v[156:159], v[178:181], v[52:55]
	v_mfma_f32_16x16x32_bf16 v[40:43], v[148:151], v[186:189], v[40:43]
	v_mfma_f32_16x16x32_bf16 v[36:39], v[156:159], v[186:189], v[36:39]
	v_mfma_f32_16x16x32_bf16 v[24:27], v[148:151], v[206:209], v[24:27]
	v_mfma_f32_16x16x32_bf16 v[20:23], v[156:159], v[206:209], v[20:23]
	v_mfma_f32_16x16x32_bf16 v[8:11], v[148:151], v[214:217], v[8:11]
	v_mfma_f32_16x16x32_bf16 v[4:7], v[156:159], v[214:217], v[4:7]
	v_mfma_f32_16x16x32_bf16 v[56:59], v[152:155], v[182:185], v[56:59]
	v_mfma_f32_16x16x32_bf16 v[52:55], v[174:177], v[182:185], v[52:55]
	v_mfma_f32_16x16x32_bf16 v[40:43], v[152:155], v[202:205], v[40:43]
	v_mfma_f32_16x16x32_bf16 v[36:39], v[174:177], v[202:205], v[36:39]
	v_mfma_f32_16x16x32_bf16 v[24:27], v[152:155], v[210:213], v[24:27]
	v_mfma_f32_16x16x32_bf16 v[20:23], v[174:177], v[210:213], v[20:23]
	v_mfma_f32_16x16x32_bf16 v[8:11], v[152:155], v[218:221], v[8:11]
	v_mfma_f32_16x16x32_bf16 v[4:7], v[174:177], v[218:221], v[4:7]
	s_setprio 0
	s_barrier
	s_add_u32 s61, s61, 0x100
	s_addc_u32 s62, s62, 0
	s_cmp_ge_i32 s63, s55
	s_mov_b64 s[20:21], s[22:23]
	s_mov_b32 s24, s63
	s_cbranch_scc0 .LBB0_412
	s_and_b64 vcc, exec, s[6:7]
	s_cbranch_vccz .LBB0_415
	s_barrier

; #define PG8_STAGE(bufoff, gbase, voff) do { _Pragma("unroll") for (int _i = 0; _i < 2; ++_i) \
;         __builtin_amdgcn_global_load_lds((const unsigned*)((const char*)(gbase) + (voff)[_i]), (LAS unsigned*)(lds + (bufoff) + ldsw + _i * 8192), 16, 0, 0); } while (0)
; #define PG8_WAIT_V(n) asm volatile("s_waitcnt vmcnt(" #n ")" ::: "memory")
; #define PG8_BAR __builtin_amdgcn_s_barrier()
; template <class Epi, bool ALIGN_EPI>
; DI void gemm_phase(LAS unsigned char* lds, const Sched& S, const Epi& E, int tid) {
;     const int wid = __builtin_amdgcn_readfirstlane(tid >> 6), lane = tid & 63, wr = wid >> 2, wc = wid & 3, fr = lane & 15, fq = lane >> 4;
;     const int lda = S.lda, ldb = S.ldb;
;     unsigned voffA[2], voffB[2];
; #pragma unroll
;     for (int i = 0; i < 2; ++i) { int R, C; stage_rc(tid * 16 + i * 8192, R, C); const int Rb = (R & ~31) + perm32(R & 31);
;         voffA[i] = (unsigned)(R * lda + C) * 2u; voffB[i] = (unsigned)(Rb * ldb + C) * 2u; }
;     const size_t kstep = (size_t)(BK * 2);
;     const size_t hstepA = (size_t)HALF * lda * 2, hstepB = (size_t)HALF * ldb * 2;
;     const unsigned ldsw = (unsigned)wid * 1024u;
;     const int aoff = lds_byte(wr * 64 + fr, fq * 8), boff = lds_byte(wc * 32 + fr, fq * 8);
;     ...
;     Unit cur, nxt; int ui = 0;
;     if (!S.next(0, cur)) return;
;     f32x4 acc[2][2][4][2];
; #pragma unroll
;     for (int a = 0; a < 2; ++a)
; #pragma unroll
;         for (int b = 0; b < 2; ++b)
; #pragma unroll
;             for (int m = 0; m < 4; ++m)
; #pragma unroll
;                 for (int n = 0; n < 2; ++n) acc[a][b][m][n] = (f32x4){0.f, 0.f, 0.f, 0.f};
;     bf16x8 At[4][2], B0[2][2], B1[2][2];
;     const char* cA = cur.a; const char* cB = cur.b;
;     PG8_STAGE(PG8_SB(0, 0), cB, voffB); PG8_STAGE(PG8_SB(0, 1), cB + hstepB, voffB); PG8_STAGE(PG8_SA(0, 0), cA, voffA); PG8_STAGE(PG8_SA(0, 1), cA + hstepA, voffA);
;     if (wr == 1) PG8_BAR;
;     PG8_WAIT_V(2); PG8_BAR;
;     PG8_STAGE(PG8_SB(1, 0), cB + kstep, voffB); PG8_STAGE(PG8_SA(1, 0), cA + kstep, voffA); PG8_STAGE(PG8_SB(1, 1), cB + hstepB + kstep, voffB);
;     PG8_WAIT_V(6); PG8_BAR;
.LBB0_643:
	v_lshrrev_b32_e32 v19, 1, v0
	v_and_b32_e32 v19, 24, v19
	v_and_b32_e32 v18, 15, v0
	v_lshlrev_b32_e32 v20, 1, v19
	s_lshl_b32 s2, s2, 5
	v_lshl_or_b32 v3, s1, 6, v18
	v_lshl_or_b32 v20, v18, 6, v20
	v_lshlrev_b32_e32 v18, 2, v18
	s_and_b32 s20, s2, 0x60
	s_lshl_b32 s3, s1, 13
	v_and_b32_e32 v21, 32, v18
	s_lshl_b32 s2, s20, 7
	v_bitop3_b32 v22, v20, s3, v21 bitop3:0xde
	v_bitop3_b32 v141, s2, v20, v21 bitop3:0xf6
	s_lshl_b64 s[2:3], s[90:91], 24
	v_readlane_b32 s8, v253, 54
	s_add_u32 s8, s8, s2
	v_readlane_b32 s9, v253, 55
	s_addc_u32 s9, s9, s3
	v_readlane_b32 s10, v253, 56
	s_add_u32 s10, s10, s2
	v_readlane_b32 s2, v253, 57
	s_addc_u32 s11, s2, s3
	s_lshl_b64 s[2:3], s[90:91], 21
	v_readlane_b32 s12, v253, 58
	s_add_u32 s12, s12, s2
	v_readlane_b32 s13, v253, 59
	s_addc_u32 s13, s13, s3
	v_readlane_b32 s14, v253, 60
	s_add_u32 s14, s14, s2
	v_readlane_b32 s2, v253, 61
	s_addc_u32 s15, s2, s3
	s_add_u32 s16, s96, 0x16b00000
	s_addc_u32 s17, s97, 0
	s_add_i32 m0, s50, 0x18000
	v_lshl_add_u64 v[10:11], v[10:11], 0, s[84:85]
	s_waitcnt vmcnt(2)
	s_barrier
	global_load_lds_dwordx4 v[10:11], off
	v_lshl_add_u64 v[8:9], v[8:9], 0, s[84:85]
	s_add_i32 m0, s50, 0x1a000
	s_add_i32 s54, s50, 0x8000
	s_add_i32 s55, s50, 0xa000
	global_load_lds_dwordx4 v[8:9], off
	v_lshl_add_u64 v[4:5], v[4:5], 0, s[84:85]
	s_mov_b32 m0, s54
	s_add_u32 s2, s24, 0x40080
	v_mov_b64_e32 v[230:231], v[4:5]
	global_load_lds_dwordx4 v[4:5], off
	v_lshl_add_u64 v[4:5], v[6:7], 0, s[84:85]
	s_mov_b32 m0, s55
	s_addc_u32 s3, s25, 0
	v_mov_b64_e32 v[232:233], v[4:5]
	global_load_lds_dwordx4 v[4:5], off
	s_add_i32 m0, s50, 0x1c000
	v_lshl_add_u64 v[4:5], s[2:3], 0, v[134:135]
	global_load_lds_dwordx4 v[4:5], off
	v_lshl_add_u64 v[4:5], s[2:3], 0, v[138:139]
	s_add_i32 m0, s50, 0x1e000
	s_cmpk_lt_u32 s18, 0x100
	global_load_lds_dwordx4 v[4:5], off
	v_lshlrev_b32_e32 v4, 14, v12
	v_and_b32_e32 v4, 0xffff8000, v4
	v_lshl_add_u32 v4, v13, 11, v4
	v_and_b32_e32 v5, 1, v12
	v_lshl_or_b32 v4, v5, 6, v4
	v_lshl_add_u32 v142, v14, 1, v4
	v_lshlrev_b32_e32 v4, 14, v15
	s_cselect_b64 s[18:19], -1, 0
	s_lshl_b32 s1, s1, 8
	v_and_b32_e32 v4, 0xffff8000, v4
	s_waitcnt vmcnt(6)
	s_add_i32 s1, s1, 0
	v_lshl_add_u32 v4, v16, 11, v4
	v_and_b32_e32 v5, 1, v15
	s_add_i32 s1, s1, 0x20000
	v_lshl_or_b32 v4, v5, 6, v4
	v_or_b32_e32 v140, s20, v19
	v_add_u32_e32 v156, s1, v18
	v_mov_b32_e32 v143, v2
	v_lshl_add_u32 v144, v17, 1, v4
	v_mov_b32_e32 v145, v2
	s_mov_b32 s1, 0
	v_add_u32_e32 v157, 0, v22
	s_mov_b32 s56, 0
	s_barrier
	s_branch .LBB0_646

; #define PG8_STAGE(bufoff, gbase, voff) do { _Pragma("unroll") for (int _i = 0; _i < 2; ++_i) \
;         __builtin_amdgcn_global_load_lds((const unsigned*)((const char*)(gbase) + (voff)[_i]), (LAS unsigned*)(lds + (bufoff) + ldsw + _i * 8192), 16, 0, 0); } while (0)
; #define PG8_LDA(dst, b, h) do { _Pragma("unroll") for (int m = 0; m < 4; ++m) _Pragma("unroll") for (int k = 0; k < 2; ++k) dst[m][k] = *(const LAS bf16x8*)(lds + PG8_SA(b, h) + aoff + m * 2048 + k * 1024); } while (0)
; #define PG8_LDB(dst, b, h) do { _Pragma("unroll") for (int n = 0; n < 2; ++n) _Pragma("unroll") for (int k = 0; k < 2; ++k) dst[n][k] = *(const LAS bf16x8*)(lds + PG8_SB(b, h) + boff + n * 2048 + k * 1024); } while (0)
; #define PG8_MMA(ai, bj, At, Bt) do { __builtin_amdgcn_s_setprio(1); _Pragma("unroll") for (int m = 0; m < 4; ++m) _Pragma("unroll") for (int n = 0; n < 2; ++n) _Pragma("unroll") for (int k = 0; k < 2; ++k) \
;         acc[ai][bj][m][n] = __builtin_amdgcn_mfma_f32_16x16x32_bf16(Bt[n][k], At[m][k], acc[ai][bj][m][n], 0, 0, 0); __builtin_amdgcn_s_setprio(0); } while (0)
; #define PG8_WAIT_V(n) asm volatile("s_waitcnt vmcnt(" #n ")" ::: "memory")
; #define PG8_WAIT_L(n) asm volatile("s_waitcnt lgkmcnt(" #n ")" ::: "memory")
; #define PG8_BAR __builtin_amdgcn_s_barrier()
; #define PG8_SCHED __builtin_amdgcn_sched_barrier(0)
; template <class Epi, bool ALIGN_EPI>
; DI void gemm_phase(LAS unsigned char* lds, const Sched& S, const Epi& E, int tid) {
;     ...
;         for (int t = 0; t < nt; t += 2) {
;             const bool last = (t == nt - 2);
;             const char* a1 = cA + (size_t)(t + 1) * kstep;
;             const char* a2 = last ? nA : cA + (size_t)(t + 2) * kstep; const char* b2 = last ? nB : cB + (size_t)(t + 2) * kstep;
;             const char* a3 = a2 + kstep; const char* b3 = b2 + kstep;
;             PG8_LDB(B0, 0, 0); PG8_LDB(B1, 0, 1); PG8_SCHED; PG8_LDA(At, 0, 0); PG8_STAGE(PG8_SA(1, 1), a1 + hstepA, voffA);
;             PG8_WAIT_V(8); PG8_WAIT_L(0); PG8_BAR; PG8_MMA(0, 0, At, B0); PG8_MMA(0, 1, At, B1); PG8_BAR; PG8_SCHED;
;             PG8_LDA(At, 0, 1); PG8_STAGE(PG8_SB(0, 0), b2, voffB); PG8_STAGE(PG8_SB(0, 1), b2 + hstepB, voffB); PG8_STAGE(PG8_SA(0, 0), a2, voffA);
;             PG8_WAIT_V(8); PG8_WAIT_L(0); PG8_BAR; PG8_MMA(1, 0, At, B0); PG8_MMA(1, 1, At, B1); PG8_BAR; PG8_SCHED;
.LBB0_653:
	s_add_u32 s24, s22, 0xfffc0080
	s_addc_u32 s25, s23, -1
	s_add_i32 s40, 0, 0x10000
	s_cmp_eq_u32 s39, 12
	s_cselect_b32 s29, s3, s25
	s_cselect_b32 s28, s2, s24
	v_add_u32_e32 v154, s40, v141
	s_cselect_b32 s25, s21, s38
	s_cselect_b32 s24, s20, s37
	s_add_i32 s58, 0, 0x14000
	ds_read_b128 v[146:149], v154
	ds_read_b128 v[150:153], v154 offset:1024
	ds_read_b128 v[162:165], v154 offset:2048
	ds_read_b128 v[166:169], v154 offset:3072
	v_add_u32_e32 v154, s58, v141
	ds_read_b128 v[170:173], v154
	ds_read_b128 v[174:177], v154 offset:1024
	ds_read_b128 v[178:181], v154 offset:2048
	ds_read_b128 v[182:185], v154 offset:3072
	v_lshl_add_u64 v[154:155], s[22:23], 0, v[142:143]
	s_mov_b32 m0, s54
	s_nop 0
	global_load_lds_dwordx4 v[230:231], off
	s_mov_b32 m0, s55
	s_nop 0
	global_load_lds_dwordx4 v[232:233], off
	s_add_i32 m0, s50, 0xc000
	ds_read_b128 v[186:189], v157
	ds_read_b128 v[190:193], v157 offset:1024
	ds_read_b128 v[202:205], v157 offset:2048
	ds_read_b128 v[206:209], v157 offset:3072
	ds_read_b128 v[210:213], v157 offset:4096
	ds_read_b128 v[214:217], v157 offset:5120
	ds_read_b128 v[218:221], v157 offset:6144
	ds_read_b128 v[222:225], v157 offset:7168
	global_load_lds_dwordx4 v[154:155], off
	v_lshl_add_u64 v[154:155], s[22:23], 0, v[144:145]
	s_add_i32 m0, s50, 0xe000
	s_nop 0
	global_load_lds_dwordx4 v[154:155], off
	s_waitcnt vmcnt(8)
	s_waitcnt lgkmcnt(0)
	s_barrier
	s_setprio 1
	s_waitcnt lgkmcnt(0)
	v_mfma_f32_16x16x32_bf16 v[128:131], v[146:149], v[186:189], v[128:131]
	v_mfma_f32_16x16x32_bf16 v[124:127], v[162:165], v[186:189], v[124:127]
	v_mfma_f32_16x16x32_bf16 v[112:115], v[146:149], v[202:205], v[112:115]
	v_mfma_f32_16x16x32_bf16 v[108:111], v[162:165], v[202:205], v[108:111]
	v_mfma_f32_16x16x32_bf16 v[96:99], v[146:149], v[210:213], v[96:99]
	v_mfma_f32_16x16x32_bf16 v[92:95], v[162:165], v[210:213], v[92:95]
	v_mfma_f32_16x16x32_bf16 v[80:83], v[146:149], v[218:221], v[80:83]
	v_mfma_f32_16x16x32_bf16 v[76:79], v[162:165], v[218:221], v[76:79]
	v_mfma_f32_16x16x32_bf16 v[128:131], v[150:153], v[190:193], v[128:131]
	v_mfma_f32_16x16x32_bf16 v[124:127], v[166:169], v[190:193], v[124:127]
	v_mfma_f32_16x16x32_bf16 v[112:115], v[150:153], v[206:209], v[112:115]
	v_mfma_f32_16x16x32_bf16 v[108:111], v[166:169], v[206:209], v[108:111]
	v_mfma_f32_16x16x32_bf16 v[96:99], v[150:153], v[214:217], v[96:99]
	v_mfma_f32_16x16x32_bf16 v[92:95], v[166:169], v[214:217], v[92:95]
	v_mfma_f32_16x16x32_bf16 v[80:83], v[150:153], v[222:225], v[80:83]
	v_mfma_f32_16x16x32_bf16 v[76:79], v[166:169], v[222:225], v[76:79]
	s_setprio 0
	s_setprio 1
	v_mfma_f32_16x16x32_bf16 v[120:123], v[170:173], v[186:189], v[120:123]
	v_mfma_f32_16x16x32_bf16 v[116:119], v[178:181], v[186:189], v[116:119]
	v_mfma_f32_16x16x32_bf16 v[104:107], v[170:173], v[202:205], v[104:107]
	v_mfma_f32_16x16x32_bf16 v[100:103], v[178:181], v[202:205], v[100:103]
	v_mfma_f32_16x16x32_bf16 v[88:91], v[170:173], v[210:213], v[88:91]
	v_mfma_f32_16x16x32_bf16 v[84:87], v[178:181], v[210:213], v[84:87]
	v_mfma_f32_16x16x32_bf16 v[72:75], v[170:173], v[218:221], v[72:75]
	v_mfma_f32_16x16x32_bf16 v[68:71], v[178:181], v[218:221], v[68:71]
	v_mfma_f32_16x16x32_bf16 v[120:123], v[174:177], v[190:193], v[120:123]
	v_mfma_f32_16x16x32_bf16 v[116:119], v[182:185], v[190:193], v[116:119]
	v_mfma_f32_16x16x32_bf16 v[104:107], v[174:177], v[206:209], v[104:107]
	v_mfma_f32_16x16x32_bf16 v[100:103], v[182:185], v[206:209], v[100:103]
	v_mfma_f32_16x16x32_bf16 v[88:91], v[174:177], v[214:217], v[88:91]
	v_mfma_f32_16x16x32_bf16 v[84:87], v[182:185], v[214:217], v[84:87]
	v_mfma_f32_16x16x32_bf16 v[72:75], v[174:177], v[222:225], v[72:75]
	v_mfma_f32_16x16x32_bf16 v[68:71], v[182:185], v[222:225], v[68:71]
	s_setprio 0
	s_barrier
	s_add_i32 s40, s40, s49
	v_lshl_add_u64 v[154:155], s[24:25], 0, v[134:135]
	s_mov_b32 m0, s40
	ds_read_b128 v[186:189], v157 offset:16384
	ds_read_b128 v[190:193], v157 offset:17408
	ds_read_b128 v[202:205], v157 offset:18432
	ds_read_b128 v[206:209], v157 offset:19456
	ds_read_b128 v[210:213], v157 offset:20480
	ds_read_b128 v[214:217], v157 offset:21504
	ds_read_b128 v[218:221], v157 offset:22528
	ds_read_b128 v[222:225], v157 offset:23552
	global_load_lds_dwordx4 v[154:155], off
	s_add_i32 m0, s40, 0x2000
	s_add_u32 s40, s24, 0x40000
	v_lshl_add_u64 v[158:159], s[24:25], 0, v[138:139]
	s_addc_u32 s41, s25, 0
	s_add_i32 s58, s58, s49
	global_load_lds_dwordx4 v[158:159], off
	v_lshl_add_u64 v[194:195], s[40:41], 0, v[134:135]
	s_mov_b32 m0, s58
	v_lshl_add_u64 v[226:227], s[28:29], 0, v[136:137]
	global_load_lds_dwordx4 v[194:195], off
	v_lshl_add_u64 v[194:195], s[40:41], 0, v[138:139]
	s_add_i32 m0, s58, 0x2000
	s_nop 0
	global_load_lds_dwordx4 v[194:195], off
	v_lshl_add_u64 v[194:195], s[28:29], 0, v[132:133]
	s_waitcnt vmcnt(6)
	s_waitcnt lgkmcnt(0)
	s_barrier
; #define PG8_STAGE(bufoff, gbase, voff) do { _Pragma("unroll") for (int _i = 0; _i < 2; ++_i) \
;         __builtin_amdgcn_global_load_lds((const unsigned*)((const char*)(gbase) + (voff)[_i]), (LAS unsigned*)(lds + (bufoff) + ldsw + _i * 8192), 16, 0, 0); } while (0)
; #define PG8_LDA(dst, b, h) do { _Pragma("unroll") for (int m = 0; m < 4; ++m) _Pragma("unroll") for (int k = 0; k < 2; ++k) dst[m][k] = *(const LAS bf16x8*)(lds + PG8_SA(b, h) + aoff + m * 2048 + k * 1024); } while (0)
; #define PG8_LDB(dst, b, h) do { _Pragma("unroll") for (int n = 0; n < 2; ++n) _Pragma("unroll") for (int k = 0; k < 2; ++k) dst[n][k] = *(const LAS bf16x8*)(lds + PG8_SB(b, h) + boff + n * 2048 + k * 1024); } while (0)
; #define PG8_MMA(ai, bj, At, Bt) do { __builtin_amdgcn_s_setprio(1); _Pragma("unroll") for (int m = 0; m < 4; ++m) _Pragma("unroll") for (int n = 0; n < 2; ++n) _Pragma("unroll") for (int k = 0; k < 2; ++k) \
;         acc[ai][bj][m][n] = __builtin_amdgcn_mfma_f32_16x16x32_bf16(Bt[n][k], At[m][k], acc[ai][bj][m][n], 0, 0, 0); __builtin_amdgcn_s_setprio(0); } while (0)
; #define PG8_WAIT_V(n) asm volatile("s_waitcnt vmcnt(" #n ")" ::: "memory")
; #define PG8_WAIT_L(n) asm volatile("s_waitcnt lgkmcnt(" #n ")" ::: "memory")
; #define PG8_BAR __builtin_amdgcn_s_barrier()
; #define PG8_SCHED __builtin_amdgcn_sched_barrier(0)
; template <class Epi, bool ALIGN_EPI>
; DI void gemm_phase(LAS unsigned char* lds, const Sched& S, const Epi& E, int tid) {
;     ...
;             PG8_WAIT_V(8); PG8_WAIT_L(0); PG8_BAR; PG8_MMA(0, 0, At, B0); PG8_MMA(0, 1, At, B1); PG8_BAR; PG8_SCHED;
;             PG8_LDA(At, 0, 1); PG8_STAGE(PG8_SB(0, 0), b2, voffB); PG8_STAGE(PG8_SB(0, 1), b2 + hstepB, voffB); PG8_STAGE(PG8_SA(0, 0), a2, voffA);
;             PG8_WAIT_V(8); PG8_WAIT_L(0); PG8_BAR; PG8_MMA(1, 0, At, B0); PG8_MMA(1, 1, At, B1); PG8_BAR; PG8_SCHED;
;             PG8_LDB(B0, 1, 0); PG8_LDB(B1, 1, 1); PG8_SCHED; PG8_LDA(At, 1, 0); PG8_STAGE(PG8_SA(0, 1), a2 + hstepA, voffA);
;             PG8_WAIT_V(8); PG8_WAIT_L(0); PG8_BAR; PG8_MMA(0, 0, At, B0); PG8_MMA(0, 1, At, B1); PG8_BAR; PG8_SCHED;
;             PG8_LDA(At, 1, 1); PG8_STAGE(PG8_SB(1, 0), b3, voffB); PG8_STAGE(PG8_SB(1, 1), b3 + hstepB, voffB); PG8_STAGE(PG8_SA(1, 0), a3, voffA);
	s_setprio 1
	s_waitcnt lgkmcnt(0)
	v_mfma_f32_16x16x32_bf16 v[64:67], v[146:149], v[186:189], v[64:67]
	v_mfma_f32_16x16x32_bf16 v[60:63], v[162:165], v[186:189], v[60:63]
	v_mfma_f32_16x16x32_bf16 v[48:51], v[146:149], v[202:205], v[48:51]
	v_mfma_f32_16x16x32_bf16 v[44:47], v[162:165], v[202:205], v[44:47]
	v_mfma_f32_16x16x32_bf16 v[32:35], v[146:149], v[210:213], v[32:35]
	v_mfma_f32_16x16x32_bf16 v[28:31], v[162:165], v[210:213], v[28:31]
	v_mfma_f32_16x16x32_bf16 v[16:19], v[146:149], v[218:221], v[16:19]
	v_mfma_f32_16x16x32_bf16 v[12:15], v[162:165], v[218:221], v[12:15]
	v_mfma_f32_16x16x32_bf16 v[64:67], v[150:153], v[190:193], v[64:67]
	v_mfma_f32_16x16x32_bf16 v[60:63], v[166:169], v[190:193], v[60:63]
	v_mfma_f32_16x16x32_bf16 v[48:51], v[150:153], v[206:209], v[48:51]
	v_mfma_f32_16x16x32_bf16 v[44:47], v[166:169], v[206:209], v[44:47]
	v_mfma_f32_16x16x32_bf16 v[32:35], v[150:153], v[214:217], v[32:35]
	v_mfma_f32_16x16x32_bf16 v[28:31], v[166:169], v[214:217], v[28:31]
	v_mfma_f32_16x16x32_bf16 v[16:19], v[150:153], v[222:225], v[16:19]
	v_mfma_f32_16x16x32_bf16 v[12:15], v[166:169], v[222:225], v[12:15]
	s_setprio 0
	s_setprio 1
	v_mfma_f32_16x16x32_bf16 v[56:59], v[170:173], v[186:189], v[56:59]
	v_mfma_f32_16x16x32_bf16 v[52:55], v[178:181], v[186:189], v[52:55]
	v_mfma_f32_16x16x32_bf16 v[40:43], v[170:173], v[202:205], v[40:43]
	v_mfma_f32_16x16x32_bf16 v[36:39], v[178:181], v[202:205], v[36:39]
	v_mfma_f32_16x16x32_bf16 v[24:27], v[170:173], v[210:213], v[24:27]
	v_mfma_f32_16x16x32_bf16 v[20:23], v[178:181], v[210:213], v[20:23]
	v_mfma_f32_16x16x32_bf16 v[8:11], v[170:173], v[218:221], v[8:11]
	v_mfma_f32_16x16x32_bf16 v[4:7], v[178:181], v[218:221], v[4:7]
	v_mfma_f32_16x16x32_bf16 v[56:59], v[174:177], v[190:193], v[56:59]
	v_mfma_f32_16x16x32_bf16 v[52:55], v[182:185], v[190:193], v[52:55]
	v_mfma_f32_16x16x32_bf16 v[40:43], v[174:177], v[206:209], v[40:43]
	v_mfma_f32_16x16x32_bf16 v[36:39], v[182:185], v[206:209], v[36:39]
	v_mfma_f32_16x16x32_bf16 v[24:27], v[174:177], v[214:217], v[24:27]
	v_mfma_f32_16x16x32_bf16 v[20:23], v[182:185], v[214:217], v[20:23]
	v_mfma_f32_16x16x32_bf16 v[8:11], v[174:177], v[222:225], v[8:11]
	v_mfma_f32_16x16x32_bf16 v[4:7], v[182:185], v[222:225], v[4:7]
	s_setprio 0
	s_barrier
	s_add_i32 s40, 0, 0x18000
	v_add_u32_e32 v161, s40, v141
	s_add_i32 s41, 0, 0x1c000
	ds_read_b128 v[146:149], v161
	ds_read_b128 v[150:153], v161 offset:1024
	ds_read_b128 v[162:165], v161 offset:2048
	ds_read_b128 v[166:169], v161 offset:3072
	v_add_u32_e32 v161, s41, v141
	ds_read_b128 v[170:173], v161
	ds_read_b128 v[174:177], v161 offset:1024
	ds_read_b128 v[178:181], v161 offset:2048
	ds_read_b128 v[182:185], v161 offset:3072
	s_add_u32 s28, s28, 0x40000
	s_addc_u32 s29, s29, 0
	s_mov_b32 m0, s50
	s_nop 0
	global_load_lds_dwordx4 v[194:195], off
	s_mov_b32 m0, s51
	s_nop 0
	global_load_lds_dwordx4 v[226:227], off
	s_mov_b32 m0, s52
	v_lshl_add_u64 v[228:229], s[28:29], 0, v[132:133]
	ds_read_b128 v[186:189], v157 offset:32768
	ds_read_b128 v[190:193], v157 offset:33792
	ds_read_b128 v[202:205], v157 offset:34816
	ds_read_b128 v[206:209], v157 offset:35840
	ds_read_b128 v[210:213], v157 offset:36864
	ds_read_b128 v[214:217], v157 offset:37888
	ds_read_b128 v[218:221], v157 offset:38912
	ds_read_b128 v[222:225], v157 offset:39936
	global_load_lds_dwordx4 v[228:229], off
	v_lshl_add_u64 v[228:229], s[28:29], 0, v[136:137]
	s_mov_b32 m0, s53
	s_nop 0
	global_load_lds_dwordx4 v[228:229], off
	s_waitcnt vmcnt(8)
	s_waitcnt lgkmcnt(0)
	s_barrier
	s_setprio 1
	s_waitcnt lgkmcnt(0)
	v_mfma_f32_16x16x32_bf16 v[128:131], v[146:149], v[186:189], v[128:131]
	v_mfma_f32_16x16x32_bf16 v[124:127], v[162:165], v[186:189], v[124:127]
	v_mfma_f32_16x16x32_bf16 v[112:115], v[146:149], v[202:205], v[112:115]
	v_mfma_f32_16x16x32_bf16 v[108:111], v[162:165], v[202:205], v[108:111]
	v_mfma_f32_16x16x32_bf16 v[96:99], v[146:149], v[210:213], v[96:99]
	v_mfma_f32_16x16x32_bf16 v[92:95], v[162:165], v[210:213], v[92:95]
	v_mfma_f32_16x16x32_bf16 v[80:83], v[146:149], v[218:221], v[80:83]
	v_mfma_f32_16x16x32_bf16 v[76:79], v[162:165], v[218:221], v[76:79]
	v_mfma_f32_16x16x32_bf16 v[128:131], v[150:153], v[190:193], v[128:131]
	v_mfma_f32_16x16x32_bf16 v[124:127], v[166:169], v[190:193], v[124:127]
	v_mfma_f32_16x16x32_bf16 v[112:115], v[150:153], v[206:209], v[112:115]
	v_mfma_f32_16x16x32_bf16 v[108:111], v[166:169], v[206:209], v[108:111]
	v_mfma_f32_16x16x32_bf16 v[96:99], v[150:153], v[214:217], v[96:99]
	v_mfma_f32_16x16x32_bf16 v[92:95], v[166:169], v[214:217], v[92:95]
	v_mfma_f32_16x16x32_bf16 v[80:83], v[150:153], v[222:225], v[80:83]
	v_mfma_f32_16x16x32_bf16 v[76:79], v[166:169], v[222:225], v[76:79]
	s_setprio 0
	s_setprio 1
	v_mfma_f32_16x16x32_bf16 v[120:123], v[170:173], v[186:189], v[120:123]
	v_mfma_f32_16x16x32_bf16 v[116:119], v[178:181], v[186:189], v[116:119]
	v_mfma_f32_16x16x32_bf16 v[104:107], v[170:173], v[202:205], v[104:107]
	v_mfma_f32_16x16x32_bf16 v[100:103], v[178:181], v[202:205], v[100:103]
	v_mfma_f32_16x16x32_bf16 v[88:91], v[170:173], v[210:213], v[88:91]
	v_mfma_f32_16x16x32_bf16 v[84:87], v[178:181], v[210:213], v[84:87]
	v_mfma_f32_16x16x32_bf16 v[72:75], v[170:173], v[218:221], v[72:75]
	v_mfma_f32_16x16x32_bf16 v[68:71], v[178:181], v[218:221], v[68:71]
	v_mfma_f32_16x16x32_bf16 v[120:123], v[174:177], v[190:193], v[120:123]
	v_mfma_f32_16x16x32_bf16 v[116:119], v[182:185], v[190:193], v[116:119]
	v_mfma_f32_16x16x32_bf16 v[104:107], v[174:177], v[206:209], v[104:107]
	v_mfma_f32_16x16x32_bf16 v[100:103], v[182:185], v[206:209], v[100:103]
	v_mfma_f32_16x16x32_bf16 v[88:91], v[174:177], v[214:217], v[88:91]
	v_mfma_f32_16x16x32_bf16 v[84:87], v[182:185], v[214:217], v[84:87]
	v_mfma_f32_16x16x32_bf16 v[72:75], v[174:177], v[222:225], v[72:75]
	v_mfma_f32_16x16x32_bf16 v[68:71], v[182:185], v[222:225], v[68:71]
	s_setprio 0
	s_barrier
; #define PG8_STAGE(bufoff, gbase, voff) do { _Pragma("unroll") for (int _i = 0; _i < 2; ++_i) \
;         __builtin_amdgcn_global_load_lds((const unsigned*)((const char*)(gbase) + (voff)[_i]), (LAS unsigned*)(lds + (bufoff) + ldsw + _i * 8192), 16, 0, 0); } while (0)
; #define PG8_LDA(dst, b, h) do { _Pragma("unroll") for (int m = 0; m < 4; ++m) _Pragma("unroll") for (int k = 0; k < 2; ++k) dst[m][k] = *(const LAS bf16x8*)(lds + PG8_SA(b, h) + aoff + m * 2048 + k * 1024); } while (0)
; #define PG8_MMA(ai, bj, At, Bt) do { __builtin_amdgcn_s_setprio(1); _Pragma("unroll") for (int m = 0; m < 4; ++m) _Pragma("unroll") for (int n = 0; n < 2; ++n) _Pragma("unroll") for (int k = 0; k < 2; ++k) \
;         acc[ai][bj][m][n] = __builtin_amdgcn_mfma_f32_16x16x32_bf16(Bt[n][k], At[m][k], acc[ai][bj][m][n], 0, 0, 0); __builtin_amdgcn_s_setprio(0); } while (0)
; #define PG8_WAIT_V(n) asm volatile("s_waitcnt vmcnt(" #n ")" ::: "memory")
; #define PG8_WAIT_L(n) asm volatile("s_waitcnt lgkmcnt(" #n ")" ::: "memory")
; #define PG8_BAR __builtin_amdgcn_s_barrier()
; #define PG8_SCHED __builtin_amdgcn_sched_barrier(0)
; template <class Epi, bool ALIGN_EPI>
; DI void gemm_phase(LAS unsigned char* lds, const Sched& S, const Epi& E, int tid) {
;     ...
;     for (;;) {
;         const bool has_next = S.next(ui + 1, nxt);
;         const char* nA = has_next ? nxt.a : cA; const char* nB = has_next ? nxt.b : cB;
;         const int nt = cur.nt;
;         for (int t = 0; t < nt; t += 2) {
;     ...
;             PG8_LDA(At, 1, 1); PG8_STAGE(PG8_SB(1, 0), b3, voffB); PG8_STAGE(PG8_SB(1, 1), b3 + hstepB, voffB); PG8_STAGE(PG8_SA(1, 0), a3, voffA);
;             PG8_WAIT_V(8); PG8_WAIT_L(0); PG8_BAR; PG8_MMA(1, 0, At, B0); PG8_MMA(1, 1, At, B1); PG8_BAR; PG8_SCHED;
;         }
	s_add_i32 s28, s40, s49
	v_lshl_add_u64 v[154:155], v[154:155], 0, s[84:85]
	s_mov_b32 m0, s28
	ds_read_b128 v[186:189], v157 offset:49152
	ds_read_b128 v[190:193], v157 offset:50176
	ds_read_b128 v[202:205], v157 offset:51200
	ds_read_b128 v[206:209], v157 offset:52224
	ds_read_b128 v[210:213], v157 offset:53248
	ds_read_b128 v[214:217], v157 offset:54272
	ds_read_b128 v[218:221], v157 offset:55296
	ds_read_b128 v[222:225], v157 offset:56320
	global_load_lds_dwordx4 v[154:155], off
	s_add_i32 m0, s28, 0x2000
	s_add_u32 s24, s24, 0x40080
	v_lshl_add_u64 v[154:155], v[158:159], 0, s[84:85]
	s_addc_u32 s25, s25, 0
	s_add_i32 s28, s41, s49
	global_load_lds_dwordx4 v[154:155], off
	v_lshl_add_u64 v[154:155], s[24:25], 0, v[134:135]
	s_mov_b32 m0, s28
	s_nop 0
	global_load_lds_dwordx4 v[154:155], off
	v_lshl_add_u64 v[154:155], s[24:25], 0, v[138:139]
	s_add_i32 m0, s28, 0x2000
	s_nop 0
	global_load_lds_dwordx4 v[154:155], off
	v_lshl_add_u64 v[230:231], v[194:195], 0, s[84:85]
	v_lshl_add_u64 v[232:233], v[226:227], 0, s[84:85]
	s_waitcnt vmcnt(6)
	s_waitcnt lgkmcnt(0)
	s_barrier
	s_setprio 1
	s_waitcnt lgkmcnt(0)
	v_mfma_f32_16x16x32_bf16 v[64:67], v[146:149], v[186:189], v[64:67]
	v_mfma_f32_16x16x32_bf16 v[60:63], v[162:165], v[186:189], v[60:63]
	v_mfma_f32_16x16x32_bf16 v[48:51], v[146:149], v[202:205], v[48:51]
	v_mfma_f32_16x16x32_bf16 v[44:47], v[162:165], v[202:205], v[44:47]
	v_mfma_f32_16x16x32_bf16 v[32:35], v[146:149], v[210:213], v[32:35]
	v_mfma_f32_16x16x32_bf16 v[28:31], v[162:165], v[210:213], v[28:31]
	v_mfma_f32_16x16x32_bf16 v[16:19], v[146:149], v[218:221], v[16:19]
	v_mfma_f32_16x16x32_bf16 v[12:15], v[162:165], v[218:221], v[12:15]
	v_mfma_f32_16x16x32_bf16 v[64:67], v[150:153], v[190:193], v[64:67]
	v_mfma_f32_16x16x32_bf16 v[60:63], v[166:169], v[190:193], v[60:63]
	v_mfma_f32_16x16x32_bf16 v[48:51], v[150:153], v[206:209], v[48:51]
	v_mfma_f32_16x16x32_bf16 v[44:47], v[166:169], v[206:209], v[44:47]
	v_mfma_f32_16x16x32_bf16 v[32:35], v[150:153], v[214:217], v[32:35]
	v_mfma_f32_16x16x32_bf16 v[28:31], v[166:169], v[214:217], v[28:31]
	v_mfma_f32_16x16x32_bf16 v[16:19], v[150:153], v[222:225], v[16:19]
	v_mfma_f32_16x16x32_bf16 v[12:15], v[166:169], v[222:225], v[12:15]
	s_setprio 0
	s_setprio 1
	v_mfma_f32_16x16x32_bf16 v[56:59], v[170:173], v[186:189], v[56:59]
	v_mfma_f32_16x16x32_bf16 v[52:55], v[178:181], v[186:189], v[52:55]
	v_mfma_f32_16x16x32_bf16 v[40:43], v[170:173], v[202:205], v[40:43]
	v_mfma_f32_16x16x32_bf16 v[36:39], v[178:181], v[202:205], v[36:39]
	v_mfma_f32_16x16x32_bf16 v[24:27], v[170:173], v[210:213], v[24:27]
	v_mfma_f32_16x16x32_bf16 v[20:23], v[178:181], v[210:213], v[20:23]
	v_mfma_f32_16x16x32_bf16 v[8:11], v[170:173], v[218:221], v[8:11]
	v_mfma_f32_16x16x32_bf16 v[4:7], v[178:181], v[218:221], v[4:7]
	v_mfma_f32_16x16x32_bf16 v[56:59], v[174:177], v[190:193], v[56:59]
	v_mfma_f32_16x16x32_bf16 v[52:55], v[182:185], v[190:193], v[52:55]
	v_mfma_f32_16x16x32_bf16 v[40:43], v[174:177], v[206:209], v[40:43]
	v_mfma_f32_16x16x32_bf16 v[36:39], v[182:185], v[206:209], v[36:39]
	v_mfma_f32_16x16x32_bf16 v[24:27], v[174:177], v[214:217], v[24:27]
	v_mfma_f32_16x16x32_bf16 v[20:23], v[182:185], v[214:217], v[20:23]
	v_mfma_f32_16x16x32_bf16 v[8:11], v[174:177], v[222:225], v[8:11]
	v_mfma_f32_16x16x32_bf16 v[4:7], v[182:185], v[222:225], v[4:7]
	s_setprio 0
	s_barrier
	s_add_i32 s39, s39, 2
	s_add_u32 s22, s22, 0x100
	s_addc_u32 s23, s23, 0
	s_add_u32 s37, s37, 0x100
	s_addc_u32 s38, s38, 0
	s_cmp_gt_u32 s39, 13
	s_cbranch_scc0 .LBB0_653
	s_and_b64 vcc, exec, s[18:19]
	s_cbranch_vccz .LBB0_656
	s_barrier

; #define PG8_STAGE(bufoff, gbase, voff) do { _Pragma("unroll") for (int _i = 0; _i < 2; ++_i) \
;         __builtin_amdgcn_global_load_lds((const unsigned*)((const char*)(gbase) + (voff)[_i]), (LAS unsigned*)(lds + (bufoff) + ldsw + _i * 8192), 16, 0, 0); } while (0)
; #define PG8_WAIT_V(n) asm volatile("s_waitcnt vmcnt(" #n ")" ::: "memory")
; #define PG8_BAR __builtin_amdgcn_s_barrier()
; template <class Epi, bool ALIGN_EPI>
; DI void gemm_phase(LAS unsigned char* lds, const Sched& S, const Epi& E, int tid) {
;     const int wid = __builtin_amdgcn_readfirstlane(tid >> 6), lane = tid & 63, wr = wid >> 2, wc = wid & 3, fr = lane & 15, fq = lane >> 4;
;     const int lda = S.lda, ldb = S.ldb;
;     unsigned voffA[2], voffB[2];
; #pragma unroll
;     for (int i = 0; i < 2; ++i) { int R, C; stage_rc(tid * 16 + i * 8192, R, C); const int Rb = (R & ~31) + perm32(R & 31);
;         voffA[i] = (unsigned)(R * lda + C) * 2u; voffB[i] = (unsigned)(Rb * ldb + C) * 2u; }
;     const size_t kstep = (size_t)(BK * 2);
;     const size_t hstepA = (size_t)HALF * lda * 2, hstepB = (size_t)HALF * ldb * 2;
;     const unsigned ldsw = (unsigned)wid * 1024u;
;     const int aoff = lds_byte(wr * 64 + fr, fq * 8), boff = lds_byte(wc * 32 + fr, fq * 8);
;     ...
;     Unit cur, nxt; int ui = 0;
;     if (!S.next(0, cur)) return;
;     f32x4 acc[2][2][4][2];
; #pragma unroll
;     for (int a = 0; a < 2; ++a)
; #pragma unroll
;         for (int b = 0; b < 2; ++b)
; #pragma unroll
;             for (int m = 0; m < 4; ++m)
; #pragma unroll
;                 for (int n = 0; n < 2; ++n) acc[a][b][m][n] = (f32x4){0.f, 0.f, 0.f, 0.f};
;     bf16x8 At[4][2], B0[2][2], B1[2][2];
;     const char* cA = cur.a; const char* cB = cur.b;
;     PG8_STAGE(PG8_SB(0, 0), cB, voffB); PG8_STAGE(PG8_SB(0, 1), cB + hstepB, voffB); PG8_STAGE(PG8_SA(0, 0), cA, voffA); PG8_STAGE(PG8_SA(0, 1), cA + hstepA, voffA);
;     if (wr == 1) PG8_BAR;
;     PG8_WAIT_V(2); PG8_BAR;
;     PG8_STAGE(PG8_SB(1, 0), cB + kstep, voffB); PG8_STAGE(PG8_SA(1, 0), cA + kstep, voffA); PG8_STAGE(PG8_SB(1, 1), cB + hstepB + kstep, voffB);
;     PG8_WAIT_V(6); PG8_BAR;
.LBB0_1040:
	v_lshrrev_b32_e32 v19, 1, v0
	v_and_b32_e32 v19, 24, v19
	v_and_b32_e32 v18, 15, v0
	v_lshlrev_b32_e32 v20, 1, v19
	s_lshl_b32 s6, s6, 5
	v_lshl_or_b32 v3, s1, 6, v18
	v_lshl_or_b32 v20, v18, 6, v20
	v_lshlrev_b32_e32 v18, 2, v18
	s_and_b32 s34, s6, 0x60
	s_lshl_b32 s7, s1, 13
	v_and_b32_e32 v21, 32, v18
	s_lshl_b32 s6, s34, 7
	v_bitop3_b32 v141, s6, v20, v21 bitop3:0xf6
	s_add_u32 s6, s96, 0x16b00000
	v_bitop3_b32 v22, v20, s7, v21 bitop3:0xde
	s_addc_u32 s7, s97, 0
	s_lshl_b64 s[10:11], s[90:91], 24
	v_readlane_b32 s8, v253, 54
	s_add_u32 s8, s8, s10
	v_readlane_b32 s9, v253, 55
	s_addc_u32 s9, s9, s11
	v_readlane_b32 s12, v253, 56
	s_add_u32 s10, s12, s10
	v_readlane_b32 s12, v253, 57
	s_addc_u32 s11, s12, s11
	v_readlane_b32 s12, v253, 58
	s_add_u32 s12, s12, s18
	v_readlane_b32 s13, v253, 59
	s_addc_u32 s13, s13, s19
	v_readlane_b32 s14, v253, 60
	s_add_u32 s14, s14, s18
	v_readlane_b32 s15, v253, 61
	s_addc_u32 s15, s15, s19
	s_add_i32 m0, s55, 0x18000
	v_lshl_add_u64 v[10:11], v[10:11], 0, s[84:85]
	s_waitcnt vmcnt(2)
	s_barrier
	global_load_lds_dwordx4 v[10:11], off
	v_lshl_add_u64 v[8:9], v[8:9], 0, s[84:85]
	s_add_i32 m0, s55, 0x1a000
	s_add_i32 s59, s55, 0x8000
	s_add_i32 s60, s55, 0xa000
	global_load_lds_dwordx4 v[8:9], off
	v_lshl_add_u64 v[4:5], v[4:5], 0, s[84:85]
	s_mov_b32 m0, s59
	s_add_u32 s26, s20, 0x40080
	v_mov_b64_e32 v[230:231], v[4:5]
	global_load_lds_dwordx4 v[4:5], off
	v_lshl_add_u64 v[4:5], v[6:7], 0, s[84:85]
	s_mov_b32 m0, s60
	s_addc_u32 s27, s21, 0
	v_mov_b64_e32 v[232:233], v[4:5]
	global_load_lds_dwordx4 v[4:5], off
	s_add_i32 m0, s55, 0x1c000
	v_lshl_add_u64 v[4:5], s[26:27], 0, v[134:135]
	global_load_lds_dwordx4 v[4:5], off
	v_lshl_add_u64 v[4:5], s[26:27], 0, v[138:139]
	s_add_i32 m0, s55, 0x1e000
	s_cmpk_lt_u32 s16, 0x100
	global_load_lds_dwordx4 v[4:5], off
	v_lshlrev_b32_e32 v4, 14, v12
	s_cselect_b64 s[16:17], -1, 0
	s_add_u32 s61, s72, s18
	v_and_b32_e32 v4, 0xffff8000, v4
	s_addc_u32 s62, s73, s19
	s_lshl_b32 s1, s1, 8
	v_lshl_add_u32 v4, v13, 11, v4
	v_and_b32_e32 v5, 1, v12
	s_add_i32 s1, s1, 0
	v_lshl_or_b32 v4, v5, 6, v4
	s_add_i32 s1, s1, 0x20000
	v_lshl_add_u32 v142, v14, 1, v4
	v_lshlrev_b32_e32 v4, 14, v15
	s_add_u32 s18, s22, 0x1d80000
	v_and_b32_e32 v4, 0xffff8000, v4
	s_waitcnt vmcnt(6)
	s_addc_u32 s19, s23, 0
	s_lshl_b64 s[22:23], s[90:91], 20
	v_lshl_add_u32 v4, v16, 11, v4
	v_and_b32_e32 v5, 1, v15
	s_add_u32 s63, s96, s22
	v_lshl_or_b32 v4, v5, 6, v4
	v_or_b32_e32 v140, s34, v19
	v_add_u32_e32 v161, s1, v18
	s_addc_u32 s64, s97, s23
	v_mov_b32_e32 v143, v2
	v_lshl_add_u32 v144, v17, 1, v4
	v_mov_b32_e32 v145, v2
	s_mov_b32 s36, 0
	v_add_u32_e32 v172, 0, v22
	s_mov_b32 s65, 0
	s_barrier
	s_branch .LBB0_1043

; #define PG8_STAGE(bufoff, gbase, voff) do { _Pragma("unroll") for (int _i = 0; _i < 2; ++_i) \
;         __builtin_amdgcn_global_load_lds((const unsigned*)((const char*)(gbase) + (voff)[_i]), (LAS unsigned*)(lds + (bufoff) + ldsw + _i * 8192), 16, 0, 0); } while (0)
; #define PG8_LDA(dst, b, h) do { _Pragma("unroll") for (int m = 0; m < 4; ++m) _Pragma("unroll") for (int k = 0; k < 2; ++k) dst[m][k] = *(const LAS bf16x8*)(lds + PG8_SA(b, h) + aoff + m * 2048 + k * 1024); } while (0)
; #define PG8_LDB(dst, b, h) do { _Pragma("unroll") for (int n = 0; n < 2; ++n) _Pragma("unroll") for (int k = 0; k < 2; ++k) dst[n][k] = *(const LAS bf16x8*)(lds + PG8_SB(b, h) + boff + n * 2048 + k * 1024); } while (0)
; #define PG8_MMA(ai, bj, At, Bt) do { __builtin_amdgcn_s_setprio(1); _Pragma("unroll") for (int m = 0; m < 4; ++m) _Pragma("unroll") for (int n = 0; n < 2; ++n) _Pragma("unroll") for (int k = 0; k < 2; ++k) \
;         acc[ai][bj][m][n] = __builtin_amdgcn_mfma_f32_16x16x32_bf16(Bt[n][k], At[m][k], acc[ai][bj][m][n], 0, 0, 0); __builtin_amdgcn_s_setprio(0); } while (0)
; #define PG8_WAIT_V(n) asm volatile("s_waitcnt vmcnt(" #n ")" ::: "memory")
; #define PG8_WAIT_L(n) asm volatile("s_waitcnt lgkmcnt(" #n ")" ::: "memory")
; #define PG8_BAR __builtin_amdgcn_s_barrier()
; #define PG8_SCHED __builtin_amdgcn_sched_barrier(0)
; template <class Epi, bool ALIGN_EPI>
; DI void gemm_phase(LAS unsigned char* lds, const Sched& S, const Epi& E, int tid) {
;     ...
;         for (int t = 0; t < nt; t += 2) {
;             const bool last = (t == nt - 2);
;             const char* a1 = cA + (size_t)(t + 1) * kstep;
;             const char* a2 = last ? nA : cA + (size_t)(t + 2) * kstep; const char* b2 = last ? nB : cB + (size_t)(t + 2) * kstep;
;             const char* a3 = a2 + kstep; const char* b3 = b2 + kstep;
;             PG8_LDB(B0, 0, 0); PG8_LDB(B1, 0, 1); PG8_SCHED; PG8_LDA(At, 0, 0); PG8_STAGE(PG8_SA(1, 1), a1 + hstepA, voffA);
;             PG8_WAIT_V(8); PG8_WAIT_L(0); PG8_BAR; PG8_MMA(0, 0, At, B0); PG8_MMA(0, 1, At, B1); PG8_BAR; PG8_SCHED;
;             PG8_LDA(At, 0, 1); PG8_STAGE(PG8_SB(0, 0), b2, voffB); PG8_STAGE(PG8_SB(0, 1), b2 + hstepB, voffB); PG8_STAGE(PG8_SA(0, 0), a2, voffA);
;             PG8_WAIT_V(8); PG8_WAIT_L(0); PG8_BAR; PG8_MMA(1, 0, At, B0); PG8_MMA(1, 1, At, B1); PG8_BAR; PG8_SCHED;
.LBB0_1049:
	s_add_u32 s20, s2, 0xfffc0080
	s_addc_u32 s21, s3, -1
	s_add_i32 s47, 0, 0x10000
	s_cmp_eq_u32 s46, 12
	s_cselect_b32 s23, s1, s21
	s_cselect_b32 s22, s37, s20
	v_add_u32_e32 v158, s47, v141
	s_cselect_b32 s21, s38, s41
	s_cselect_b32 s20, s39, s40
	s_add_i32 s68, 0, 0x14000
	ds_read_b128 v[146:149], v158
	ds_read_b128 v[150:153], v158 offset:1024
	ds_read_b128 v[154:157], v158 offset:2048
	ds_read_b128 v[162:165], v158 offset:3072
	v_add_u32_e32 v158, s68, v141
	ds_read_b128 v[166:169], v158
	ds_read_b128 v[174:177], v158 offset:1024
	ds_read_b128 v[178:181], v158 offset:2048
	ds_read_b128 v[182:185], v158 offset:3072
	v_lshl_add_u64 v[158:159], s[2:3], 0, v[142:143]
	s_mov_b32 m0, s59
	s_nop 0
	global_load_lds_dwordx4 v[230:231], off
	s_mov_b32 m0, s60
	s_nop 0
	global_load_lds_dwordx4 v[232:233], off
	s_add_i32 m0, s55, 0xc000
	ds_read_b128 v[186:189], v172
	ds_read_b128 v[190:193], v172 offset:1024
	ds_read_b128 v[202:205], v172 offset:2048
	ds_read_b128 v[206:209], v172 offset:3072
	ds_read_b128 v[210:213], v172 offset:4096
	ds_read_b128 v[214:217], v172 offset:5120
	ds_read_b128 v[218:221], v172 offset:6144
	ds_read_b128 v[222:225], v172 offset:7168
	global_load_lds_dwordx4 v[158:159], off
	v_lshl_add_u64 v[158:159], s[2:3], 0, v[144:145]
	s_add_i32 m0, s55, 0xe000
	s_nop 0
	global_load_lds_dwordx4 v[158:159], off
	s_waitcnt vmcnt(8)
	s_waitcnt lgkmcnt(0)
	s_barrier
	s_setprio 1
	s_waitcnt lgkmcnt(0)
	v_mfma_f32_16x16x32_bf16 v[128:131], v[146:149], v[186:189], v[128:131]
	v_mfma_f32_16x16x32_bf16 v[124:127], v[154:157], v[186:189], v[124:127]
	v_mfma_f32_16x16x32_bf16 v[112:115], v[146:149], v[202:205], v[112:115]
	v_mfma_f32_16x16x32_bf16 v[108:111], v[154:157], v[202:205], v[108:111]
	v_mfma_f32_16x16x32_bf16 v[96:99], v[146:149], v[210:213], v[96:99]
	v_mfma_f32_16x16x32_bf16 v[92:95], v[154:157], v[210:213], v[92:95]
	v_mfma_f32_16x16x32_bf16 v[80:83], v[146:149], v[218:221], v[80:83]
	v_mfma_f32_16x16x32_bf16 v[76:79], v[154:157], v[218:221], v[76:79]
	v_mfma_f32_16x16x32_bf16 v[128:131], v[150:153], v[190:193], v[128:131]
	v_mfma_f32_16x16x32_bf16 v[124:127], v[162:165], v[190:193], v[124:127]
	v_mfma_f32_16x16x32_bf16 v[112:115], v[150:153], v[206:209], v[112:115]
	v_mfma_f32_16x16x32_bf16 v[108:111], v[162:165], v[206:209], v[108:111]
	v_mfma_f32_16x16x32_bf16 v[96:99], v[150:153], v[214:217], v[96:99]
	v_mfma_f32_16x16x32_bf16 v[92:95], v[162:165], v[214:217], v[92:95]
	v_mfma_f32_16x16x32_bf16 v[80:83], v[150:153], v[222:225], v[80:83]
	v_mfma_f32_16x16x32_bf16 v[76:79], v[162:165], v[222:225], v[76:79]
	s_setprio 0
	s_setprio 1
	v_mfma_f32_16x16x32_bf16 v[120:123], v[166:169], v[186:189], v[120:123]
	v_mfma_f32_16x16x32_bf16 v[116:119], v[178:181], v[186:189], v[116:119]
	v_mfma_f32_16x16x32_bf16 v[104:107], v[166:169], v[202:205], v[104:107]
	v_mfma_f32_16x16x32_bf16 v[100:103], v[178:181], v[202:205], v[100:103]
	v_mfma_f32_16x16x32_bf16 v[88:91], v[166:169], v[210:213], v[88:91]
	v_mfma_f32_16x16x32_bf16 v[84:87], v[178:181], v[210:213], v[84:87]
	v_mfma_f32_16x16x32_bf16 v[72:75], v[166:169], v[218:221], v[72:75]
	v_mfma_f32_16x16x32_bf16 v[68:71], v[178:181], v[218:221], v[68:71]
	v_mfma_f32_16x16x32_bf16 v[120:123], v[174:177], v[190:193], v[120:123]
	v_mfma_f32_16x16x32_bf16 v[116:119], v[182:185], v[190:193], v[116:119]
	v_mfma_f32_16x16x32_bf16 v[104:107], v[174:177], v[206:209], v[104:107]
	v_mfma_f32_16x16x32_bf16 v[100:103], v[182:185], v[206:209], v[100:103]
	v_mfma_f32_16x16x32_bf16 v[88:91], v[174:177], v[214:217], v[88:91]
	v_mfma_f32_16x16x32_bf16 v[84:87], v[182:185], v[214:217], v[84:87]
	v_mfma_f32_16x16x32_bf16 v[72:75], v[174:177], v[222:225], v[72:75]
	v_mfma_f32_16x16x32_bf16 v[68:71], v[182:185], v[222:225], v[68:71]
	s_setprio 0
	s_barrier
	s_add_i32 s47, s47, s54
	v_lshl_add_u64 v[158:159], s[20:21], 0, v[134:135]
	s_mov_b32 m0, s47
	ds_read_b128 v[186:189], v172 offset:16384
	ds_read_b128 v[190:193], v172 offset:17408
	ds_read_b128 v[202:205], v172 offset:18432
	ds_read_b128 v[206:209], v172 offset:19456
	ds_read_b128 v[210:213], v172 offset:20480
	ds_read_b128 v[214:217], v172 offset:21504
	ds_read_b128 v[218:221], v172 offset:22528
	ds_read_b128 v[222:225], v172 offset:23552
	global_load_lds_dwordx4 v[158:159], off
	s_add_i32 m0, s47, 0x2000
	s_add_u32 s48, s20, 0x40000
	v_lshl_add_u64 v[170:171], s[20:21], 0, v[138:139]
	s_addc_u32 s49, s21, 0
	s_add_i32 s47, s68, s54
	global_load_lds_dwordx4 v[170:171], off
	v_lshl_add_u64 v[194:195], s[48:49], 0, v[134:135]
	s_mov_b32 m0, s47
	v_lshl_add_u64 v[226:227], s[22:23], 0, v[136:137]
	global_load_lds_dwordx4 v[194:195], off
	v_lshl_add_u64 v[194:195], s[48:49], 0, v[138:139]
	s_add_i32 m0, s47, 0x2000
	s_nop 0
	global_load_lds_dwordx4 v[194:195], off
	v_lshl_add_u64 v[194:195], s[22:23], 0, v[132:133]
	s_waitcnt vmcnt(6)
	s_waitcnt lgkmcnt(0)
	s_barrier
; #define PG8_STAGE(bufoff, gbase, voff) do { _Pragma("unroll") for (int _i = 0; _i < 2; ++_i) \
;         __builtin_amdgcn_global_load_lds((const unsigned*)((const char*)(gbase) + (voff)[_i]), (LAS unsigned*)(lds + (bufoff) + ldsw + _i * 8192), 16, 0, 0); } while (0)
; #define PG8_LDA(dst, b, h) do { _Pragma("unroll") for (int m = 0; m < 4; ++m) _Pragma("unroll") for (int k = 0; k < 2; ++k) dst[m][k] = *(const LAS bf16x8*)(lds + PG8_SA(b, h) + aoff + m * 2048 + k * 1024); } while (0)
; #define PG8_LDB(dst, b, h) do { _Pragma("unroll") for (int n = 0; n < 2; ++n) _Pragma("unroll") for (int k = 0; k < 2; ++k) dst[n][k] = *(const LAS bf16x8*)(lds + PG8_SB(b, h) + boff + n * 2048 + k * 1024); } while (0)
; #define PG8_MMA(ai, bj, At, Bt) do { __builtin_amdgcn_s_setprio(1); _Pragma("unroll") for (int m = 0; m < 4; ++m) _Pragma("unroll") for (int n = 0; n < 2; ++n) _Pragma("unroll") for (int k = 0; k < 2; ++k) \
;         acc[ai][bj][m][n] = __builtin_amdgcn_mfma_f32_16x16x32_bf16(Bt[n][k], At[m][k], acc[ai][bj][m][n], 0, 0, 0); __builtin_amdgcn_s_setprio(0); } while (0)
; #define PG8_WAIT_V(n) asm volatile("s_waitcnt vmcnt(" #n ")" ::: "memory")
; #define PG8_WAIT_L(n) asm volatile("s_waitcnt lgkmcnt(" #n ")" ::: "memory")
; #define PG8_BAR __builtin_amdgcn_s_barrier()
; #define PG8_SCHED __builtin_amdgcn_sched_barrier(0)
; template <class Epi, bool ALIGN_EPI>
; DI void gemm_phase(LAS unsigned char* lds, const Sched& S, const Epi& E, int tid) {
;     ...
;             PG8_WAIT_V(8); PG8_WAIT_L(0); PG8_BAR; PG8_MMA(0, 0, At, B0); PG8_MMA(0, 1, At, B1); PG8_BAR; PG8_SCHED;
;             PG8_LDA(At, 0, 1); PG8_STAGE(PG8_SB(0, 0), b2, voffB); PG8_STAGE(PG8_SB(0, 1), b2 + hstepB, voffB); PG8_STAGE(PG8_SA(0, 0), a2, voffA);
;             PG8_WAIT_V(8); PG8_WAIT_L(0); PG8_BAR; PG8_MMA(1, 0, At, B0); PG8_MMA(1, 1, At, B1); PG8_BAR; PG8_SCHED;
;             PG8_LDB(B0, 1, 0); PG8_LDB(B1, 1, 1); PG8_SCHED; PG8_LDA(At, 1, 0); PG8_STAGE(PG8_SA(0, 1), a2 + hstepA, voffA);
;             PG8_WAIT_V(8); PG8_WAIT_L(0); PG8_BAR; PG8_MMA(0, 0, At, B0); PG8_MMA(0, 1, At, B1); PG8_BAR; PG8_SCHED;
;             PG8_LDA(At, 1, 1); PG8_STAGE(PG8_SB(1, 0), b3, voffB); PG8_STAGE(PG8_SB(1, 1), b3 + hstepB, voffB); PG8_STAGE(PG8_SA(1, 0), a3, voffA);
	s_setprio 1
	s_waitcnt lgkmcnt(0)
	v_mfma_f32_16x16x32_bf16 v[64:67], v[146:149], v[186:189], v[64:67]
	v_mfma_f32_16x16x32_bf16 v[60:63], v[154:157], v[186:189], v[60:63]
	v_mfma_f32_16x16x32_bf16 v[48:51], v[146:149], v[202:205], v[48:51]
	v_mfma_f32_16x16x32_bf16 v[44:47], v[154:157], v[202:205], v[44:47]
	v_mfma_f32_16x16x32_bf16 v[32:35], v[146:149], v[210:213], v[32:35]
	v_mfma_f32_16x16x32_bf16 v[28:31], v[154:157], v[210:213], v[28:31]
	v_mfma_f32_16x16x32_bf16 v[16:19], v[146:149], v[218:221], v[16:19]
	v_mfma_f32_16x16x32_bf16 v[12:15], v[154:157], v[218:221], v[12:15]
	v_mfma_f32_16x16x32_bf16 v[64:67], v[150:153], v[190:193], v[64:67]
	v_mfma_f32_16x16x32_bf16 v[60:63], v[162:165], v[190:193], v[60:63]
	v_mfma_f32_16x16x32_bf16 v[48:51], v[150:153], v[206:209], v[48:51]
	v_mfma_f32_16x16x32_bf16 v[44:47], v[162:165], v[206:209], v[44:47]
	v_mfma_f32_16x16x32_bf16 v[32:35], v[150:153], v[214:217], v[32:35]
	v_mfma_f32_16x16x32_bf16 v[28:31], v[162:165], v[214:217], v[28:31]
	v_mfma_f32_16x16x32_bf16 v[16:19], v[150:153], v[222:225], v[16:19]
	v_mfma_f32_16x16x32_bf16 v[12:15], v[162:165], v[222:225], v[12:15]
	s_setprio 0
	s_setprio 1
	v_mfma_f32_16x16x32_bf16 v[56:59], v[166:169], v[186:189], v[56:59]
	v_mfma_f32_16x16x32_bf16 v[52:55], v[178:181], v[186:189], v[52:55]
	v_mfma_f32_16x16x32_bf16 v[40:43], v[166:169], v[202:205], v[40:43]
	v_mfma_f32_16x16x32_bf16 v[36:39], v[178:181], v[202:205], v[36:39]
	v_mfma_f32_16x16x32_bf16 v[24:27], v[166:169], v[210:213], v[24:27]
	v_mfma_f32_16x16x32_bf16 v[20:23], v[178:181], v[210:213], v[20:23]
	v_mfma_f32_16x16x32_bf16 v[8:11], v[166:169], v[218:221], v[8:11]
	v_mfma_f32_16x16x32_bf16 v[4:7], v[178:181], v[218:221], v[4:7]
	v_mfma_f32_16x16x32_bf16 v[56:59], v[174:177], v[190:193], v[56:59]
	v_mfma_f32_16x16x32_bf16 v[52:55], v[182:185], v[190:193], v[52:55]
	v_mfma_f32_16x16x32_bf16 v[40:43], v[174:177], v[206:209], v[40:43]
	v_mfma_f32_16x16x32_bf16 v[36:39], v[182:185], v[206:209], v[36:39]
	v_mfma_f32_16x16x32_bf16 v[24:27], v[174:177], v[214:217], v[24:27]
	v_mfma_f32_16x16x32_bf16 v[20:23], v[182:185], v[214:217], v[20:23]
	v_mfma_f32_16x16x32_bf16 v[8:11], v[174:177], v[222:225], v[8:11]
	v_mfma_f32_16x16x32_bf16 v[4:7], v[182:185], v[222:225], v[4:7]
	s_setprio 0
	s_barrier
	s_add_i32 s47, 0, 0x18000
	s_add_i32 s48, 0, 0x1c000
	v_add_u32_e32 v162, s47, v141
	v_add_u32_e32 v173, s48, v141
	ds_read_b128 v[146:149], v162
	ds_read_b128 v[150:153], v162 offset:1024
	ds_read_b128 v[154:157], v162 offset:2048
	ds_read_b128 v[162:165], v162 offset:3072
	ds_read_b128 v[166:169], v173
	ds_read_b128 v[174:177], v173 offset:1024
	ds_read_b128 v[178:181], v173 offset:2048
	ds_read_b128 v[182:185], v173 offset:3072
	s_add_u32 s22, s22, 0x40000
	s_addc_u32 s23, s23, 0
	s_mov_b32 m0, s55
	s_nop 0
	global_load_lds_dwordx4 v[194:195], off
	s_mov_b32 m0, s56
	s_nop 0
	global_load_lds_dwordx4 v[226:227], off
	s_mov_b32 m0, s57
	v_lshl_add_u64 v[228:229], s[22:23], 0, v[132:133]
	ds_read_b128 v[186:189], v172 offset:32768
	ds_read_b128 v[190:193], v172 offset:33792
	ds_read_b128 v[202:205], v172 offset:34816
	ds_read_b128 v[206:209], v172 offset:35840
	ds_read_b128 v[210:213], v172 offset:36864
	ds_read_b128 v[214:217], v172 offset:37888
	ds_read_b128 v[218:221], v172 offset:38912
	ds_read_b128 v[222:225], v172 offset:39936
	global_load_lds_dwordx4 v[228:229], off
	v_lshl_add_u64 v[228:229], s[22:23], 0, v[136:137]
	s_mov_b32 m0, s58
	s_nop 0
	global_load_lds_dwordx4 v[228:229], off
	s_waitcnt vmcnt(8)
	s_waitcnt lgkmcnt(0)
	s_barrier
	s_setprio 1
	s_waitcnt lgkmcnt(0)
	v_mfma_f32_16x16x32_bf16 v[128:131], v[146:149], v[186:189], v[128:131]
	v_mfma_f32_16x16x32_bf16 v[124:127], v[154:157], v[186:189], v[124:127]
	v_mfma_f32_16x16x32_bf16 v[112:115], v[146:149], v[202:205], v[112:115]
	v_mfma_f32_16x16x32_bf16 v[108:111], v[154:157], v[202:205], v[108:111]
	v_mfma_f32_16x16x32_bf16 v[96:99], v[146:149], v[210:213], v[96:99]
	v_mfma_f32_16x16x32_bf16 v[92:95], v[154:157], v[210:213], v[92:95]
	v_mfma_f32_16x16x32_bf16 v[80:83], v[146:149], v[218:221], v[80:83]
	v_mfma_f32_16x16x32_bf16 v[76:79], v[154:157], v[218:221], v[76:79]
	v_mfma_f32_16x16x32_bf16 v[128:131], v[150:153], v[190:193], v[128:131]
	v_mfma_f32_16x16x32_bf16 v[124:127], v[162:165], v[190:193], v[124:127]
	v_mfma_f32_16x16x32_bf16 v[112:115], v[150:153], v[206:209], v[112:115]
	v_mfma_f32_16x16x32_bf16 v[108:111], v[162:165], v[206:209], v[108:111]
	v_mfma_f32_16x16x32_bf16 v[96:99], v[150:153], v[214:217], v[96:99]
	v_mfma_f32_16x16x32_bf16 v[92:95], v[162:165], v[214:217], v[92:95]
	v_mfma_f32_16x16x32_bf16 v[80:83], v[150:153], v[222:225], v[80:83]
	v_mfma_f32_16x16x32_bf16 v[76:79], v[162:165], v[222:225], v[76:79]
	s_setprio 0
	s_setprio 1
	v_mfma_f32_16x16x32_bf16 v[120:123], v[166:169], v[186:189], v[120:123]
	v_mfma_f32_16x16x32_bf16 v[116:119], v[178:181], v[186:189], v[116:119]
	v_mfma_f32_16x16x32_bf16 v[104:107], v[166:169], v[202:205], v[104:107]
	v_mfma_f32_16x16x32_bf16 v[100:103], v[178:181], v[202:205], v[100:103]
	v_mfma_f32_16x16x32_bf16 v[88:91], v[166:169], v[210:213], v[88:91]
	v_mfma_f32_16x16x32_bf16 v[84:87], v[178:181], v[210:213], v[84:87]
	v_mfma_f32_16x16x32_bf16 v[72:75], v[166:169], v[218:221], v[72:75]
	v_mfma_f32_16x16x32_bf16 v[68:71], v[178:181], v[218:221], v[68:71]
	v_mfma_f32_16x16x32_bf16 v[120:123], v[174:177], v[190:193], v[120:123]
	v_mfma_f32_16x16x32_bf16 v[116:119], v[182:185], v[190:193], v[116:119]
	v_mfma_f32_16x16x32_bf16 v[104:107], v[174:177], v[206:209], v[104:107]
	v_mfma_f32_16x16x32_bf16 v[100:103], v[182:185], v[206:209], v[100:103]
	v_mfma_f32_16x16x32_bf16 v[88:91], v[174:177], v[214:217], v[88:91]
	v_mfma_f32_16x16x32_bf16 v[84:87], v[182:185], v[214:217], v[84:87]
	v_mfma_f32_16x16x32_bf16 v[72:75], v[174:177], v[222:225], v[72:75]
	v_mfma_f32_16x16x32_bf16 v[68:71], v[182:185], v[222:225], v[68:71]
	s_setprio 0
	s_barrier
; #define PG8_STAGE(bufoff, gbase, voff) do { _Pragma("unroll") for (int _i = 0; _i < 2; ++_i) \
;         __builtin_amdgcn_global_load_lds((const unsigned*)((const char*)(gbase) + (voff)[_i]), (LAS unsigned*)(lds + (bufoff) + ldsw + _i * 8192), 16, 0, 0); } while (0)
; #define PG8_LDA(dst, b, h) do { _Pragma("unroll") for (int m = 0; m < 4; ++m) _Pragma("unroll") for (int k = 0; k < 2; ++k) dst[m][k] = *(const LAS bf16x8*)(lds + PG8_SA(b, h) + aoff + m * 2048 + k * 1024); } while (0)
; #define PG8_MMA(ai, bj, At, Bt) do { __builtin_amdgcn_s_setprio(1); _Pragma("unroll") for (int m = 0; m < 4; ++m) _Pragma("unroll") for (int n = 0; n < 2; ++n) _Pragma("unroll") for (int k = 0; k < 2; ++k) \
;         acc[ai][bj][m][n] = __builtin_amdgcn_mfma_f32_16x16x32_bf16(Bt[n][k], At[m][k], acc[ai][bj][m][n], 0, 0, 0); __builtin_amdgcn_s_setprio(0); } while (0)
; #define PG8_WAIT_V(n) asm volatile("s_waitcnt vmcnt(" #n ")" ::: "memory")
; #define PG8_WAIT_L(n) asm volatile("s_waitcnt lgkmcnt(" #n ")" ::: "memory")
; #define PG8_BAR __builtin_amdgcn_s_barrier()
; #define PG8_SCHED __builtin_amdgcn_sched_barrier(0)
; template <class Epi, bool ALIGN_EPI>
; DI void gemm_phase(LAS unsigned char* lds, const Sched& S, const Epi& E, int tid) {
;     ...
;     for (;;) {
;         const bool has_next = S.next(ui + 1, nxt);
;         const char* nA = has_next ? nxt.a : cA; const char* nB = has_next ? nxt.b : cB;
;         const int nt = cur.nt;
;         for (int t = 0; t < nt; t += 2) {
;     ...
;             PG8_LDA(At, 1, 1); PG8_STAGE(PG8_SB(1, 0), b3, voffB); PG8_STAGE(PG8_SB(1, 1), b3 + hstepB, voffB); PG8_STAGE(PG8_SA(1, 0), a3, voffA);
;             PG8_WAIT_V(8); PG8_WAIT_L(0); PG8_BAR; PG8_MMA(1, 0, At, B0); PG8_MMA(1, 1, At, B1); PG8_BAR; PG8_SCHED;
;         }
	s_add_i32 s22, s47, s54
	v_lshl_add_u64 v[158:159], v[158:159], 0, s[84:85]
	s_mov_b32 m0, s22
	ds_read_b128 v[186:189], v172 offset:49152
	ds_read_b128 v[190:193], v172 offset:50176
	ds_read_b128 v[202:205], v172 offset:51200
	ds_read_b128 v[206:209], v172 offset:52224
	ds_read_b128 v[210:213], v172 offset:53248
	ds_read_b128 v[214:217], v172 offset:54272
	ds_read_b128 v[218:221], v172 offset:55296
	ds_read_b128 v[222:225], v172 offset:56320
	global_load_lds_dwordx4 v[158:159], off
	s_add_i32 m0, s22, 0x2000
	s_add_u32 s20, s20, 0x40080
	v_lshl_add_u64 v[158:159], v[170:171], 0, s[84:85]
	s_addc_u32 s21, s21, 0
	s_add_i32 s22, s48, s54
	global_load_lds_dwordx4 v[158:159], off
	v_lshl_add_u64 v[158:159], s[20:21], 0, v[134:135]
	s_mov_b32 m0, s22
	s_nop 0
	global_load_lds_dwordx4 v[158:159], off
	v_lshl_add_u64 v[158:159], s[20:21], 0, v[138:139]
	s_add_i32 m0, s22, 0x2000
	s_nop 0
	global_load_lds_dwordx4 v[158:159], off
	v_lshl_add_u64 v[230:231], v[194:195], 0, s[84:85]
	v_lshl_add_u64 v[232:233], v[226:227], 0, s[84:85]
	s_waitcnt vmcnt(6)
	s_waitcnt lgkmcnt(0)
	s_barrier
	s_setprio 1
	s_waitcnt lgkmcnt(0)
	v_mfma_f32_16x16x32_bf16 v[64:67], v[146:149], v[186:189], v[64:67]
	v_mfma_f32_16x16x32_bf16 v[60:63], v[154:157], v[186:189], v[60:63]
	v_mfma_f32_16x16x32_bf16 v[48:51], v[146:149], v[202:205], v[48:51]
	v_mfma_f32_16x16x32_bf16 v[44:47], v[154:157], v[202:205], v[44:47]
	v_mfma_f32_16x16x32_bf16 v[32:35], v[146:149], v[210:213], v[32:35]
	v_mfma_f32_16x16x32_bf16 v[28:31], v[154:157], v[210:213], v[28:31]
	v_mfma_f32_16x16x32_bf16 v[16:19], v[146:149], v[218:221], v[16:19]
	v_mfma_f32_16x16x32_bf16 v[12:15], v[154:157], v[218:221], v[12:15]
	v_mfma_f32_16x16x32_bf16 v[64:67], v[150:153], v[190:193], v[64:67]
	v_mfma_f32_16x16x32_bf16 v[60:63], v[162:165], v[190:193], v[60:63]
	v_mfma_f32_16x16x32_bf16 v[48:51], v[150:153], v[206:209], v[48:51]
	v_mfma_f32_16x16x32_bf16 v[44:47], v[162:165], v[206:209], v[44:47]
	v_mfma_f32_16x16x32_bf16 v[32:35], v[150:153], v[214:217], v[32:35]
	v_mfma_f32_16x16x32_bf16 v[28:31], v[162:165], v[214:217], v[28:31]
	v_mfma_f32_16x16x32_bf16 v[16:19], v[150:153], v[222:225], v[16:19]
	v_mfma_f32_16x16x32_bf16 v[12:15], v[162:165], v[222:225], v[12:15]
	s_setprio 0
	s_setprio 1
	v_mfma_f32_16x16x32_bf16 v[56:59], v[166:169], v[186:189], v[56:59]
	v_mfma_f32_16x16x32_bf16 v[52:55], v[178:181], v[186:189], v[52:55]
	v_mfma_f32_16x16x32_bf16 v[40:43], v[166:169], v[202:205], v[40:43]
	v_mfma_f32_16x16x32_bf16 v[36:39], v[178:181], v[202:205], v[36:39]
	v_mfma_f32_16x16x32_bf16 v[24:27], v[166:169], v[210:213], v[24:27]
	v_mfma_f32_16x16x32_bf16 v[20:23], v[178:181], v[210:213], v[20:23]
	v_mfma_f32_16x16x32_bf16 v[8:11], v[166:169], v[218:221], v[8:11]
	v_mfma_f32_16x16x32_bf16 v[4:7], v[178:181], v[218:221], v[4:7]
	v_mfma_f32_16x16x32_bf16 v[56:59], v[174:177], v[190:193], v[56:59]
	v_mfma_f32_16x16x32_bf16 v[52:55], v[182:185], v[190:193], v[52:55]
	v_mfma_f32_16x16x32_bf16 v[40:43], v[174:177], v[206:209], v[40:43]
	v_mfma_f32_16x16x32_bf16 v[36:39], v[182:185], v[206:209], v[36:39]
	v_mfma_f32_16x16x32_bf16 v[24:27], v[174:177], v[214:217], v[24:27]
	v_mfma_f32_16x16x32_bf16 v[20:23], v[182:185], v[214:217], v[20:23]
	v_mfma_f32_16x16x32_bf16 v[8:11], v[174:177], v[222:225], v[8:11]
	v_mfma_f32_16x16x32_bf16 v[4:7], v[182:185], v[222:225], v[4:7]
	s_setprio 0
	s_barrier
	s_add_i32 s46, s46, 2
	s_add_u32 s2, s2, 0x100
	s_addc_u32 s3, s3, 0
	s_add_u32 s40, s40, 0x100
	s_addc_u32 s41, s41, 0
	s_cmp_gt_u32 s46, 13
	s_cbranch_scc0 .LBB0_1049
	s_and_b64 vcc, exec, s[16:17]
	s_cbranch_vccz .LBB0_1052
	s_barrier

; #define PG8_STAGE(bufoff, gbase, voff) do { _Pragma("unroll") for (int _i = 0; _i < 2; ++_i) \
;         __builtin_amdgcn_global_load_lds((const unsigned*)((const char*)(gbase) + (voff)[_i]), (LAS unsigned*)(lds + (bufoff) + ldsw + _i * 8192), 16, 0, 0); } while (0)
; #define PG8_WAIT_V(n) asm volatile("s_waitcnt vmcnt(" #n ")" ::: "memory")
; #define PG8_BAR __builtin_amdgcn_s_barrier()
; template <class Epi, bool ALIGN_EPI>
; DI void gemm_phase(LAS unsigned char* lds, const Sched& S, const Epi& E, int tid) {
;     const int wid = __builtin_amdgcn_readfirstlane(tid >> 6), lane = tid & 63, wr = wid >> 2, wc = wid & 3, fr = lane & 15, fq = lane >> 4;
;     const int lda = S.lda, ldb = S.ldb;
;     unsigned voffA[2], voffB[2];
; #pragma unroll
;     for (int i = 0; i < 2; ++i) { int R, C; stage_rc(tid * 16 + i * 8192, R, C); const int Rb = (R & ~31) + perm32(R & 31);
;         voffA[i] = (unsigned)(R * lda + C) * 2u; voffB[i] = (unsigned)(Rb * ldb + C) * 2u; }
;     const size_t kstep = (size_t)(BK * 2);
;     const size_t hstepA = (size_t)HALF * lda * 2, hstepB = (size_t)HALF * ldb * 2;
;     const unsigned ldsw = (unsigned)wid * 1024u;
;     const int aoff = lds_byte(wr * 64 + fr, fq * 8), boff = lds_byte(wc * 32 + fr, fq * 8);
;     ...
;     Unit cur, nxt; int ui = 0;
;     if (!S.next(0, cur)) return;
;     f32x4 acc[2][2][4][2];
; #pragma unroll
;     for (int a = 0; a < 2; ++a)
; #pragma unroll
;         for (int b = 0; b < 2; ++b)
; #pragma unroll
;             for (int m = 0; m < 4; ++m)
; #pragma unroll
;                 for (int n = 0; n < 2; ++n) acc[a][b][m][n] = (f32x4){0.f, 0.f, 0.f, 0.f};
;     bf16x8 At[4][2], B0[2][2], B1[2][2];
;     const char* cA = cur.a; const char* cB = cur.b;
;     PG8_STAGE(PG8_SB(0, 0), cB, voffB); PG8_STAGE(PG8_SB(0, 1), cB + hstepB, voffB); PG8_STAGE(PG8_SA(0, 0), cA, voffA); PG8_STAGE(PG8_SA(0, 1), cA + hstepA, voffA);
;     if (wr == 1) PG8_BAR;
;     PG8_WAIT_V(2); PG8_BAR;
;     PG8_STAGE(PG8_SB(1, 0), cB + kstep, voffB); PG8_STAGE(PG8_SA(1, 0), cA + kstep, voffA); PG8_STAGE(PG8_SB(1, 1), cB + hstepB + kstep, voffB);
;     PG8_WAIT_V(6); PG8_BAR;
.LBB0_1752:
	v_bfe_u32 v19, v0, 4, 2
	v_and_b32_e32 v18, 15, v0
	v_lshlrev_b32_e32 v21, 4, v19
	v_lshl_or_b32 v3, s3, 6, v18
	v_lshl_or_b32 v18, v18, 6, v21
	v_lshlrev_b32_e32 v21, 2, v0
	s_and_b32 s45, s2, 3
	s_lshl_b32 s2, s3, 13
	v_and_b32_e32 v21, 32, v21
	s_add_i32 m0, s41, 0x18000
	v_lshl_add_u64 v[10:11], v[10:11], 0, s[84:85]
	v_bitop3_b32 v22, v18, s2, v21 bitop3:0xde
	s_lshl_b32 s2, s45, 12
	s_waitcnt vmcnt(2)
	s_barrier
	global_load_lds_dwordx4 v[10:11], off
	v_lshl_add_u64 v[8:9], v[8:9], 0, s[84:85]
	s_add_i32 m0, s41, 0x1a000
	s_add_i32 s46, s41, 0x8000
	s_add_i32 s47, s41, 0xa000
	v_bitop3_b32 v161, s2, v18, v21 bitop3:0xf6
	global_load_lds_dwordx4 v[8:9], off
	v_lshl_add_u64 v[4:5], v[4:5], 0, s[84:85]
	s_mov_b32 m0, s46
	s_add_u32 s2, s26, 0x40080
	v_mov_b64_e32 v[230:231], v[4:5]
	global_load_lds_dwordx4 v[4:5], off
	v_lshl_add_u64 v[4:5], v[6:7], 0, s[84:85]
	s_mov_b32 m0, s47
	s_addc_u32 s3, s27, 0
	v_mov_b64_e32 v[232:233], v[4:5]
	global_load_lds_dwordx4 v[4:5], off
	s_add_i32 m0, s41, 0x1c000
	v_lshl_add_u64 v[4:5], s[2:3], 0, v[164:165]
	global_load_lds_dwordx4 v[4:5], off
	v_lshl_add_u64 v[4:5], s[2:3], 0, v[168:169]
	s_add_i32 m0, s41, 0x1e000
	s_cmpk_lt_u32 s6, 0x100
	global_load_lds_dwordx4 v[4:5], off
	v_lshlrev_b32_e32 v4, 14, v12
	s_cselect_b64 s[6:7], -1, 0
	s_add_u32 s49, s96, 0x1ff00000
	v_and_b32_e32 v4, 0xffff8000, v4
	s_addc_u32 s50, s97, 0
	v_lshl_add_u32 v4, v13, 11, v4
	v_and_b32_e32 v5, 1, v12
	s_add_u32 s8, s96, 0xff00000
	v_lshl_or_b32 v4, v5, 6, v4
	s_mul_i32 s10, s90, 0x480000
	s_addc_u32 s9, s97, 0
	v_lshl_add_u32 v170, v14, 1, v4
	v_lshlrev_b32_e32 v4, 14, v15
	s_add_u32 s10, s96, s10
	v_and_b32_e32 v4, 0xffff8000, v4
	s_waitcnt vmcnt(6)
	s_addc_u32 s11, s97, 0
	v_lshl_add_u32 v4, v16, 11, v4
	v_and_b32_e32 v5, 1, v15
	v_lshlrev_b32_e32 v20, 3, v19
	s_add_u32 s10, s10, 0x24340000
	v_lshl_or_b32 v4, v5, 6, v4
	v_lshl_or_b32 v192, s45, 5, v20
	s_mov_b32 s48, 0
	v_cmp_eq_u32_e64 s[2:3], 0, v19
	s_addc_u32 s11, s11, 0
	v_mov_b32_e32 v171, v2
	v_lshl_add_u32 v172, v17, 1, v4
	v_mov_b32_e32 v173, v2
	v_add_u32_e32 v193, 0, v22
	s_barrier
	s_branch .LBB0_1755

; #define PG8_STAGE(bufoff, gbase, voff) do { _Pragma("unroll") for (int _i = 0; _i < 2; ++_i) \
;         __builtin_amdgcn_global_load_lds((const unsigned*)((const char*)(gbase) + (voff)[_i]), (LAS unsigned*)(lds + (bufoff) + ldsw + _i * 8192), 16, 0, 0); } while (0)
; #define PG8_LDA(dst, b, h) do { _Pragma("unroll") for (int m = 0; m < 4; ++m) _Pragma("unroll") for (int k = 0; k < 2; ++k) dst[m][k] = *(const LAS bf16x8*)(lds + PG8_SA(b, h) + aoff + m * 2048 + k * 1024); } while (0)
; #define PG8_LDB(dst, b, h) do { _Pragma("unroll") for (int n = 0; n < 2; ++n) _Pragma("unroll") for (int k = 0; k < 2; ++k) dst[n][k] = *(const LAS bf16x8*)(lds + PG8_SB(b, h) + boff + n * 2048 + k * 1024); } while (0)
; #define PG8_MMA(ai, bj, At, Bt) do { __builtin_amdgcn_s_setprio(1); _Pragma("unroll") for (int m = 0; m < 4; ++m) _Pragma("unroll") for (int n = 0; n < 2; ++n) _Pragma("unroll") for (int k = 0; k < 2; ++k) \
;         acc[ai][bj][m][n] = __builtin_amdgcn_mfma_f32_16x16x32_bf16(Bt[n][k], At[m][k], acc[ai][bj][m][n], 0, 0, 0); __builtin_amdgcn_s_setprio(0); } while (0)
; #define PG8_WAIT_V(n) asm volatile("s_waitcnt vmcnt(" #n ")" ::: "memory")
; #define PG8_WAIT_L(n) asm volatile("s_waitcnt lgkmcnt(" #n ")" ::: "memory")
; #define PG8_BAR __builtin_amdgcn_s_barrier()
; #define PG8_SCHED __builtin_amdgcn_sched_barrier(0)
; template <class Epi, bool ALIGN_EPI>
; DI void gemm_phase(LAS unsigned char* lds, const Sched& S, const Epi& E, int tid) {
;     ...
;         for (int t = 0; t < nt; t += 2) {
;             const bool last = (t == nt - 2);
;             const char* a1 = cA + (size_t)(t + 1) * kstep;
;             const char* a2 = last ? nA : cA + (size_t)(t + 2) * kstep; const char* b2 = last ? nB : cB + (size_t)(t + 2) * kstep;
;             const char* a3 = a2 + kstep; const char* b3 = b2 + kstep;
;             PG8_LDB(B0, 0, 0); PG8_LDB(B1, 0, 1); PG8_SCHED; PG8_LDA(At, 0, 0); PG8_STAGE(PG8_SA(1, 1), a1 + hstepA, voffA);
;             PG8_WAIT_V(8); PG8_WAIT_L(0); PG8_BAR; PG8_MMA(0, 0, At, B0); PG8_MMA(0, 1, At, B1); PG8_BAR; PG8_SCHED;
;             PG8_LDA(At, 0, 1); PG8_STAGE(PG8_SB(0, 0), b2, voffB); PG8_STAGE(PG8_SB(0, 1), b2 + hstepB, voffB); PG8_STAGE(PG8_SA(0, 0), a2, voffA);
;             PG8_WAIT_V(8); PG8_WAIT_L(0); PG8_BAR; PG8_MMA(1, 0, At, B0); PG8_MMA(1, 1, At, B1); PG8_BAR; PG8_SCHED;
.LBB0_1765:
	s_add_i32 s61, s26, 2
	s_add_u32 s27, s24, 0xfffc0080
	s_addc_u32 s28, s25, -1
	s_add_i32 s62, 0, 0x10000
	s_cmp_eq_u32 s58, s26
	s_cselect_b32 s29, s54, s28
	s_cselect_b32 s28, s55, s27
	s_cselect_b32 s27, s56, s60
	s_cselect_b32 s26, s57, s59
	s_add_i32 s64, 0, 0x14000
	v_add_u32_e32 v144, s62, v161
	v_add_u32_e32 v174, s64, v161
	ds_read_b128 v[132:135], v144
	ds_read_b128 v[136:139], v144 offset:1024
	ds_read_b128 v[140:143], v144 offset:2048
	ds_read_b128 v[144:147], v144 offset:3072
	ds_read_b128 v[148:151], v174
	ds_read_b128 v[152:155], v174 offset:1024
	ds_read_b128 v[156:159], v174 offset:2048
	ds_read_b128 v[174:177], v174 offset:3072
	v_lshl_add_u64 v[190:191], s[24:25], 0, v[170:171]
	s_mov_b32 m0, s46
	s_nop 0
	global_load_lds_dwordx4 v[230:231], off
	s_mov_b32 m0, s47
	s_nop 0
	global_load_lds_dwordx4 v[232:233], off
	s_add_i32 m0, s41, 0xc000
	ds_read_b128 v[178:181], v193
	ds_read_b128 v[182:185], v193 offset:1024
	ds_read_b128 v[186:189], v193 offset:2048
	ds_read_b128 v[202:205], v193 offset:3072
	ds_read_b128 v[206:209], v193 offset:4096
	ds_read_b128 v[210:213], v193 offset:5120
	ds_read_b128 v[214:217], v193 offset:6144
	ds_read_b128 v[218:221], v193 offset:7168
	global_load_lds_dwordx4 v[190:191], off
	v_lshl_add_u64 v[190:191], s[24:25], 0, v[172:173]
	s_add_i32 m0, s41, 0xe000
	s_nop 0
	global_load_lds_dwordx4 v[190:191], off
	s_waitcnt vmcnt(8)
	s_waitcnt lgkmcnt(0)
	s_barrier
	s_setprio 1
	s_waitcnt lgkmcnt(0)
	v_mfma_f32_16x16x32_bf16 v[128:131], v[132:135], v[178:181], v[128:131]
	v_mfma_f32_16x16x32_bf16 v[124:127], v[140:143], v[178:181], v[124:127]
	v_mfma_f32_16x16x32_bf16 v[112:115], v[132:135], v[186:189], v[112:115]
	v_mfma_f32_16x16x32_bf16 v[108:111], v[140:143], v[186:189], v[108:111]
	v_mfma_f32_16x16x32_bf16 v[96:99], v[132:135], v[206:209], v[96:99]
	v_mfma_f32_16x16x32_bf16 v[92:95], v[140:143], v[206:209], v[92:95]
	v_mfma_f32_16x16x32_bf16 v[80:83], v[132:135], v[214:217], v[80:83]
	v_mfma_f32_16x16x32_bf16 v[76:79], v[140:143], v[214:217], v[76:79]
	v_mfma_f32_16x16x32_bf16 v[128:131], v[136:139], v[182:185], v[128:131]
	v_mfma_f32_16x16x32_bf16 v[124:127], v[144:147], v[182:185], v[124:127]
	v_mfma_f32_16x16x32_bf16 v[112:115], v[136:139], v[202:205], v[112:115]
	v_mfma_f32_16x16x32_bf16 v[108:111], v[144:147], v[202:205], v[108:111]
	v_mfma_f32_16x16x32_bf16 v[96:99], v[136:139], v[210:213], v[96:99]
	v_mfma_f32_16x16x32_bf16 v[92:95], v[144:147], v[210:213], v[92:95]
	v_mfma_f32_16x16x32_bf16 v[80:83], v[136:139], v[218:221], v[80:83]
	v_mfma_f32_16x16x32_bf16 v[76:79], v[144:147], v[218:221], v[76:79]
	s_setprio 0
	s_setprio 1
	v_mfma_f32_16x16x32_bf16 v[120:123], v[148:151], v[178:181], v[120:123]
	v_mfma_f32_16x16x32_bf16 v[116:119], v[156:159], v[178:181], v[116:119]
	v_mfma_f32_16x16x32_bf16 v[104:107], v[148:151], v[186:189], v[104:107]
	v_mfma_f32_16x16x32_bf16 v[100:103], v[156:159], v[186:189], v[100:103]
	v_mfma_f32_16x16x32_bf16 v[88:91], v[148:151], v[206:209], v[88:91]
	v_mfma_f32_16x16x32_bf16 v[84:87], v[156:159], v[206:209], v[84:87]
	v_mfma_f32_16x16x32_bf16 v[72:75], v[148:151], v[214:217], v[72:75]
	v_mfma_f32_16x16x32_bf16 v[68:71], v[156:159], v[214:217], v[68:71]
	v_mfma_f32_16x16x32_bf16 v[120:123], v[152:155], v[182:185], v[120:123]
	v_mfma_f32_16x16x32_bf16 v[116:119], v[174:177], v[182:185], v[116:119]
	v_mfma_f32_16x16x32_bf16 v[104:107], v[152:155], v[202:205], v[104:107]
	v_mfma_f32_16x16x32_bf16 v[100:103], v[174:177], v[202:205], v[100:103]
	v_mfma_f32_16x16x32_bf16 v[88:91], v[152:155], v[210:213], v[88:91]
	v_mfma_f32_16x16x32_bf16 v[84:87], v[174:177], v[210:213], v[84:87]
	v_mfma_f32_16x16x32_bf16 v[72:75], v[152:155], v[218:221], v[72:75]
	v_mfma_f32_16x16x32_bf16 v[68:71], v[174:177], v[218:221], v[68:71]
	s_setprio 0
	s_barrier
	s_add_i32 s62, s62, s40
	v_lshl_add_u64 v[190:191], s[26:27], 0, v[164:165]
	s_mov_b32 m0, s62
	ds_read_b128 v[178:181], v193 offset:16384
	ds_read_b128 v[182:185], v193 offset:17408
	ds_read_b128 v[186:189], v193 offset:18432
	ds_read_b128 v[202:205], v193 offset:19456
	ds_read_b128 v[206:209], v193 offset:20480
	ds_read_b128 v[210:213], v193 offset:21504
	ds_read_b128 v[214:217], v193 offset:22528
	ds_read_b128 v[218:221], v193 offset:23552
	global_load_lds_dwordx4 v[190:191], off
	s_add_i32 m0, s62, 0x2000
	s_add_u32 s62, s26, 0x40000
	v_lshl_add_u64 v[194:195], s[26:27], 0, v[168:169]
	s_addc_u32 s63, s27, 0
	s_add_i32 s64, s64, s40
	global_load_lds_dwordx4 v[194:195], off
	v_lshl_add_u64 v[222:223], s[62:63], 0, v[164:165]
	s_mov_b32 m0, s64
	v_lshl_add_u64 v[224:225], s[28:29], 0, v[166:167]
	global_load_lds_dwordx4 v[222:223], off
	v_lshl_add_u64 v[222:223], s[62:63], 0, v[168:169]
	s_add_i32 m0, s64, 0x2000
	s_nop 0
	global_load_lds_dwordx4 v[222:223], off
	v_lshl_add_u64 v[222:223], s[28:29], 0, v[162:163]
	s_waitcnt vmcnt(6)
	s_waitcnt lgkmcnt(0)
	s_barrier
; #define PG8_STAGE(bufoff, gbase, voff) do { _Pragma("unroll") for (int _i = 0; _i < 2; ++_i) \
;         __builtin_amdgcn_global_load_lds((const unsigned*)((const char*)(gbase) + (voff)[_i]), (LAS unsigned*)(lds + (bufoff) + ldsw + _i * 8192), 16, 0, 0); } while (0)
; #define PG8_LDA(dst, b, h) do { _Pragma("unroll") for (int m = 0; m < 4; ++m) _Pragma("unroll") for (int k = 0; k < 2; ++k) dst[m][k] = *(const LAS bf16x8*)(lds + PG8_SA(b, h) + aoff + m * 2048 + k * 1024); } while (0)
; #define PG8_LDB(dst, b, h) do { _Pragma("unroll") for (int n = 0; n < 2; ++n) _Pragma("unroll") for (int k = 0; k < 2; ++k) dst[n][k] = *(const LAS bf16x8*)(lds + PG8_SB(b, h) + boff + n * 2048 + k * 1024); } while (0)
; #define PG8_MMA(ai, bj, At, Bt) do { __builtin_amdgcn_s_setprio(1); _Pragma("unroll") for (int m = 0; m < 4; ++m) _Pragma("unroll") for (int n = 0; n < 2; ++n) _Pragma("unroll") for (int k = 0; k < 2; ++k) \
;         acc[ai][bj][m][n] = __builtin_amdgcn_mfma_f32_16x16x32_bf16(Bt[n][k], At[m][k], acc[ai][bj][m][n], 0, 0, 0); __builtin_amdgcn_s_setprio(0); } while (0)
; #define PG8_WAIT_V(n) asm volatile("s_waitcnt vmcnt(" #n ")" ::: "memory")
; #define PG8_WAIT_L(n) asm volatile("s_waitcnt lgkmcnt(" #n ")" ::: "memory")
; #define PG8_BAR __builtin_amdgcn_s_barrier()
; #define PG8_SCHED __builtin_amdgcn_sched_barrier(0)
; template <class Epi, bool ALIGN_EPI>
; DI void gemm_phase(LAS unsigned char* lds, const Sched& S, const Epi& E, int tid) {
;     ...
;             PG8_WAIT_V(8); PG8_WAIT_L(0); PG8_BAR; PG8_MMA(0, 0, At, B0); PG8_MMA(0, 1, At, B1); PG8_BAR; PG8_SCHED;
;             PG8_LDA(At, 0, 1); PG8_STAGE(PG8_SB(0, 0), b2, voffB); PG8_STAGE(PG8_SB(0, 1), b2 + hstepB, voffB); PG8_STAGE(PG8_SA(0, 0), a2, voffA);
;             PG8_WAIT_V(8); PG8_WAIT_L(0); PG8_BAR; PG8_MMA(1, 0, At, B0); PG8_MMA(1, 1, At, B1); PG8_BAR; PG8_SCHED;
;             PG8_LDB(B0, 1, 0); PG8_LDB(B1, 1, 1); PG8_SCHED; PG8_LDA(At, 1, 0); PG8_STAGE(PG8_SA(0, 1), a2 + hstepA, voffA);
;             PG8_WAIT_V(8); PG8_WAIT_L(0); PG8_BAR; PG8_MMA(0, 0, At, B0); PG8_MMA(0, 1, At, B1); PG8_BAR; PG8_SCHED;
;             PG8_LDA(At, 1, 1); PG8_STAGE(PG8_SB(1, 0), b3, voffB); PG8_STAGE(PG8_SB(1, 1), b3 + hstepB, voffB); PG8_STAGE(PG8_SA(1, 0), a3, voffA);
	s_setprio 1
	s_waitcnt lgkmcnt(0)
	v_mfma_f32_16x16x32_bf16 v[64:67], v[132:135], v[178:181], v[64:67]
	v_mfma_f32_16x16x32_bf16 v[60:63], v[140:143], v[178:181], v[60:63]
	v_mfma_f32_16x16x32_bf16 v[48:51], v[132:135], v[186:189], v[48:51]
	v_mfma_f32_16x16x32_bf16 v[44:47], v[140:143], v[186:189], v[44:47]
	v_mfma_f32_16x16x32_bf16 v[32:35], v[132:135], v[206:209], v[32:35]
	v_mfma_f32_16x16x32_bf16 v[28:31], v[140:143], v[206:209], v[28:31]
	v_mfma_f32_16x16x32_bf16 v[16:19], v[132:135], v[214:217], v[16:19]
	v_mfma_f32_16x16x32_bf16 v[12:15], v[140:143], v[214:217], v[12:15]
	v_mfma_f32_16x16x32_bf16 v[64:67], v[136:139], v[182:185], v[64:67]
	v_mfma_f32_16x16x32_bf16 v[60:63], v[144:147], v[182:185], v[60:63]
	v_mfma_f32_16x16x32_bf16 v[48:51], v[136:139], v[202:205], v[48:51]
	v_mfma_f32_16x16x32_bf16 v[44:47], v[144:147], v[202:205], v[44:47]
	v_mfma_f32_16x16x32_bf16 v[32:35], v[136:139], v[210:213], v[32:35]
	v_mfma_f32_16x16x32_bf16 v[28:31], v[144:147], v[210:213], v[28:31]
	v_mfma_f32_16x16x32_bf16 v[16:19], v[136:139], v[218:221], v[16:19]
	v_mfma_f32_16x16x32_bf16 v[12:15], v[144:147], v[218:221], v[12:15]
	s_setprio 0
	s_setprio 1
	v_mfma_f32_16x16x32_bf16 v[56:59], v[148:151], v[178:181], v[56:59]
	v_mfma_f32_16x16x32_bf16 v[52:55], v[156:159], v[178:181], v[52:55]
	v_mfma_f32_16x16x32_bf16 v[40:43], v[148:151], v[186:189], v[40:43]
	v_mfma_f32_16x16x32_bf16 v[36:39], v[156:159], v[186:189], v[36:39]
	v_mfma_f32_16x16x32_bf16 v[24:27], v[148:151], v[206:209], v[24:27]
	v_mfma_f32_16x16x32_bf16 v[20:23], v[156:159], v[206:209], v[20:23]
	v_mfma_f32_16x16x32_bf16 v[8:11], v[148:151], v[214:217], v[8:11]
	v_mfma_f32_16x16x32_bf16 v[4:7], v[156:159], v[214:217], v[4:7]
	v_mfma_f32_16x16x32_bf16 v[56:59], v[152:155], v[182:185], v[56:59]
	v_mfma_f32_16x16x32_bf16 v[52:55], v[174:177], v[182:185], v[52:55]
	v_mfma_f32_16x16x32_bf16 v[40:43], v[152:155], v[202:205], v[40:43]
	v_mfma_f32_16x16x32_bf16 v[36:39], v[174:177], v[202:205], v[36:39]
	v_mfma_f32_16x16x32_bf16 v[24:27], v[152:155], v[210:213], v[24:27]
	v_mfma_f32_16x16x32_bf16 v[20:23], v[174:177], v[210:213], v[20:23]
	v_mfma_f32_16x16x32_bf16 v[8:11], v[152:155], v[218:221], v[8:11]
	v_mfma_f32_16x16x32_bf16 v[4:7], v[174:177], v[218:221], v[4:7]
	s_setprio 0
	s_barrier
	s_add_i32 s62, 0, 0x18000
	s_add_i32 s63, 0, 0x1c000
	v_add_u32_e32 v144, s62, v161
	v_add_u32_e32 v174, s63, v161
	ds_read_b128 v[132:135], v144
	ds_read_b128 v[136:139], v144 offset:1024
	ds_read_b128 v[140:143], v144 offset:2048
	ds_read_b128 v[144:147], v144 offset:3072
	ds_read_b128 v[148:151], v174
	ds_read_b128 v[152:155], v174 offset:1024
	ds_read_b128 v[156:159], v174 offset:2048
	ds_read_b128 v[174:177], v174 offset:3072
	s_add_u32 s28, s28, 0x40000
	s_addc_u32 s29, s29, 0
	s_mov_b32 m0, s41
	s_nop 0
	global_load_lds_dwordx4 v[222:223], off
	s_mov_b32 m0, s42
	s_nop 0
	global_load_lds_dwordx4 v[224:225], off
	s_mov_b32 m0, s43
	v_lshl_add_u64 v[226:227], s[28:29], 0, v[162:163]
	ds_read_b128 v[178:181], v193 offset:32768
	ds_read_b128 v[182:185], v193 offset:33792
	ds_read_b128 v[186:189], v193 offset:34816
	ds_read_b128 v[202:205], v193 offset:35840
	ds_read_b128 v[206:209], v193 offset:36864
	ds_read_b128 v[210:213], v193 offset:37888
	ds_read_b128 v[214:217], v193 offset:38912
	ds_read_b128 v[218:221], v193 offset:39936
	global_load_lds_dwordx4 v[226:227], off
	v_lshl_add_u64 v[226:227], s[28:29], 0, v[166:167]
	s_mov_b32 m0, s44
	s_nop 0
	global_load_lds_dwordx4 v[226:227], off
	s_waitcnt vmcnt(8)
	s_waitcnt lgkmcnt(0)
	s_barrier
	s_setprio 1
	s_waitcnt lgkmcnt(0)
	v_mfma_f32_16x16x32_bf16 v[128:131], v[132:135], v[178:181], v[128:131]
	v_mfma_f32_16x16x32_bf16 v[124:127], v[140:143], v[178:181], v[124:127]
	v_mfma_f32_16x16x32_bf16 v[112:115], v[132:135], v[186:189], v[112:115]
	v_mfma_f32_16x16x32_bf16 v[108:111], v[140:143], v[186:189], v[108:111]
	v_mfma_f32_16x16x32_bf16 v[96:99], v[132:135], v[206:209], v[96:99]
	v_mfma_f32_16x16x32_bf16 v[92:95], v[140:143], v[206:209], v[92:95]
	v_mfma_f32_16x16x32_bf16 v[80:83], v[132:135], v[214:217], v[80:83]
	v_mfma_f32_16x16x32_bf16 v[76:79], v[140:143], v[214:217], v[76:79]
	v_mfma_f32_16x16x32_bf16 v[128:131], v[136:139], v[182:185], v[128:131]
	v_mfma_f32_16x16x32_bf16 v[124:127], v[144:147], v[182:185], v[124:127]
	v_mfma_f32_16x16x32_bf16 v[112:115], v[136:139], v[202:205], v[112:115]
	v_mfma_f32_16x16x32_bf16 v[108:111], v[144:147], v[202:205], v[108:111]
	v_mfma_f32_16x16x32_bf16 v[96:99], v[136:139], v[210:213], v[96:99]
	v_mfma_f32_16x16x32_bf16 v[92:95], v[144:147], v[210:213], v[92:95]
	v_mfma_f32_16x16x32_bf16 v[80:83], v[136:139], v[218:221], v[80:83]
	v_mfma_f32_16x16x32_bf16 v[76:79], v[144:147], v[218:221], v[76:79]
	s_setprio 0
	s_setprio 1
	v_mfma_f32_16x16x32_bf16 v[120:123], v[148:151], v[178:181], v[120:123]
	v_mfma_f32_16x16x32_bf16 v[116:119], v[156:159], v[178:181], v[116:119]
	v_mfma_f32_16x16x32_bf16 v[104:107], v[148:151], v[186:189], v[104:107]
	v_mfma_f32_16x16x32_bf16 v[100:103], v[156:159], v[186:189], v[100:103]
	v_mfma_f32_16x16x32_bf16 v[88:91], v[148:151], v[206:209], v[88:91]
	v_mfma_f32_16x16x32_bf16 v[84:87], v[156:159], v[206:209], v[84:87]
	v_mfma_f32_16x16x32_bf16 v[72:75], v[148:151], v[214:217], v[72:75]
	v_mfma_f32_16x16x32_bf16 v[68:71], v[156:159], v[214:217], v[68:71]
	v_mfma_f32_16x16x32_bf16 v[120:123], v[152:155], v[182:185], v[120:123]
	v_mfma_f32_16x16x32_bf16 v[116:119], v[174:177], v[182:185], v[116:119]
	v_mfma_f32_16x16x32_bf16 v[104:107], v[152:155], v[202:205], v[104:107]
	v_mfma_f32_16x16x32_bf16 v[100:103], v[174:177], v[202:205], v[100:103]
	v_mfma_f32_16x16x32_bf16 v[88:91], v[152:155], v[210:213], v[88:91]
	v_mfma_f32_16x16x32_bf16 v[84:87], v[174:177], v[210:213], v[84:87]
	v_mfma_f32_16x16x32_bf16 v[72:75], v[152:155], v[218:221], v[72:75]
	v_mfma_f32_16x16x32_bf16 v[68:71], v[174:177], v[218:221], v[68:71]
	s_setprio 0
	s_barrier
; #define PG8_STAGE(bufoff, gbase, voff) do { _Pragma("unroll") for (int _i = 0; _i < 2; ++_i) \
;         __builtin_amdgcn_global_load_lds((const unsigned*)((const char*)(gbase) + (voff)[_i]), (LAS unsigned*)(lds + (bufoff) + ldsw + _i * 8192), 16, 0, 0); } while (0)
; #define PG8_LDA(dst, b, h) do { _Pragma("unroll") for (int m = 0; m < 4; ++m) _Pragma("unroll") for (int k = 0; k < 2; ++k) dst[m][k] = *(const LAS bf16x8*)(lds + PG8_SA(b, h) + aoff + m * 2048 + k * 1024); } while (0)
; #define PG8_MMA(ai, bj, At, Bt) do { __builtin_amdgcn_s_setprio(1); _Pragma("unroll") for (int m = 0; m < 4; ++m) _Pragma("unroll") for (int n = 0; n < 2; ++n) _Pragma("unroll") for (int k = 0; k < 2; ++k) \
;         acc[ai][bj][m][n] = __builtin_amdgcn_mfma_f32_16x16x32_bf16(Bt[n][k], At[m][k], acc[ai][bj][m][n], 0, 0, 0); __builtin_amdgcn_s_setprio(0); } while (0)
; #define PG8_WAIT_V(n) asm volatile("s_waitcnt vmcnt(" #n ")" ::: "memory")
; #define PG8_WAIT_L(n) asm volatile("s_waitcnt lgkmcnt(" #n ")" ::: "memory")
; #define PG8_BAR __builtin_amdgcn_s_barrier()
; #define PG8_SCHED __builtin_amdgcn_sched_barrier(0)
; template <class Epi, bool ALIGN_EPI>
; DI void gemm_phase(LAS unsigned char* lds, const Sched& S, const Epi& E, int tid) {
;     ...
;             PG8_LDA(At, 1, 1); PG8_STAGE(PG8_SB(1, 0), b3, voffB); PG8_STAGE(PG8_SB(1, 1), b3 + hstepB, voffB); PG8_STAGE(PG8_SA(1, 0), a3, voffA);
;             PG8_WAIT_V(8); PG8_WAIT_L(0); PG8_BAR; PG8_MMA(1, 0, At, B0); PG8_MMA(1, 1, At, B1); PG8_BAR; PG8_SCHED;
;         }
	s_add_i32 s28, s62, s40
	v_lshl_add_u64 v[190:191], v[190:191], 0, s[84:85]
	s_mov_b32 m0, s28
	ds_read_b128 v[178:181], v193 offset:49152
	ds_read_b128 v[182:185], v193 offset:50176
	ds_read_b128 v[186:189], v193 offset:51200
	ds_read_b128 v[202:205], v193 offset:52224
	ds_read_b128 v[206:209], v193 offset:53248
	ds_read_b128 v[210:213], v193 offset:54272
	ds_read_b128 v[214:217], v193 offset:55296
	ds_read_b128 v[218:221], v193 offset:56320
	global_load_lds_dwordx4 v[190:191], off
	s_add_i32 m0, s28, 0x2000
	s_add_u32 s26, s26, 0x40080
	v_lshl_add_u64 v[190:191], v[194:195], 0, s[84:85]
	s_addc_u32 s27, s27, 0
	s_add_i32 s28, s63, s40
	global_load_lds_dwordx4 v[190:191], off
	v_lshl_add_u64 v[190:191], s[26:27], 0, v[164:165]
	s_mov_b32 m0, s28
	s_nop 0
	global_load_lds_dwordx4 v[190:191], off
	v_lshl_add_u64 v[190:191], s[26:27], 0, v[168:169]
	s_add_i32 m0, s28, 0x2000
	s_nop 0
	global_load_lds_dwordx4 v[190:191], off
	v_lshl_add_u64 v[230:231], v[222:223], 0, s[84:85]
	v_lshl_add_u64 v[232:233], v[224:225], 0, s[84:85]
	s_waitcnt vmcnt(6)
	s_waitcnt lgkmcnt(0)
	s_barrier
	s_setprio 1
	s_waitcnt lgkmcnt(0)
	v_mfma_f32_16x16x32_bf16 v[64:67], v[132:135], v[178:181], v[64:67]
	v_mfma_f32_16x16x32_bf16 v[60:63], v[140:143], v[178:181], v[60:63]
	v_mfma_f32_16x16x32_bf16 v[48:51], v[132:135], v[186:189], v[48:51]
	v_mfma_f32_16x16x32_bf16 v[44:47], v[140:143], v[186:189], v[44:47]
	v_mfma_f32_16x16x32_bf16 v[32:35], v[132:135], v[206:209], v[32:35]
	v_mfma_f32_16x16x32_bf16 v[28:31], v[140:143], v[206:209], v[28:31]
	v_mfma_f32_16x16x32_bf16 v[16:19], v[132:135], v[214:217], v[16:19]
	v_mfma_f32_16x16x32_bf16 v[12:15], v[140:143], v[214:217], v[12:15]
	v_mfma_f32_16x16x32_bf16 v[64:67], v[136:139], v[182:185], v[64:67]
	v_mfma_f32_16x16x32_bf16 v[60:63], v[144:147], v[182:185], v[60:63]
	v_mfma_f32_16x16x32_bf16 v[48:51], v[136:139], v[202:205], v[48:51]
	v_mfma_f32_16x16x32_bf16 v[44:47], v[144:147], v[202:205], v[44:47]
	v_mfma_f32_16x16x32_bf16 v[32:35], v[136:139], v[210:213], v[32:35]
	v_mfma_f32_16x16x32_bf16 v[28:31], v[144:147], v[210:213], v[28:31]
	v_mfma_f32_16x16x32_bf16 v[16:19], v[136:139], v[218:221], v[16:19]
	v_mfma_f32_16x16x32_bf16 v[12:15], v[144:147], v[218:221], v[12:15]
	s_setprio 0
	s_setprio 1
	v_mfma_f32_16x16x32_bf16 v[56:59], v[148:151], v[178:181], v[56:59]
	v_mfma_f32_16x16x32_bf16 v[52:55], v[156:159], v[178:181], v[52:55]
	v_mfma_f32_16x16x32_bf16 v[40:43], v[148:151], v[186:189], v[40:43]
	v_mfma_f32_16x16x32_bf16 v[36:39], v[156:159], v[186:189], v[36:39]
	v_mfma_f32_16x16x32_bf16 v[24:27], v[148:151], v[206:209], v[24:27]
	v_mfma_f32_16x16x32_bf16 v[20:23], v[156:159], v[206:209], v[20:23]
	v_mfma_f32_16x16x32_bf16 v[8:11], v[148:151], v[214:217], v[8:11]
	v_mfma_f32_16x16x32_bf16 v[4:7], v[156:159], v[214:217], v[4:7]
	v_mfma_f32_16x16x32_bf16 v[56:59], v[152:155], v[182:185], v[56:59]
	v_mfma_f32_16x16x32_bf16 v[52:55], v[174:177], v[182:185], v[52:55]
	v_mfma_f32_16x16x32_bf16 v[40:43], v[152:155], v[202:205], v[40:43]
	v_mfma_f32_16x16x32_bf16 v[36:39], v[174:177], v[202:205], v[36:39]
	v_mfma_f32_16x16x32_bf16 v[24:27], v[152:155], v[210:213], v[24:27]
	v_mfma_f32_16x16x32_bf16 v[20:23], v[174:177], v[210:213], v[20:23]
	v_mfma_f32_16x16x32_bf16 v[8:11], v[152:155], v[218:221], v[8:11]
	v_mfma_f32_16x16x32_bf16 v[4:7], v[174:177], v[218:221], v[4:7]
	s_setprio 0
	s_barrier
	s_add_u32 s24, s24, 0x100
	s_addc_u32 s25, s25, 0
	s_add_u32 s59, s59, 0x100
	s_addc_u32 s60, s60, 0
	s_cmp_ge_i32 s61, s23
	s_mov_b32 s26, s61
	s_cbranch_scc0 .LBB0_1765
	s_and_b64 vcc, exec, s[6:7]
	s_cbranch_vccz .LBB0_1768
	s_barrier

; #define PG8_STAGE(bufoff, gbase, voff) do { _Pragma("unroll") for (int _i = 0; _i < 2; ++_i) \
;         __builtin_amdgcn_global_load_lds((const unsigned*)((const char*)(gbase) + (voff)[_i]), (LAS unsigned*)(lds + (bufoff) + ldsw + _i * 8192), 16, 0, 0); } while (0)
; #define PG8_WAIT_V(n) asm volatile("s_waitcnt vmcnt(" #n ")" ::: "memory")
; #define PG8_BAR __builtin_amdgcn_s_barrier()
; template <class Epi, bool ALIGN_EPI>
; DI void gemm_phase(LAS unsigned char* lds, const Sched& S, const Epi& E, int tid) {
;     const int wid = __builtin_amdgcn_readfirstlane(tid >> 6), lane = tid & 63, wr = wid >> 2, wc = wid & 3, fr = lane & 15, fq = lane >> 4;
;     const int lda = S.lda, ldb = S.ldb;
;     unsigned voffA[2], voffB[2];
; #pragma unroll
;     for (int i = 0; i < 2; ++i) { int R, C; stage_rc(tid * 16 + i * 8192, R, C); const int Rb = (R & ~31) + perm32(R & 31);
;         voffA[i] = (unsigned)(R * lda + C) * 2u; voffB[i] = (unsigned)(Rb * ldb + C) * 2u; }
;     const size_t kstep = (size_t)(BK * 2);
;     const size_t hstepA = (size_t)HALF * lda * 2, hstepB = (size_t)HALF * ldb * 2;
;     const unsigned ldsw = (unsigned)wid * 1024u;
;     const int aoff = lds_byte(wr * 64 + fr, fq * 8), boff = lds_byte(wc * 32 + fr, fq * 8);
;     ...
;     PG8_STAGE(PG8_SB(0, 0), cB, voffB); PG8_STAGE(PG8_SB(0, 1), cB + hstepB, voffB); PG8_STAGE(PG8_SA(0, 0), cA, voffA); PG8_STAGE(PG8_SA(0, 1), cA + hstepA, voffA);
;     if (wr == 1) PG8_BAR;
;     PG8_WAIT_V(2); PG8_BAR;
;     PG8_STAGE(PG8_SB(1, 0), cB + kstep, voffB); PG8_STAGE(PG8_SA(1, 0), cA + kstep, voffA); PG8_STAGE(PG8_SB(1, 1), cB + hstepB + kstep, voffB);
;     PG8_WAIT_V(6); PG8_BAR;
.LBB0_1955:
	v_lshrrev_b32_e32 v19, 1, v0
	s_sext_i32_i8 s43, s4
	s_add_u32 s4, s96, 0x1d700000
	v_and_b32_e32 v19, 24, v19
	s_addc_u32 s5, s97, 0
	v_and_b32_e32 v18, 15, v0
	v_lshlrev_b32_e32 v20, 1, v19
	s_lshl_b32 s8, s8, 5
	v_lshl_or_b32 v3, s7, 6, v18
	v_lshl_or_b32 v20, v18, 6, v20
	v_lshlrev_b32_e32 v18, 2, v18
	s_and_b32 s10, s8, 0x60
	s_add_i32 m0, s17, 0x18000
	v_lshl_add_u64 v[10:11], v[10:11], 0, s[84:85]
	s_lshl_b32 s9, s7, 13
	v_and_b32_e32 v21, 32, v18
	s_lshl_b32 s8, s10, 7
	s_waitcnt vmcnt(2)
	s_barrier
	global_load_lds_dwordx4 v[10:11], off
	v_lshl_add_u64 v[8:9], v[8:9], 0, s[84:85]
	s_add_i32 m0, s17, 0x1a000
	s_add_i32 s39, s17, 0x8000
	s_add_i32 s40, s17, 0xa000
	v_bitop3_b32 v144, s8, v20, v21 bitop3:0xf6
	global_load_lds_dwordx4 v[8:9], off
	v_lshl_add_u64 v[4:5], v[4:5], 0, s[84:85]
	s_mov_b32 m0, s39
	s_add_u32 s8, s24, 0x40080
	v_bitop3_b32 v22, v20, s9, v21 bitop3:0xde
	v_mov_b64_e32 v[230:231], v[4:5]
	global_load_lds_dwordx4 v[4:5], off
	v_lshl_add_u64 v[4:5], v[6:7], 0, s[84:85]
	s_mov_b32 m0, s40
	s_addc_u32 s9, s25, 0
	v_mov_b64_e32 v[232:233], v[4:5]
	global_load_lds_dwordx4 v[4:5], off
	s_add_i32 m0, s17, 0x1c000
	v_lshl_add_u64 v[4:5], s[8:9], 0, v[136:137]
	global_load_lds_dwordx4 v[4:5], off
	v_lshl_add_u64 v[4:5], s[8:9], 0, v[132:133]
	s_add_i32 m0, s17, 0x1e000
	s_lshl_b32 s7, s7, 8
	global_load_lds_dwordx4 v[4:5], off
	v_lshlrev_b32_e32 v4, 14, v16
	v_and_b32_e32 v4, 0xffff8000, v4
	v_lshl_add_u32 v4, v15, 11, v4
	v_and_b32_e32 v5, 1, v16
	v_lshl_or_b32 v4, v5, 6, v4
	v_lshl_add_u32 v140, v17, 1, v4
	v_lshlrev_b32_e32 v4, 14, v12
	s_add_i32 s7, s7, 0
	v_and_b32_e32 v4, 0xffff8000, v4
	s_waitcnt vmcnt(6)
	s_add_i32 s7, s7, 0x20000
	v_lshl_add_u32 v4, v13, 11, v4
	v_and_b32_e32 v5, 1, v12
	s_cmpk_lt_u32 s6, 0x100
	v_lshl_or_b32 v4, v5, 6, v4
	v_add_u32_e32 v145, s7, v18
	s_cselect_b64 s[6:7], -1, 0
	v_or_b32_e32 v146, s10, v19
	v_mov_b32_e32 v141, v2
	v_lshl_add_u32 v142, v14, 1, v4
	v_mov_b32_e32 v143, v2
	s_mov_b32 s44, 0
	v_add_u32_e32 v147, 0, v22
	s_mov_b32 s41, 0
	s_barrier
	s_branch .LBB0_1958

; #define PG8_STAGE(bufoff, gbase, voff) do { _Pragma("unroll") for (int _i = 0; _i < 2; ++_i) \
;         __builtin_amdgcn_global_load_lds((const unsigned*)((const char*)(gbase) + (voff)[_i]), (LAS unsigned*)(lds + (bufoff) + ldsw + _i * 8192), 16, 0, 0); } while (0)
; #define PG8_LDA(dst, b, h) do { _Pragma("unroll") for (int m = 0; m < 4; ++m) _Pragma("unroll") for (int k = 0; k < 2; ++k) dst[m][k] = *(const LAS bf16x8*)(lds + PG8_SA(b, h) + aoff + m * 2048 + k * 1024); } while (0)
; #define PG8_LDB(dst, b, h) do { _Pragma("unroll") for (int n = 0; n < 2; ++n) _Pragma("unroll") for (int k = 0; k < 2; ++k) dst[n][k] = *(const LAS bf16x8*)(lds + PG8_SB(b, h) + boff + n * 2048 + k * 1024); } while (0)
; #define PG8_MMA(ai, bj, At, Bt) do { __builtin_amdgcn_s_setprio(1); _Pragma("unroll") for (int m = 0; m < 4; ++m) _Pragma("unroll") for (int n = 0; n < 2; ++n) _Pragma("unroll") for (int k = 0; k < 2; ++k) \
;         acc[ai][bj][m][n] = __builtin_amdgcn_mfma_f32_16x16x32_bf16(Bt[n][k], At[m][k], acc[ai][bj][m][n], 0, 0, 0); __builtin_amdgcn_s_setprio(0); } while (0)
; #define PG8_WAIT_V(n) asm volatile("s_waitcnt vmcnt(" #n ")" ::: "memory")
; #define PG8_WAIT_L(n) asm volatile("s_waitcnt lgkmcnt(" #n ")" ::: "memory")
; #define PG8_BAR __builtin_amdgcn_s_barrier()
; #define PG8_SCHED __builtin_amdgcn_sched_barrier(0)
; template <class Epi, bool ALIGN_EPI>
; DI void gemm_phase(LAS unsigned char* lds, const Sched& S, const Epi& E, int tid) {
;     ...
;             PG8_LDB(B0, 0, 0); PG8_LDB(B1, 0, 1); PG8_SCHED; PG8_LDA(At, 0, 0); PG8_STAGE(PG8_SA(1, 1), a1 + hstepA, voffA);
;             PG8_WAIT_V(8); PG8_WAIT_L(0); PG8_BAR; PG8_MMA(0, 0, At, B0); PG8_MMA(0, 1, At, B1); PG8_BAR; PG8_SCHED;
;             PG8_LDA(At, 0, 1); PG8_STAGE(PG8_SB(0, 0), b2, voffB); PG8_STAGE(PG8_SB(0, 1), b2 + hstepB, voffB); PG8_STAGE(PG8_SA(0, 0), a2, voffA);
;             PG8_WAIT_V(8); PG8_WAIT_L(0); PG8_BAR; PG8_MMA(1, 0, At, B0); PG8_MMA(1, 1, At, B1); PG8_BAR; PG8_SCHED;
.LBB0_1961:
	s_add_u32 s24, s22, 0xfffc0080
	s_addc_u32 s25, s23, -1
	s_add_i32 s48, 0, 0x10000
	s_cmp_eq_u32 s47, 12
	s_cselect_b32 s27, s19, s25
	s_cselect_b32 s26, s18, s24
	v_add_u32_e32 v161, s48, v144
	s_cselect_b32 s25, s21, s46
	s_cselect_b32 s24, s20, s45
	s_add_i32 s50, 0, 0x14000
	ds_read_b128 v[148:151], v161
	ds_read_b128 v[152:155], v161 offset:1024
	ds_read_b128 v[156:159], v161 offset:2048
	ds_read_b128 v[162:165], v161 offset:3072
	v_add_u32_e32 v161, s50, v144
	ds_read_b128 v[166:169], v161
	ds_read_b128 v[170:173], v161 offset:1024
	ds_read_b128 v[174:177], v161 offset:2048
	ds_read_b128 v[178:181], v161 offset:3072
	v_lshl_add_u64 v[194:195], s[22:23], 0, v[140:141]
	s_mov_b32 m0, s39
	s_nop 0
	global_load_lds_dwordx4 v[230:231], off
	s_mov_b32 m0, s40
	s_nop 0
	global_load_lds_dwordx4 v[232:233], off
	s_add_i32 m0, s17, 0xc000
	ds_read_b128 v[182:185], v147
	ds_read_b128 v[186:189], v147 offset:1024
	ds_read_b128 v[190:193], v147 offset:2048
	ds_read_b128 v[202:205], v147 offset:3072
	ds_read_b128 v[206:209], v147 offset:4096
	ds_read_b128 v[210:213], v147 offset:5120
	ds_read_b128 v[214:217], v147 offset:6144
	ds_read_b128 v[218:221], v147 offset:7168
	global_load_lds_dwordx4 v[194:195], off
	v_lshl_add_u64 v[194:195], s[22:23], 0, v[142:143]
	s_add_i32 m0, s17, 0xe000
	s_nop 0
	global_load_lds_dwordx4 v[194:195], off
	s_waitcnt vmcnt(8)
	s_waitcnt lgkmcnt(0)
	s_barrier
	s_setprio 1
	s_waitcnt lgkmcnt(0)
	v_mfma_f32_16x16x32_bf16 v[128:131], v[148:151], v[182:185], v[128:131]
	v_mfma_f32_16x16x32_bf16 v[124:127], v[156:159], v[182:185], v[124:127]
	v_mfma_f32_16x16x32_bf16 v[120:123], v[148:151], v[190:193], v[120:123]
	v_mfma_f32_16x16x32_bf16 v[112:115], v[156:159], v[190:193], v[112:115]
	v_mfma_f32_16x16x32_bf16 v[100:103], v[148:151], v[206:209], v[100:103]
	v_mfma_f32_16x16x32_bf16 v[92:95], v[156:159], v[206:209], v[92:95]
	v_mfma_f32_16x16x32_bf16 v[88:91], v[148:151], v[214:217], v[88:91]
	v_mfma_f32_16x16x32_bf16 v[80:83], v[156:159], v[214:217], v[80:83]
	v_mfma_f32_16x16x32_bf16 v[128:131], v[152:155], v[186:189], v[128:131]
	v_mfma_f32_16x16x32_bf16 v[124:127], v[162:165], v[186:189], v[124:127]
	v_mfma_f32_16x16x32_bf16 v[120:123], v[152:155], v[202:205], v[120:123]
	v_mfma_f32_16x16x32_bf16 v[112:115], v[162:165], v[202:205], v[112:115]
	v_mfma_f32_16x16x32_bf16 v[100:103], v[152:155], v[210:213], v[100:103]
	v_mfma_f32_16x16x32_bf16 v[92:95], v[162:165], v[210:213], v[92:95]
	v_mfma_f32_16x16x32_bf16 v[88:91], v[152:155], v[218:221], v[88:91]
	v_mfma_f32_16x16x32_bf16 v[80:83], v[162:165], v[218:221], v[80:83]
	s_setprio 0
	s_setprio 1
	v_mfma_f32_16x16x32_bf16 v[116:119], v[166:169], v[182:185], v[116:119]
	v_mfma_f32_16x16x32_bf16 v[108:111], v[174:177], v[182:185], v[108:111]
	v_mfma_f32_16x16x32_bf16 v[104:107], v[166:169], v[190:193], v[104:107]
	v_mfma_f32_16x16x32_bf16 v[96:99], v[174:177], v[190:193], v[96:99]
	v_mfma_f32_16x16x32_bf16 v[84:87], v[166:169], v[206:209], v[84:87]
	v_mfma_f32_16x16x32_bf16 v[76:79], v[174:177], v[206:209], v[76:79]
	v_mfma_f32_16x16x32_bf16 v[72:75], v[166:169], v[214:217], v[72:75]
	v_mfma_f32_16x16x32_bf16 v[68:71], v[174:177], v[214:217], v[68:71]
	v_mfma_f32_16x16x32_bf16 v[116:119], v[170:173], v[186:189], v[116:119]
	v_mfma_f32_16x16x32_bf16 v[108:111], v[178:181], v[186:189], v[108:111]
	v_mfma_f32_16x16x32_bf16 v[104:107], v[170:173], v[202:205], v[104:107]
	v_mfma_f32_16x16x32_bf16 v[96:99], v[178:181], v[202:205], v[96:99]
	v_mfma_f32_16x16x32_bf16 v[84:87], v[170:173], v[210:213], v[84:87]
	v_mfma_f32_16x16x32_bf16 v[76:79], v[178:181], v[210:213], v[76:79]
	v_mfma_f32_16x16x32_bf16 v[72:75], v[170:173], v[218:221], v[72:75]
	v_mfma_f32_16x16x32_bf16 v[68:71], v[178:181], v[218:221], v[68:71]
	s_setprio 0
	s_barrier
	s_add_i32 s48, s48, s28
	v_lshl_add_u64 v[194:195], s[24:25], 0, v[136:137]
	s_mov_b32 m0, s48
	ds_read_b128 v[182:185], v147 offset:16384
	ds_read_b128 v[186:189], v147 offset:17408
	ds_read_b128 v[190:193], v147 offset:18432
	ds_read_b128 v[202:205], v147 offset:19456
	ds_read_b128 v[206:209], v147 offset:20480
	ds_read_b128 v[210:213], v147 offset:21504
	ds_read_b128 v[214:217], v147 offset:22528
	ds_read_b128 v[218:221], v147 offset:23552
	global_load_lds_dwordx4 v[194:195], off
	s_add_i32 m0, s48, 0x2000
	s_add_u32 s48, s24, 0x40000
	v_lshl_add_u64 v[222:223], s[24:25], 0, v[132:133]
	s_addc_u32 s49, s25, 0
	s_add_i32 s50, s50, s28
	global_load_lds_dwordx4 v[222:223], off
	v_lshl_add_u64 v[224:225], s[48:49], 0, v[136:137]
	s_mov_b32 m0, s50
	v_lshl_add_u64 v[226:227], s[26:27], 0, v[134:135]
	global_load_lds_dwordx4 v[224:225], off
	v_lshl_add_u64 v[224:225], s[48:49], 0, v[132:133]
	s_add_i32 m0, s50, 0x2000
	s_nop 0
	global_load_lds_dwordx4 v[224:225], off
	v_lshl_add_u64 v[224:225], s[26:27], 0, v[138:139]
	s_waitcnt vmcnt(6)
	s_waitcnt lgkmcnt(0)
	s_barrier
; #define PG8_STAGE(bufoff, gbase, voff) do { _Pragma("unroll") for (int _i = 0; _i < 2; ++_i) \
;         __builtin_amdgcn_global_load_lds((const unsigned*)((const char*)(gbase) + (voff)[_i]), (LAS unsigned*)(lds + (bufoff) + ldsw + _i * 8192), 16, 0, 0); } while (0)
; #define PG8_LDA(dst, b, h) do { _Pragma("unroll") for (int m = 0; m < 4; ++m) _Pragma("unroll") for (int k = 0; k < 2; ++k) dst[m][k] = *(const LAS bf16x8*)(lds + PG8_SA(b, h) + aoff + m * 2048 + k * 1024); } while (0)
; #define PG8_LDB(dst, b, h) do { _Pragma("unroll") for (int n = 0; n < 2; ++n) _Pragma("unroll") for (int k = 0; k < 2; ++k) dst[n][k] = *(const LAS bf16x8*)(lds + PG8_SB(b, h) + boff + n * 2048 + k * 1024); } while (0)
; #define PG8_MMA(ai, bj, At, Bt) do { __builtin_amdgcn_s_setprio(1); _Pragma("unroll") for (int m = 0; m < 4; ++m) _Pragma("unroll") for (int n = 0; n < 2; ++n) _Pragma("unroll") for (int k = 0; k < 2; ++k) \
;         acc[ai][bj][m][n] = __builtin_amdgcn_mfma_f32_16x16x32_bf16(Bt[n][k], At[m][k], acc[ai][bj][m][n], 0, 0, 0); __builtin_amdgcn_s_setprio(0); } while (0)
; #define PG8_WAIT_V(n) asm volatile("s_waitcnt vmcnt(" #n ")" ::: "memory")
; #define PG8_WAIT_L(n) asm volatile("s_waitcnt lgkmcnt(" #n ")" ::: "memory")
; #define PG8_BAR __builtin_amdgcn_s_barrier()
; #define PG8_SCHED __builtin_amdgcn_sched_barrier(0)
; template <class Epi, bool ALIGN_EPI>
; DI void gemm_phase(LAS unsigned char* lds, const Sched& S, const Epi& E, int tid) {
;     ...
;             PG8_WAIT_V(8); PG8_WAIT_L(0); PG8_BAR; PG8_MMA(1, 0, At, B0); PG8_MMA(1, 1, At, B1); PG8_BAR; PG8_SCHED;
;             PG8_LDB(B0, 1, 0); PG8_LDB(B1, 1, 1); PG8_SCHED; PG8_LDA(At, 1, 0); PG8_STAGE(PG8_SA(0, 1), a2 + hstepA, voffA);
;             PG8_WAIT_V(8); PG8_WAIT_L(0); PG8_BAR; PG8_MMA(0, 0, At, B0); PG8_MMA(0, 1, At, B1); PG8_BAR; PG8_SCHED;
	s_setprio 1
	s_waitcnt lgkmcnt(0)
	v_mfma_f32_16x16x32_bf16 v[64:67], v[148:151], v[182:185], v[64:67]
	v_mfma_f32_16x16x32_bf16 v[60:63], v[156:159], v[182:185], v[60:63]
	v_mfma_f32_16x16x32_bf16 v[56:59], v[148:151], v[190:193], v[56:59]
	v_mfma_f32_16x16x32_bf16 v[48:51], v[156:159], v[190:193], v[48:51]
	v_mfma_f32_16x16x32_bf16 v[40:43], v[148:151], v[206:209], v[40:43]
	v_mfma_f32_16x16x32_bf16 v[32:35], v[156:159], v[206:209], v[32:35]
	v_mfma_f32_16x16x32_bf16 v[24:27], v[148:151], v[214:217], v[24:27]
	v_mfma_f32_16x16x32_bf16 v[16:19], v[156:159], v[214:217], v[16:19]
	v_mfma_f32_16x16x32_bf16 v[64:67], v[152:155], v[186:189], v[64:67]
	v_mfma_f32_16x16x32_bf16 v[60:63], v[162:165], v[186:189], v[60:63]
	v_mfma_f32_16x16x32_bf16 v[56:59], v[152:155], v[202:205], v[56:59]
	v_mfma_f32_16x16x32_bf16 v[48:51], v[162:165], v[202:205], v[48:51]
	v_mfma_f32_16x16x32_bf16 v[40:43], v[152:155], v[210:213], v[40:43]
	v_mfma_f32_16x16x32_bf16 v[32:35], v[162:165], v[210:213], v[32:35]
	v_mfma_f32_16x16x32_bf16 v[24:27], v[152:155], v[218:221], v[24:27]
	v_mfma_f32_16x16x32_bf16 v[16:19], v[162:165], v[218:221], v[16:19]
	s_setprio 0
	s_setprio 1
	v_mfma_f32_16x16x32_bf16 v[52:55], v[166:169], v[182:185], v[52:55]
	v_mfma_f32_16x16x32_bf16 v[44:47], v[174:177], v[182:185], v[44:47]
	v_mfma_f32_16x16x32_bf16 v[36:39], v[166:169], v[190:193], v[36:39]
	v_mfma_f32_16x16x32_bf16 v[28:31], v[174:177], v[190:193], v[28:31]
	v_mfma_f32_16x16x32_bf16 v[20:23], v[166:169], v[206:209], v[20:23]
	v_mfma_f32_16x16x32_bf16 v[12:15], v[174:177], v[206:209], v[12:15]
	v_mfma_f32_16x16x32_bf16 v[8:11], v[166:169], v[214:217], v[8:11]
	v_mfma_f32_16x16x32_bf16 v[4:7], v[174:177], v[214:217], v[4:7]
	v_mfma_f32_16x16x32_bf16 v[52:55], v[170:173], v[186:189], v[52:55]
	v_mfma_f32_16x16x32_bf16 v[44:47], v[178:181], v[186:189], v[44:47]
	v_mfma_f32_16x16x32_bf16 v[36:39], v[170:173], v[202:205], v[36:39]
	v_mfma_f32_16x16x32_bf16 v[28:31], v[178:181], v[202:205], v[28:31]
	v_mfma_f32_16x16x32_bf16 v[20:23], v[170:173], v[210:213], v[20:23]
	v_mfma_f32_16x16x32_bf16 v[12:15], v[178:181], v[210:213], v[12:15]
	v_mfma_f32_16x16x32_bf16 v[8:11], v[170:173], v[218:221], v[8:11]
	v_mfma_f32_16x16x32_bf16 v[4:7], v[178:181], v[218:221], v[4:7]
	s_setprio 0
	s_barrier
	s_add_i32 s48, 0, 0x18000
	v_add_u32_e32 v161, s48, v144
	s_add_i32 s49, 0, 0x1c000
	ds_read_b128 v[148:151], v161
	ds_read_b128 v[152:155], v161 offset:1024
	ds_read_b128 v[156:159], v161 offset:2048
	ds_read_b128 v[162:165], v161 offset:3072
	v_add_u32_e32 v161, s49, v144
	ds_read_b128 v[166:169], v161
	ds_read_b128 v[170:173], v161 offset:1024
	ds_read_b128 v[174:177], v161 offset:2048
	ds_read_b128 v[178:181], v161 offset:3072
	s_add_u32 s26, s26, 0x40000
	s_addc_u32 s27, s27, 0
	s_mov_b32 m0, s17
	s_nop 0
	global_load_lds_dwordx4 v[224:225], off
	s_mov_b32 m0, s36
	s_nop 0
	global_load_lds_dwordx4 v[226:227], off
	s_mov_b32 m0, s37
	v_lshl_add_u64 v[228:229], s[26:27], 0, v[138:139]
	ds_read_b128 v[182:185], v147 offset:32768
	ds_read_b128 v[186:189], v147 offset:33792
	ds_read_b128 v[190:193], v147 offset:34816
	ds_read_b128 v[202:205], v147 offset:35840
	ds_read_b128 v[206:209], v147 offset:36864
	ds_read_b128 v[210:213], v147 offset:37888
	ds_read_b128 v[214:217], v147 offset:38912
	ds_read_b128 v[218:221], v147 offset:39936
	global_load_lds_dwordx4 v[228:229], off
	v_lshl_add_u64 v[228:229], s[26:27], 0, v[134:135]
	s_mov_b32 m0, s38
	s_nop 0
	global_load_lds_dwordx4 v[228:229], off
	s_waitcnt vmcnt(8)
	s_waitcnt lgkmcnt(0)
	s_barrier
	s_setprio 1
	s_waitcnt lgkmcnt(0)
	v_mfma_f32_16x16x32_bf16 v[128:131], v[148:151], v[182:185], v[128:131]
	v_mfma_f32_16x16x32_bf16 v[124:127], v[156:159], v[182:185], v[124:127]
	v_mfma_f32_16x16x32_bf16 v[120:123], v[148:151], v[190:193], v[120:123]
	v_mfma_f32_16x16x32_bf16 v[112:115], v[156:159], v[190:193], v[112:115]
	v_mfma_f32_16x16x32_bf16 v[100:103], v[148:151], v[206:209], v[100:103]
	v_mfma_f32_16x16x32_bf16 v[92:95], v[156:159], v[206:209], v[92:95]
	v_mfma_f32_16x16x32_bf16 v[88:91], v[148:151], v[214:217], v[88:91]
	v_mfma_f32_16x16x32_bf16 v[80:83], v[156:159], v[214:217], v[80:83]
	v_mfma_f32_16x16x32_bf16 v[128:131], v[152:155], v[186:189], v[128:131]
	v_mfma_f32_16x16x32_bf16 v[124:127], v[162:165], v[186:189], v[124:127]
	v_mfma_f32_16x16x32_bf16 v[120:123], v[152:155], v[202:205], v[120:123]
	v_mfma_f32_16x16x32_bf16 v[112:115], v[162:165], v[202:205], v[112:115]
	v_mfma_f32_16x16x32_bf16 v[100:103], v[152:155], v[210:213], v[100:103]
	v_mfma_f32_16x16x32_bf16 v[92:95], v[162:165], v[210:213], v[92:95]
	v_mfma_f32_16x16x32_bf16 v[88:91], v[152:155], v[218:221], v[88:91]
	v_mfma_f32_16x16x32_bf16 v[80:83], v[162:165], v[218:221], v[80:83]
	s_setprio 0
	s_setprio 1
	v_mfma_f32_16x16x32_bf16 v[116:119], v[166:169], v[182:185], v[116:119]
	v_mfma_f32_16x16x32_bf16 v[108:111], v[174:177], v[182:185], v[108:111]
	v_mfma_f32_16x16x32_bf16 v[104:107], v[166:169], v[190:193], v[104:107]
	v_mfma_f32_16x16x32_bf16 v[96:99], v[174:177], v[190:193], v[96:99]
	v_mfma_f32_16x16x32_bf16 v[84:87], v[166:169], v[206:209], v[84:87]
	v_mfma_f32_16x16x32_bf16 v[76:79], v[174:177], v[206:209], v[76:79]
	v_mfma_f32_16x16x32_bf16 v[72:75], v[166:169], v[214:217], v[72:75]
	v_mfma_f32_16x16x32_bf16 v[68:71], v[174:177], v[214:217], v[68:71]
	v_mfma_f32_16x16x32_bf16 v[116:119], v[170:173], v[186:189], v[116:119]
	v_mfma_f32_16x16x32_bf16 v[108:111], v[178:181], v[186:189], v[108:111]
	v_mfma_f32_16x16x32_bf16 v[104:107], v[170:173], v[202:205], v[104:107]
	v_mfma_f32_16x16x32_bf16 v[96:99], v[178:181], v[202:205], v[96:99]
	v_mfma_f32_16x16x32_bf16 v[84:87], v[170:173], v[210:213], v[84:87]
	v_mfma_f32_16x16x32_bf16 v[76:79], v[178:181], v[210:213], v[76:79]
	v_mfma_f32_16x16x32_bf16 v[72:75], v[170:173], v[218:221], v[72:75]
	v_mfma_f32_16x16x32_bf16 v[68:71], v[178:181], v[218:221], v[68:71]
	s_setprio 0
	s_barrier
; #define PG8_STAGE(bufoff, gbase, voff) do { _Pragma("unroll") for (int _i = 0; _i < 2; ++_i) \
;         __builtin_amdgcn_global_load_lds((const unsigned*)((const char*)(gbase) + (voff)[_i]), (LAS unsigned*)(lds + (bufoff) + ldsw + _i * 8192), 16, 0, 0); } while (0)
; #define PG8_LDA(dst, b, h) do { _Pragma("unroll") for (int m = 0; m < 4; ++m) _Pragma("unroll") for (int k = 0; k < 2; ++k) dst[m][k] = *(const LAS bf16x8*)(lds + PG8_SA(b, h) + aoff + m * 2048 + k * 1024); } while (0)
; #define PG8_MMA(ai, bj, At, Bt) do { __builtin_amdgcn_s_setprio(1); _Pragma("unroll") for (int m = 0; m < 4; ++m) _Pragma("unroll") for (int n = 0; n < 2; ++n) _Pragma("unroll") for (int k = 0; k < 2; ++k) \
;         acc[ai][bj][m][n] = __builtin_amdgcn_mfma_f32_16x16x32_bf16(Bt[n][k], At[m][k], acc[ai][bj][m][n], 0, 0, 0); __builtin_amdgcn_s_setprio(0); } while (0)
; #define PG8_WAIT_V(n) asm volatile("s_waitcnt vmcnt(" #n ")" ::: "memory")
; #define PG8_WAIT_L(n) asm volatile("s_waitcnt lgkmcnt(" #n ")" ::: "memory")
; #define PG8_BAR __builtin_amdgcn_s_barrier()
; #define PG8_SCHED __builtin_amdgcn_sched_barrier(0)
; template <class Epi, bool ALIGN_EPI>
; DI void gemm_phase(LAS unsigned char* lds, const Sched& S, const Epi& E, int tid) {
;     ...
;             PG8_LDA(At, 1, 1); PG8_STAGE(PG8_SB(1, 0), b3, voffB); PG8_STAGE(PG8_SB(1, 1), b3 + hstepB, voffB); PG8_STAGE(PG8_SA(1, 0), a3, voffA);
;             PG8_WAIT_V(8); PG8_WAIT_L(0); PG8_BAR; PG8_MMA(1, 0, At, B0); PG8_MMA(1, 1, At, B1); PG8_BAR; PG8_SCHED;
;         }
	s_add_i32 s26, s48, s28
	v_lshl_add_u64 v[194:195], v[194:195], 0, s[84:85]
	s_mov_b32 m0, s26
	ds_read_b128 v[182:185], v147 offset:49152
	ds_read_b128 v[186:189], v147 offset:50176
	ds_read_b128 v[190:193], v147 offset:51200
	ds_read_b128 v[202:205], v147 offset:52224
	ds_read_b128 v[206:209], v147 offset:53248
	ds_read_b128 v[210:213], v147 offset:54272
	ds_read_b128 v[214:217], v147 offset:55296
	ds_read_b128 v[218:221], v147 offset:56320
	global_load_lds_dwordx4 v[194:195], off
	s_add_i32 m0, s26, 0x2000
	s_add_u32 s24, s24, 0x40080
	v_lshl_add_u64 v[194:195], v[222:223], 0, s[84:85]
	s_addc_u32 s25, s25, 0
	s_add_i32 s26, s49, s28
	global_load_lds_dwordx4 v[194:195], off
	v_lshl_add_u64 v[194:195], s[24:25], 0, v[136:137]
	s_mov_b32 m0, s26
	s_nop 0
	global_load_lds_dwordx4 v[194:195], off
	v_lshl_add_u64 v[194:195], s[24:25], 0, v[132:133]
	s_add_i32 m0, s26, 0x2000
	s_nop 0
	global_load_lds_dwordx4 v[194:195], off
	v_lshl_add_u64 v[230:231], v[224:225], 0, s[84:85]
	v_lshl_add_u64 v[232:233], v[226:227], 0, s[84:85]
	s_waitcnt vmcnt(6)
	s_waitcnt lgkmcnt(0)
	s_barrier
	s_setprio 1
	s_waitcnt lgkmcnt(0)
	v_mfma_f32_16x16x32_bf16 v[64:67], v[148:151], v[182:185], v[64:67]
	v_mfma_f32_16x16x32_bf16 v[60:63], v[156:159], v[182:185], v[60:63]
	v_mfma_f32_16x16x32_bf16 v[56:59], v[148:151], v[190:193], v[56:59]
	v_mfma_f32_16x16x32_bf16 v[48:51], v[156:159], v[190:193], v[48:51]
	v_mfma_f32_16x16x32_bf16 v[40:43], v[148:151], v[206:209], v[40:43]
	v_mfma_f32_16x16x32_bf16 v[32:35], v[156:159], v[206:209], v[32:35]
	v_mfma_f32_16x16x32_bf16 v[24:27], v[148:151], v[214:217], v[24:27]
	v_mfma_f32_16x16x32_bf16 v[16:19], v[156:159], v[214:217], v[16:19]
	v_mfma_f32_16x16x32_bf16 v[64:67], v[152:155], v[186:189], v[64:67]
	v_mfma_f32_16x16x32_bf16 v[60:63], v[162:165], v[186:189], v[60:63]
	v_mfma_f32_16x16x32_bf16 v[56:59], v[152:155], v[202:205], v[56:59]
	v_mfma_f32_16x16x32_bf16 v[48:51], v[162:165], v[202:205], v[48:51]
	v_mfma_f32_16x16x32_bf16 v[40:43], v[152:155], v[210:213], v[40:43]
	v_mfma_f32_16x16x32_bf16 v[32:35], v[162:165], v[210:213], v[32:35]
	v_mfma_f32_16x16x32_bf16 v[24:27], v[152:155], v[218:221], v[24:27]
	v_mfma_f32_16x16x32_bf16 v[16:19], v[162:165], v[218:221], v[16:19]
	s_setprio 0
	s_setprio 1
	v_mfma_f32_16x16x32_bf16 v[52:55], v[166:169], v[182:185], v[52:55]
	v_mfma_f32_16x16x32_bf16 v[44:47], v[174:177], v[182:185], v[44:47]
	v_mfma_f32_16x16x32_bf16 v[36:39], v[166:169], v[190:193], v[36:39]
	v_mfma_f32_16x16x32_bf16 v[28:31], v[174:177], v[190:193], v[28:31]
	v_mfma_f32_16x16x32_bf16 v[20:23], v[166:169], v[206:209], v[20:23]
	v_mfma_f32_16x16x32_bf16 v[12:15], v[174:177], v[206:209], v[12:15]
	v_mfma_f32_16x16x32_bf16 v[8:11], v[166:169], v[214:217], v[8:11]
	v_mfma_f32_16x16x32_bf16 v[4:7], v[174:177], v[214:217], v[4:7]
	v_mfma_f32_16x16x32_bf16 v[52:55], v[170:173], v[186:189], v[52:55]
	v_mfma_f32_16x16x32_bf16 v[44:47], v[178:181], v[186:189], v[44:47]
	v_mfma_f32_16x16x32_bf16 v[36:39], v[170:173], v[202:205], v[36:39]
	v_mfma_f32_16x16x32_bf16 v[28:31], v[178:181], v[202:205], v[28:31]
	v_mfma_f32_16x16x32_bf16 v[20:23], v[170:173], v[210:213], v[20:23]
	v_mfma_f32_16x16x32_bf16 v[12:15], v[178:181], v[210:213], v[12:15]
	v_mfma_f32_16x16x32_bf16 v[8:11], v[170:173], v[218:221], v[8:11]
	v_mfma_f32_16x16x32_bf16 v[4:7], v[178:181], v[218:221], v[4:7]
	s_setprio 0
	s_barrier
	s_add_i32 s47, s47, 2
	s_add_u32 s22, s22, 0x100
	s_addc_u32 s23, s23, 0
	s_add_u32 s45, s45, 0x100
	s_addc_u32 s46, s46, 0
	s_cmp_gt_u32 s47, 13
	s_cbranch_scc0 .LBB0_1961
	s_and_b64 vcc, exec, s[6:7]
	s_cbranch_vccz .LBB0_1964
	s_barrier

; #define PG8_STAGE(bufoff, gbase, voff) do { _Pragma("unroll") for (int _i = 0; _i < 2; ++_i) \
;         __builtin_amdgcn_global_load_lds((const unsigned*)((const char*)(gbase) + (voff)[_i]), (LAS unsigned*)(lds + (bufoff) + ldsw + _i * 8192), 16, 0, 0); } while (0)
; #define PG8_WAIT_V(n) asm volatile("s_waitcnt vmcnt(" #n ")" ::: "memory")
; #define PG8_BAR __builtin_amdgcn_s_barrier()
; template <class Epi, bool ALIGN_EPI>
; DI void gemm_phase(LAS unsigned char* lds, const Sched& S, const Epi& E, int tid) {
;     const int wid = __builtin_amdgcn_readfirstlane(tid >> 6), lane = tid & 63, wr = wid >> 2, wc = wid & 3, fr = lane & 15, fq = lane >> 4;
;     const int lda = S.lda, ldb = S.ldb;
;     unsigned voffA[2], voffB[2];
; #pragma unroll
;     for (int i = 0; i < 2; ++i) { int R, C; stage_rc(tid * 16 + i * 8192, R, C); const int Rb = (R & ~31) + perm32(R & 31);
;         voffA[i] = (unsigned)(R * lda + C) * 2u; voffB[i] = (unsigned)(Rb * ldb + C) * 2u; }
;     const size_t kstep = (size_t)(BK * 2);
;     const size_t hstepA = (size_t)HALF * lda * 2, hstepB = (size_t)HALF * ldb * 2;
;     const unsigned ldsw = (unsigned)wid * 1024u;
;     const int aoff = lds_byte(wr * 64 + fr, fq * 8), boff = lds_byte(wc * 32 + fr, fq * 8);
;     ...
;     PG8_STAGE(PG8_SB(0, 0), cB, voffB); PG8_STAGE(PG8_SB(0, 1), cB + hstepB, voffB); PG8_STAGE(PG8_SA(0, 0), cA, voffA); PG8_STAGE(PG8_SA(0, 1), cA + hstepA, voffA);
;     if (wr == 1) PG8_BAR;
;     PG8_WAIT_V(2); PG8_BAR;
;     PG8_STAGE(PG8_SB(1, 0), cB + kstep, voffB); PG8_STAGE(PG8_SA(1, 0), cA + kstep, voffA); PG8_STAGE(PG8_SB(1, 1), cB + hstepB + kstep, voffB);
;     PG8_WAIT_V(6); PG8_BAR;
.LBB0_2112:
	v_bfe_u32 v19, v0, 4, 2
	v_and_b32_e32 v18, 15, v0
	v_lshlrev_b32_e32 v21, 4, v19
	v_lshl_or_b32 v3, s3, 6, v18
	v_lshl_or_b32 v18, v18, 6, v21
	v_lshlrev_b32_e32 v21, 2, v0
	s_and_b32 s45, s2, 3
	s_lshl_b32 s2, s3, 13
	v_and_b32_e32 v21, 32, v21
	s_add_i32 m0, s41, 0x18000
	v_lshl_add_u64 v[10:11], v[10:11], 0, s[84:85]
	v_bitop3_b32 v22, v18, s2, v21 bitop3:0xde
	s_lshl_b32 s2, s45, 12
	s_waitcnt vmcnt(2)
	s_barrier
	global_load_lds_dwordx4 v[10:11], off
	v_lshl_add_u64 v[8:9], v[8:9], 0, s[84:85]
	s_add_i32 m0, s41, 0x1a000
	s_add_i32 s46, s41, 0x8000
	s_add_i32 s47, s41, 0xa000
	v_bitop3_b32 v161, s2, v18, v21 bitop3:0xf6
	global_load_lds_dwordx4 v[8:9], off
	v_lshl_add_u64 v[4:5], v[4:5], 0, s[84:85]
	s_mov_b32 m0, s46
	s_add_u32 s2, s26, 0x20080
	v_mov_b64_e32 v[230:231], v[4:5]
	global_load_lds_dwordx4 v[4:5], off
	v_lshl_add_u64 v[4:5], v[6:7], 0, s[84:85]
	s_mov_b32 m0, s47
	s_addc_u32 s3, s27, 0
	v_mov_b64_e32 v[232:233], v[4:5]
	global_load_lds_dwordx4 v[4:5], off
	s_add_i32 m0, s41, 0x1c000
	v_lshl_add_u64 v[4:5], s[2:3], 0, v[164:165]
	global_load_lds_dwordx4 v[4:5], off
	v_lshl_add_u64 v[4:5], s[2:3], 0, v[168:169]
	s_add_i32 m0, s41, 0x1e000
	s_cmpk_lt_u32 s6, 0x100
	global_load_lds_dwordx4 v[4:5], off
	v_lshlrev_b32_e32 v4, 13, v12
	s_cselect_b64 s[6:7], -1, 0
	s_add_u32 s49, s96, 0x1ff00000
	v_and_b32_e32 v4, 0xffffc000, v4
	s_addc_u32 s50, s97, 0
	v_lshl_add_u32 v4, v13, 10, v4
	v_and_b32_e32 v5, 1, v12
	s_add_u32 s8, s96, 0xff00000
	v_lshl_or_b32 v4, v5, 6, v4
	s_mul_i32 s10, s90, 0x480000
	s_addc_u32 s9, s97, 0
	v_lshl_add_u32 v170, v14, 1, v4
	v_lshlrev_b32_e32 v4, 13, v15
	s_add_u32 s10, s96, s10
	v_and_b32_e32 v4, 0xffffc000, v4
	s_waitcnt vmcnt(6)
	s_addc_u32 s11, s97, 0
	v_lshl_add_u32 v4, v16, 10, v4
	v_and_b32_e32 v5, 1, v15
	v_lshlrev_b32_e32 v20, 3, v19
	s_add_u32 s10, s10, 0x24460000
	v_lshl_or_b32 v4, v5, 6, v4
	v_lshl_or_b32 v192, s45, 5, v20
	s_mov_b32 s48, 0
	v_cmp_eq_u32_e64 s[2:3], 0, v19
	s_addc_u32 s11, s11, 0
	v_mov_b32_e32 v171, v2
	v_lshl_add_u32 v172, v17, 1, v4
	v_mov_b32_e32 v173, v2
	v_add_u32_e32 v193, 0, v22
	s_barrier
	s_branch .LBB0_2115

; #define PG8_STAGE(bufoff, gbase, voff) do { _Pragma("unroll") for (int _i = 0; _i < 2; ++_i) \
;         __builtin_amdgcn_global_load_lds((const unsigned*)((const char*)(gbase) + (voff)[_i]), (LAS unsigned*)(lds + (bufoff) + ldsw + _i * 8192), 16, 0, 0); } while (0)
; #define PG8_LDA(dst, b, h) do { _Pragma("unroll") for (int m = 0; m < 4; ++m) _Pragma("unroll") for (int k = 0; k < 2; ++k) dst[m][k] = *(const LAS bf16x8*)(lds + PG8_SA(b, h) + aoff + m * 2048 + k * 1024); } while (0)
; #define PG8_LDB(dst, b, h) do { _Pragma("unroll") for (int n = 0; n < 2; ++n) _Pragma("unroll") for (int k = 0; k < 2; ++k) dst[n][k] = *(const LAS bf16x8*)(lds + PG8_SB(b, h) + boff + n * 2048 + k * 1024); } while (0)
; #define PG8_MMA(ai, bj, At, Bt) do { __builtin_amdgcn_s_setprio(1); _Pragma("unroll") for (int m = 0; m < 4; ++m) _Pragma("unroll") for (int n = 0; n < 2; ++n) _Pragma("unroll") for (int k = 0; k < 2; ++k) \
;         acc[ai][bj][m][n] = __builtin_amdgcn_mfma_f32_16x16x32_bf16(Bt[n][k], At[m][k], acc[ai][bj][m][n], 0, 0, 0); __builtin_amdgcn_s_setprio(0); } while (0)
; #define PG8_WAIT_V(n) asm volatile("s_waitcnt vmcnt(" #n ")" ::: "memory")
; #define PG8_WAIT_L(n) asm volatile("s_waitcnt lgkmcnt(" #n ")" ::: "memory")
; template <class Epi, bool ALIGN_EPI>
; DI void gemm_phase(LAS unsigned char* lds, const Sched& S, const Epi& E, int tid) {
;     ...
;         const char* nA = has_next ? nxt.a : cA; const char* nB = has_next ? nxt.b : cB;
;         const int nt = cur.nt;
;         for (int t = 0; t < nt; t += 2) {
;             const bool last = (t == nt - 2);
;             const char* a1 = cA + (size_t)(t + 1) * kstep;
;             const char* a2 = last ? nA : cA + (size_t)(t + 2) * kstep; const char* b2 = last ? nB : cB + (size_t)(t + 2) * kstep;
;             const char* a3 = a2 + kstep; const char* b3 = b2 + kstep;
;             PG8_LDB(B0, 0, 0); PG8_LDB(B1, 0, 1); PG8_SCHED; PG8_LDA(At, 0, 0); PG8_STAGE(PG8_SA(1, 1), a1 + hstepA, voffA);
;             PG8_WAIT_V(8); PG8_WAIT_L(0); PG8_BAR; PG8_MMA(0, 0, At, B0); PG8_MMA(0, 1, At, B1); PG8_BAR; PG8_SCHED;
;             PG8_LDA(At, 0, 1); PG8_STAGE(PG8_SB(0, 0), b2, voffB); PG8_STAGE(PG8_SB(0, 1), b2 + hstepB, voffB); PG8_STAGE(PG8_SA(0, 0), a2, voffA);
;             PG8_WAIT_V(8); PG8_WAIT_L(0); PG8_BAR; PG8_MMA(1, 0, At, B0); PG8_MMA(1, 1, At, B1); PG8_BAR; PG8_SCHED;
.LBB0_2125:
	s_add_i32 s61, s26, 2
	s_add_u32 s27, s24, 0xfffe0080
	s_addc_u32 s28, s25, -1
	s_add_i32 s62, 0, 0x10000
	s_cmp_eq_u32 s58, s26
	s_cselect_b32 s29, s54, s28
	s_cselect_b32 s28, s55, s27
	s_cselect_b32 s27, s56, s60
	s_cselect_b32 s26, s57, s59
	s_add_i32 s64, 0, 0x14000
	v_add_u32_e32 v144, s62, v161
	v_add_u32_e32 v174, s64, v161
	ds_read_b128 v[132:135], v144
	ds_read_b128 v[136:139], v144 offset:1024
	ds_read_b128 v[140:143], v144 offset:2048
	ds_read_b128 v[144:147], v144 offset:3072
	ds_read_b128 v[148:151], v174
	ds_read_b128 v[152:155], v174 offset:1024
	ds_read_b128 v[156:159], v174 offset:2048
	ds_read_b128 v[174:177], v174 offset:3072
	v_lshl_add_u64 v[190:191], s[24:25], 0, v[170:171]
	s_mov_b32 m0, s46
	s_nop 0
	global_load_lds_dwordx4 v[230:231], off
	s_mov_b32 m0, s47
	s_nop 0
	global_load_lds_dwordx4 v[232:233], off
	s_add_i32 m0, s41, 0xc000
	ds_read_b128 v[178:181], v193
	ds_read_b128 v[182:185], v193 offset:1024
	ds_read_b128 v[186:189], v193 offset:2048
	ds_read_b128 v[202:205], v193 offset:3072
	ds_read_b128 v[206:209], v193 offset:4096
	ds_read_b128 v[210:213], v193 offset:5120
	ds_read_b128 v[214:217], v193 offset:6144
	ds_read_b128 v[218:221], v193 offset:7168
	global_load_lds_dwordx4 v[190:191], off
	v_lshl_add_u64 v[190:191], s[24:25], 0, v[172:173]
	s_add_i32 m0, s41, 0xe000
	s_nop 0
	global_load_lds_dwordx4 v[190:191], off
	s_waitcnt vmcnt(8)
	s_waitcnt lgkmcnt(0)
	s_barrier
	s_setprio 1
	s_waitcnt lgkmcnt(0)
	v_mfma_f32_16x16x32_bf16 v[128:131], v[132:135], v[178:181], v[128:131]
	v_mfma_f32_16x16x32_bf16 v[124:127], v[140:143], v[178:181], v[124:127]
	v_mfma_f32_16x16x32_bf16 v[112:115], v[132:135], v[186:189], v[112:115]
	v_mfma_f32_16x16x32_bf16 v[108:111], v[140:143], v[186:189], v[108:111]
	v_mfma_f32_16x16x32_bf16 v[96:99], v[132:135], v[206:209], v[96:99]
	v_mfma_f32_16x16x32_bf16 v[92:95], v[140:143], v[206:209], v[92:95]
	v_mfma_f32_16x16x32_bf16 v[80:83], v[132:135], v[214:217], v[80:83]
	v_mfma_f32_16x16x32_bf16 v[76:79], v[140:143], v[214:217], v[76:79]
	v_mfma_f32_16x16x32_bf16 v[128:131], v[136:139], v[182:185], v[128:131]
	v_mfma_f32_16x16x32_bf16 v[124:127], v[144:147], v[182:185], v[124:127]
	v_mfma_f32_16x16x32_bf16 v[112:115], v[136:139], v[202:205], v[112:115]
	v_mfma_f32_16x16x32_bf16 v[108:111], v[144:147], v[202:205], v[108:111]
	v_mfma_f32_16x16x32_bf16 v[96:99], v[136:139], v[210:213], v[96:99]
	v_mfma_f32_16x16x32_bf16 v[92:95], v[144:147], v[210:213], v[92:95]
	v_mfma_f32_16x16x32_bf16 v[80:83], v[136:139], v[218:221], v[80:83]
	v_mfma_f32_16x16x32_bf16 v[76:79], v[144:147], v[218:221], v[76:79]
	s_setprio 0
	s_setprio 1
	v_mfma_f32_16x16x32_bf16 v[120:123], v[148:151], v[178:181], v[120:123]
	v_mfma_f32_16x16x32_bf16 v[116:119], v[156:159], v[178:181], v[116:119]
	v_mfma_f32_16x16x32_bf16 v[104:107], v[148:151], v[186:189], v[104:107]
	v_mfma_f32_16x16x32_bf16 v[100:103], v[156:159], v[186:189], v[100:103]
	v_mfma_f32_16x16x32_bf16 v[88:91], v[148:151], v[206:209], v[88:91]
	v_mfma_f32_16x16x32_bf16 v[84:87], v[156:159], v[206:209], v[84:87]
	v_mfma_f32_16x16x32_bf16 v[72:75], v[148:151], v[214:217], v[72:75]
	v_mfma_f32_16x16x32_bf16 v[68:71], v[156:159], v[214:217], v[68:71]
	v_mfma_f32_16x16x32_bf16 v[120:123], v[152:155], v[182:185], v[120:123]
	v_mfma_f32_16x16x32_bf16 v[116:119], v[174:177], v[182:185], v[116:119]
	v_mfma_f32_16x16x32_bf16 v[104:107], v[152:155], v[202:205], v[104:107]
	v_mfma_f32_16x16x32_bf16 v[100:103], v[174:177], v[202:205], v[100:103]
	v_mfma_f32_16x16x32_bf16 v[88:91], v[152:155], v[210:213], v[88:91]
	v_mfma_f32_16x16x32_bf16 v[84:87], v[174:177], v[210:213], v[84:87]
	v_mfma_f32_16x16x32_bf16 v[72:75], v[152:155], v[218:221], v[72:75]
	v_mfma_f32_16x16x32_bf16 v[68:71], v[174:177], v[218:221], v[68:71]
	s_setprio 0
	s_barrier
	s_add_i32 s62, s62, s40
	v_lshl_add_u64 v[190:191], s[26:27], 0, v[164:165]
	s_mov_b32 m0, s62
	ds_read_b128 v[178:181], v193 offset:16384
	ds_read_b128 v[182:185], v193 offset:17408
	ds_read_b128 v[186:189], v193 offset:18432
	ds_read_b128 v[202:205], v193 offset:19456
	ds_read_b128 v[206:209], v193 offset:20480
	ds_read_b128 v[210:213], v193 offset:21504
	ds_read_b128 v[214:217], v193 offset:22528
	ds_read_b128 v[218:221], v193 offset:23552
	global_load_lds_dwordx4 v[190:191], off
	s_add_i32 m0, s62, 0x2000
	s_add_u32 s62, s26, 0x20000
	v_lshl_add_u64 v[194:195], s[26:27], 0, v[168:169]
	s_addc_u32 s63, s27, 0
	s_add_i32 s64, s64, s40
	global_load_lds_dwordx4 v[194:195], off
	v_lshl_add_u64 v[222:223], s[62:63], 0, v[164:165]
	s_mov_b32 m0, s64
	v_lshl_add_u64 v[224:225], s[28:29], 0, v[166:167]
	global_load_lds_dwordx4 v[222:223], off
	v_lshl_add_u64 v[222:223], s[62:63], 0, v[168:169]
	s_add_i32 m0, s64, 0x2000
	s_nop 0
	global_load_lds_dwordx4 v[222:223], off
	v_lshl_add_u64 v[222:223], s[28:29], 0, v[162:163]
	s_waitcnt vmcnt(6)
	s_waitcnt lgkmcnt(0)
	s_barrier
; #define PG8_STAGE(bufoff, gbase, voff) do { _Pragma("unroll") for (int _i = 0; _i < 2; ++_i) \
;         __builtin_amdgcn_global_load_lds((const unsigned*)((const char*)(gbase) + (voff)[_i]), (LAS unsigned*)(lds + (bufoff) + ldsw + _i * 8192), 16, 0, 0); } while (0)
; #define PG8_LDA(dst, b, h) do { _Pragma("unroll") for (int m = 0; m < 4; ++m) _Pragma("unroll") for (int k = 0; k < 2; ++k) dst[m][k] = *(const LAS bf16x8*)(lds + PG8_SA(b, h) + aoff + m * 2048 + k * 1024); } while (0)
; #define PG8_LDB(dst, b, h) do { _Pragma("unroll") for (int n = 0; n < 2; ++n) _Pragma("unroll") for (int k = 0; k < 2; ++k) dst[n][k] = *(const LAS bf16x8*)(lds + PG8_SB(b, h) + boff + n * 2048 + k * 1024); } while (0)
; #define PG8_MMA(ai, bj, At, Bt) do { __builtin_amdgcn_s_setprio(1); _Pragma("unroll") for (int m = 0; m < 4; ++m) _Pragma("unroll") for (int n = 0; n < 2; ++n) _Pragma("unroll") for (int k = 0; k < 2; ++k) \
;         acc[ai][bj][m][n] = __builtin_amdgcn_mfma_f32_16x16x32_bf16(Bt[n][k], At[m][k], acc[ai][bj][m][n], 0, 0, 0); __builtin_amdgcn_s_setprio(0); } while (0)
; #define PG8_WAIT_V(n) asm volatile("s_waitcnt vmcnt(" #n ")" ::: "memory")
; #define PG8_WAIT_L(n) asm volatile("s_waitcnt lgkmcnt(" #n ")" ::: "memory")
; #define PG8_BAR __builtin_amdgcn_s_barrier()
; #define PG8_SCHED __builtin_amdgcn_sched_barrier(0)
; template <class Epi, bool ALIGN_EPI>
; DI void gemm_phase(LAS unsigned char* lds, const Sched& S, const Epi& E, int tid) {
;     ...
;             PG8_WAIT_V(8); PG8_WAIT_L(0); PG8_BAR; PG8_MMA(1, 0, At, B0); PG8_MMA(1, 1, At, B1); PG8_BAR; PG8_SCHED;
;             PG8_LDB(B0, 1, 0); PG8_LDB(B1, 1, 1); PG8_SCHED; PG8_LDA(At, 1, 0); PG8_STAGE(PG8_SA(0, 1), a2 + hstepA, voffA);
;             PG8_WAIT_V(8); PG8_WAIT_L(0); PG8_BAR; PG8_MMA(0, 0, At, B0); PG8_MMA(0, 1, At, B1); PG8_BAR; PG8_SCHED;
	s_setprio 1
	s_waitcnt lgkmcnt(0)
	v_mfma_f32_16x16x32_bf16 v[64:67], v[132:135], v[178:181], v[64:67]
	v_mfma_f32_16x16x32_bf16 v[60:63], v[140:143], v[178:181], v[60:63]
	v_mfma_f32_16x16x32_bf16 v[48:51], v[132:135], v[186:189], v[48:51]
	v_mfma_f32_16x16x32_bf16 v[44:47], v[140:143], v[186:189], v[44:47]
	v_mfma_f32_16x16x32_bf16 v[32:35], v[132:135], v[206:209], v[32:35]
	v_mfma_f32_16x16x32_bf16 v[28:31], v[140:143], v[206:209], v[28:31]
	v_mfma_f32_16x16x32_bf16 v[16:19], v[132:135], v[214:217], v[16:19]
	v_mfma_f32_16x16x32_bf16 v[12:15], v[140:143], v[214:217], v[12:15]
	v_mfma_f32_16x16x32_bf16 v[64:67], v[136:139], v[182:185], v[64:67]
	v_mfma_f32_16x16x32_bf16 v[60:63], v[144:147], v[182:185], v[60:63]
	v_mfma_f32_16x16x32_bf16 v[48:51], v[136:139], v[202:205], v[48:51]
	v_mfma_f32_16x16x32_bf16 v[44:47], v[144:147], v[202:205], v[44:47]
	v_mfma_f32_16x16x32_bf16 v[32:35], v[136:139], v[210:213], v[32:35]
	v_mfma_f32_16x16x32_bf16 v[28:31], v[144:147], v[210:213], v[28:31]
	v_mfma_f32_16x16x32_bf16 v[16:19], v[136:139], v[218:221], v[16:19]
	v_mfma_f32_16x16x32_bf16 v[12:15], v[144:147], v[218:221], v[12:15]
	s_setprio 0
	s_setprio 1
	v_mfma_f32_16x16x32_bf16 v[56:59], v[148:151], v[178:181], v[56:59]
	v_mfma_f32_16x16x32_bf16 v[52:55], v[156:159], v[178:181], v[52:55]
	v_mfma_f32_16x16x32_bf16 v[40:43], v[148:151], v[186:189], v[40:43]
	v_mfma_f32_16x16x32_bf16 v[36:39], v[156:159], v[186:189], v[36:39]
	v_mfma_f32_16x16x32_bf16 v[24:27], v[148:151], v[206:209], v[24:27]
	v_mfma_f32_16x16x32_bf16 v[20:23], v[156:159], v[206:209], v[20:23]
	v_mfma_f32_16x16x32_bf16 v[8:11], v[148:151], v[214:217], v[8:11]
	v_mfma_f32_16x16x32_bf16 v[4:7], v[156:159], v[214:217], v[4:7]
	v_mfma_f32_16x16x32_bf16 v[56:59], v[152:155], v[182:185], v[56:59]
	v_mfma_f32_16x16x32_bf16 v[52:55], v[174:177], v[182:185], v[52:55]
	v_mfma_f32_16x16x32_bf16 v[40:43], v[152:155], v[202:205], v[40:43]
	v_mfma_f32_16x16x32_bf16 v[36:39], v[174:177], v[202:205], v[36:39]
	v_mfma_f32_16x16x32_bf16 v[24:27], v[152:155], v[210:213], v[24:27]
	v_mfma_f32_16x16x32_bf16 v[20:23], v[174:177], v[210:213], v[20:23]
	v_mfma_f32_16x16x32_bf16 v[8:11], v[152:155], v[218:221], v[8:11]
	v_mfma_f32_16x16x32_bf16 v[4:7], v[174:177], v[218:221], v[4:7]
	s_setprio 0
	s_barrier
	s_add_i32 s62, 0, 0x18000
	s_add_i32 s63, 0, 0x1c000
	v_add_u32_e32 v144, s62, v161
	v_add_u32_e32 v174, s63, v161
	ds_read_b128 v[132:135], v144
	ds_read_b128 v[136:139], v144 offset:1024
	ds_read_b128 v[140:143], v144 offset:2048
	ds_read_b128 v[144:147], v144 offset:3072
	ds_read_b128 v[148:151], v174
	ds_read_b128 v[152:155], v174 offset:1024
	ds_read_b128 v[156:159], v174 offset:2048
	ds_read_b128 v[174:177], v174 offset:3072
	s_add_u32 s28, s28, 0x20000
	s_addc_u32 s29, s29, 0
	s_mov_b32 m0, s41
	s_nop 0
	global_load_lds_dwordx4 v[222:223], off
	s_mov_b32 m0, s42
	s_nop 0
	global_load_lds_dwordx4 v[224:225], off
	s_mov_b32 m0, s43
	v_lshl_add_u64 v[226:227], s[28:29], 0, v[162:163]
	ds_read_b128 v[178:181], v193 offset:32768
	ds_read_b128 v[182:185], v193 offset:33792
	ds_read_b128 v[186:189], v193 offset:34816
	ds_read_b128 v[202:205], v193 offset:35840
	ds_read_b128 v[206:209], v193 offset:36864
	ds_read_b128 v[210:213], v193 offset:37888
	ds_read_b128 v[214:217], v193 offset:38912
	ds_read_b128 v[218:221], v193 offset:39936
	global_load_lds_dwordx4 v[226:227], off
	v_lshl_add_u64 v[226:227], s[28:29], 0, v[166:167]
	s_mov_b32 m0, s44
	s_nop 0
	global_load_lds_dwordx4 v[226:227], off
	s_waitcnt vmcnt(8)
	s_waitcnt lgkmcnt(0)
	s_barrier
	s_setprio 1
	s_waitcnt lgkmcnt(0)
	v_mfma_f32_16x16x32_bf16 v[128:131], v[132:135], v[178:181], v[128:131]
	v_mfma_f32_16x16x32_bf16 v[124:127], v[140:143], v[178:181], v[124:127]
	v_mfma_f32_16x16x32_bf16 v[112:115], v[132:135], v[186:189], v[112:115]
	v_mfma_f32_16x16x32_bf16 v[108:111], v[140:143], v[186:189], v[108:111]
	v_mfma_f32_16x16x32_bf16 v[96:99], v[132:135], v[206:209], v[96:99]
	v_mfma_f32_16x16x32_bf16 v[92:95], v[140:143], v[206:209], v[92:95]
	v_mfma_f32_16x16x32_bf16 v[80:83], v[132:135], v[214:217], v[80:83]
	v_mfma_f32_16x16x32_bf16 v[76:79], v[140:143], v[214:217], v[76:79]
	v_mfma_f32_16x16x32_bf16 v[128:131], v[136:139], v[182:185], v[128:131]
	v_mfma_f32_16x16x32_bf16 v[124:127], v[144:147], v[182:185], v[124:127]
	v_mfma_f32_16x16x32_bf16 v[112:115], v[136:139], v[202:205], v[112:115]
	v_mfma_f32_16x16x32_bf16 v[108:111], v[144:147], v[202:205], v[108:111]
	v_mfma_f32_16x16x32_bf16 v[96:99], v[136:139], v[210:213], v[96:99]
	v_mfma_f32_16x16x32_bf16 v[92:95], v[144:147], v[210:213], v[92:95]
	v_mfma_f32_16x16x32_bf16 v[80:83], v[136:139], v[218:221], v[80:83]
	v_mfma_f32_16x16x32_bf16 v[76:79], v[144:147], v[218:221], v[76:79]
	s_setprio 0
	s_setprio 1
	v_mfma_f32_16x16x32_bf16 v[120:123], v[148:151], v[178:181], v[120:123]
	v_mfma_f32_16x16x32_bf16 v[116:119], v[156:159], v[178:181], v[116:119]
	v_mfma_f32_16x16x32_bf16 v[104:107], v[148:151], v[186:189], v[104:107]
	v_mfma_f32_16x16x32_bf16 v[100:103], v[156:159], v[186:189], v[100:103]
	v_mfma_f32_16x16x32_bf16 v[88:91], v[148:151], v[206:209], v[88:91]
	v_mfma_f32_16x16x32_bf16 v[84:87], v[156:159], v[206:209], v[84:87]
	v_mfma_f32_16x16x32_bf16 v[72:75], v[148:151], v[214:217], v[72:75]
	v_mfma_f32_16x16x32_bf16 v[68:71], v[156:159], v[214:217], v[68:71]
	v_mfma_f32_16x16x32_bf16 v[120:123], v[152:155], v[182:185], v[120:123]
	v_mfma_f32_16x16x32_bf16 v[116:119], v[174:177], v[182:185], v[116:119]
	v_mfma_f32_16x16x32_bf16 v[104:107], v[152:155], v[202:205], v[104:107]
	v_mfma_f32_16x16x32_bf16 v[100:103], v[174:177], v[202:205], v[100:103]
	v_mfma_f32_16x16x32_bf16 v[88:91], v[152:155], v[210:213], v[88:91]
	v_mfma_f32_16x16x32_bf16 v[84:87], v[174:177], v[210:213], v[84:87]
	v_mfma_f32_16x16x32_bf16 v[72:75], v[152:155], v[218:221], v[72:75]
	v_mfma_f32_16x16x32_bf16 v[68:71], v[174:177], v[218:221], v[68:71]
	s_setprio 0
	s_barrier
; #define PG8_STAGE(bufoff, gbase, voff) do { _Pragma("unroll") for (int _i = 0; _i < 2; ++_i) \
;         __builtin_amdgcn_global_load_lds((const unsigned*)((const char*)(gbase) + (voff)[_i]), (LAS unsigned*)(lds + (bufoff) + ldsw + _i * 8192), 16, 0, 0); } while (0)
; #define PG8_LDA(dst, b, h) do { _Pragma("unroll") for (int m = 0; m < 4; ++m) _Pragma("unroll") for (int k = 0; k < 2; ++k) dst[m][k] = *(const LAS bf16x8*)(lds + PG8_SA(b, h) + aoff + m * 2048 + k * 1024); } while (0)
; #define PG8_MMA(ai, bj, At, Bt) do { __builtin_amdgcn_s_setprio(1); _Pragma("unroll") for (int m = 0; m < 4; ++m) _Pragma("unroll") for (int n = 0; n < 2; ++n) _Pragma("unroll") for (int k = 0; k < 2; ++k) \
;         acc[ai][bj][m][n] = __builtin_amdgcn_mfma_f32_16x16x32_bf16(Bt[n][k], At[m][k], acc[ai][bj][m][n], 0, 0, 0); __builtin_amdgcn_s_setprio(0); } while (0)
; #define PG8_WAIT_V(n) asm volatile("s_waitcnt vmcnt(" #n ")" ::: "memory")
; #define PG8_WAIT_L(n) asm volatile("s_waitcnt lgkmcnt(" #n ")" ::: "memory")
; #define PG8_BAR __builtin_amdgcn_s_barrier()
; #define PG8_SCHED __builtin_amdgcn_sched_barrier(0)
; template <class Epi, bool ALIGN_EPI>
; DI void gemm_phase(LAS unsigned char* lds, const Sched& S, const Epi& E, int tid) {
;     ...
;             PG8_LDA(At, 1, 1); PG8_STAGE(PG8_SB(1, 0), b3, voffB); PG8_STAGE(PG8_SB(1, 1), b3 + hstepB, voffB); PG8_STAGE(PG8_SA(1, 0), a3, voffA);
;             PG8_WAIT_V(8); PG8_WAIT_L(0); PG8_BAR; PG8_MMA(1, 0, At, B0); PG8_MMA(1, 1, At, B1); PG8_BAR; PG8_SCHED;
;         }
	s_add_i32 s28, s62, s40
	v_lshl_add_u64 v[190:191], v[190:191], 0, s[84:85]
	s_mov_b32 m0, s28
	ds_read_b128 v[178:181], v193 offset:49152
	ds_read_b128 v[182:185], v193 offset:50176
	ds_read_b128 v[186:189], v193 offset:51200
	ds_read_b128 v[202:205], v193 offset:52224
	ds_read_b128 v[206:209], v193 offset:53248
	ds_read_b128 v[210:213], v193 offset:54272
	ds_read_b128 v[214:217], v193 offset:55296
	ds_read_b128 v[218:221], v193 offset:56320
	global_load_lds_dwordx4 v[190:191], off
	s_add_i32 m0, s28, 0x2000
	s_add_u32 s26, s26, 0x20080
	v_lshl_add_u64 v[190:191], v[194:195], 0, s[84:85]
	s_addc_u32 s27, s27, 0
	s_add_i32 s28, s63, s40
	global_load_lds_dwordx4 v[190:191], off
	v_lshl_add_u64 v[190:191], s[26:27], 0, v[164:165]
	s_mov_b32 m0, s28
	s_nop 0
	global_load_lds_dwordx4 v[190:191], off
	v_lshl_add_u64 v[190:191], s[26:27], 0, v[168:169]
	s_add_i32 m0, s28, 0x2000
	s_nop 0
	global_load_lds_dwordx4 v[190:191], off
	v_lshl_add_u64 v[230:231], v[222:223], 0, s[84:85]
	v_lshl_add_u64 v[232:233], v[224:225], 0, s[84:85]
	s_waitcnt vmcnt(6)
	s_waitcnt lgkmcnt(0)
	s_barrier
	s_setprio 1
	s_waitcnt lgkmcnt(0)
	v_mfma_f32_16x16x32_bf16 v[64:67], v[132:135], v[178:181], v[64:67]
	v_mfma_f32_16x16x32_bf16 v[60:63], v[140:143], v[178:181], v[60:63]
	v_mfma_f32_16x16x32_bf16 v[48:51], v[132:135], v[186:189], v[48:51]
	v_mfma_f32_16x16x32_bf16 v[44:47], v[140:143], v[186:189], v[44:47]
	v_mfma_f32_16x16x32_bf16 v[32:35], v[132:135], v[206:209], v[32:35]
	v_mfma_f32_16x16x32_bf16 v[28:31], v[140:143], v[206:209], v[28:31]
	v_mfma_f32_16x16x32_bf16 v[16:19], v[132:135], v[214:217], v[16:19]
	v_mfma_f32_16x16x32_bf16 v[12:15], v[140:143], v[214:217], v[12:15]
	v_mfma_f32_16x16x32_bf16 v[64:67], v[136:139], v[182:185], v[64:67]
	v_mfma_f32_16x16x32_bf16 v[60:63], v[144:147], v[182:185], v[60:63]
	v_mfma_f32_16x16x32_bf16 v[48:51], v[136:139], v[202:205], v[48:51]
	v_mfma_f32_16x16x32_bf16 v[44:47], v[144:147], v[202:205], v[44:47]
	v_mfma_f32_16x16x32_bf16 v[32:35], v[136:139], v[210:213], v[32:35]
	v_mfma_f32_16x16x32_bf16 v[28:31], v[144:147], v[210:213], v[28:31]
	v_mfma_f32_16x16x32_bf16 v[16:19], v[136:139], v[218:221], v[16:19]
	v_mfma_f32_16x16x32_bf16 v[12:15], v[144:147], v[218:221], v[12:15]
	s_setprio 0
	s_setprio 1
	v_mfma_f32_16x16x32_bf16 v[56:59], v[148:151], v[178:181], v[56:59]
	v_mfma_f32_16x16x32_bf16 v[52:55], v[156:159], v[178:181], v[52:55]
	v_mfma_f32_16x16x32_bf16 v[40:43], v[148:151], v[186:189], v[40:43]
	v_mfma_f32_16x16x32_bf16 v[36:39], v[156:159], v[186:189], v[36:39]
	v_mfma_f32_16x16x32_bf16 v[24:27], v[148:151], v[206:209], v[24:27]
	v_mfma_f32_16x16x32_bf16 v[20:23], v[156:159], v[206:209], v[20:23]
	v_mfma_f32_16x16x32_bf16 v[8:11], v[148:151], v[214:217], v[8:11]
	v_mfma_f32_16x16x32_bf16 v[4:7], v[156:159], v[214:217], v[4:7]
	v_mfma_f32_16x16x32_bf16 v[56:59], v[152:155], v[182:185], v[56:59]
	v_mfma_f32_16x16x32_bf16 v[52:55], v[174:177], v[182:185], v[52:55]
	v_mfma_f32_16x16x32_bf16 v[40:43], v[152:155], v[202:205], v[40:43]
	v_mfma_f32_16x16x32_bf16 v[36:39], v[174:177], v[202:205], v[36:39]
	v_mfma_f32_16x16x32_bf16 v[24:27], v[152:155], v[210:213], v[24:27]
	v_mfma_f32_16x16x32_bf16 v[20:23], v[174:177], v[210:213], v[20:23]
	v_mfma_f32_16x16x32_bf16 v[8:11], v[152:155], v[218:221], v[8:11]
	v_mfma_f32_16x16x32_bf16 v[4:7], v[174:177], v[218:221], v[4:7]
	s_setprio 0
	s_barrier
	s_add_u32 s24, s24, 0x100
	s_addc_u32 s25, s25, 0
	s_add_u32 s59, s59, 0x100
	s_addc_u32 s60, s60, 0
	s_cmp_ge_i32 s61, s23
	s_mov_b32 s26, s61
	s_cbranch_scc0 .LBB0_2125
	s_and_b64 vcc, exec, s[6:7]
	s_cbranch_vccz .LBB0_2128
	s_barrier

; #define PG8_STAGE(bufoff, gbase, voff) do { _Pragma("unroll") for (int _i = 0; _i < 2; ++_i) \
;         __builtin_amdgcn_global_load_lds((const unsigned*)((const char*)(gbase) + (voff)[_i]), (LAS unsigned*)(lds + (bufoff) + ldsw + _i * 8192), 16, 0, 0); } while (0)
; #define PG8_WAIT_V(n) asm volatile("s_waitcnt vmcnt(" #n ")" ::: "memory")
; #define PG8_BAR __builtin_amdgcn_s_barrier()
; template <class Epi, bool ALIGN_EPI>
; DI void gemm_phase(LAS unsigned char* lds, const Sched& S, const Epi& E, int tid) {
;     const int wid = __builtin_amdgcn_readfirstlane(tid >> 6), lane = tid & 63, wr = wid >> 2, wc = wid & 3, fr = lane & 15, fq = lane >> 4;
;     const int lda = S.lda, ldb = S.ldb;
;     unsigned voffA[2], voffB[2];
; #pragma unroll
;     for (int i = 0; i < 2; ++i) { int R, C; stage_rc(tid * 16 + i * 8192, R, C); const int Rb = (R & ~31) + perm32(R & 31);
;         voffA[i] = (unsigned)(R * lda + C) * 2u; voffB[i] = (unsigned)(Rb * ldb + C) * 2u; }
;     const size_t kstep = (size_t)(BK * 2);
;     const size_t hstepA = (size_t)HALF * lda * 2, hstepB = (size_t)HALF * ldb * 2;
;     const unsigned ldsw = (unsigned)wid * 1024u;
;     const int aoff = lds_byte(wr * 64 + fr, fq * 8), boff = lds_byte(wc * 32 + fr, fq * 8);
;     ...
;     PG8_STAGE(PG8_SB(0, 0), cB, voffB); PG8_STAGE(PG8_SB(0, 1), cB + hstepB, voffB); PG8_STAGE(PG8_SA(0, 0), cA, voffA); PG8_STAGE(PG8_SA(0, 1), cA + hstepA, voffA);
;     if (wr == 1) PG8_BAR;
;     PG8_WAIT_V(2); PG8_BAR;
;     PG8_STAGE(PG8_SB(1, 0), cB + kstep, voffB); PG8_STAGE(PG8_SA(1, 0), cA + kstep, voffA); PG8_STAGE(PG8_SB(1, 1), cB + hstepB + kstep, voffB);
;     PG8_WAIT_V(6); PG8_BAR;
.LBB0_2315:
	v_lshrrev_b32_e32 v19, 1, v0
	s_sext_i32_i16 s43, s4
	s_add_u32 s4, s96, 0x16b00000
	v_and_b32_e32 v19, 24, v19
	s_addc_u32 s5, s97, 0
	v_and_b32_e32 v18, 15, v0
	v_lshlrev_b32_e32 v20, 1, v19
	s_lshl_b32 s8, s8, 5
	v_lshl_or_b32 v3, s7, 6, v18
	v_lshl_or_b32 v20, v18, 6, v20
	v_lshlrev_b32_e32 v18, 2, v18
	s_and_b32 s10, s8, 0x60
	s_add_i32 m0, s17, 0x18000
	v_lshl_add_u64 v[10:11], v[10:11], 0, s[84:85]
	s_lshl_b32 s9, s7, 13
	v_and_b32_e32 v21, 32, v18
	s_lshl_b32 s8, s10, 7
	s_waitcnt vmcnt(2)
	s_barrier
	global_load_lds_dwordx4 v[10:11], off
	v_lshl_add_u64 v[8:9], v[8:9], 0, s[84:85]
	s_add_i32 m0, s17, 0x1a000
	s_add_i32 s39, s17, 0x8000
	s_add_i32 s40, s17, 0xa000
	v_bitop3_b32 v144, s8, v20, v21 bitop3:0xf6
	global_load_lds_dwordx4 v[8:9], off
	v_lshl_add_u64 v[4:5], v[4:5], 0, s[84:85]
	s_mov_b32 m0, s39
	s_add_u32 s8, s24, 0x40080
	v_bitop3_b32 v22, v20, s9, v21 bitop3:0xde
	v_mov_b64_e32 v[230:231], v[4:5]
	global_load_lds_dwordx4 v[4:5], off
	v_lshl_add_u64 v[4:5], v[6:7], 0, s[84:85]
	s_mov_b32 m0, s40
	s_addc_u32 s9, s25, 0
	v_mov_b64_e32 v[232:233], v[4:5]
	global_load_lds_dwordx4 v[4:5], off
	s_add_i32 m0, s17, 0x1c000
	v_lshl_add_u64 v[4:5], s[8:9], 0, v[136:137]
	global_load_lds_dwordx4 v[4:5], off
	v_lshl_add_u64 v[4:5], s[8:9], 0, v[132:133]
	s_add_i32 m0, s17, 0x1e000
	s_lshl_b32 s7, s7, 8
	global_load_lds_dwordx4 v[4:5], off
	v_lshlrev_b32_e32 v4, 14, v16
	v_and_b32_e32 v4, 0xffff8000, v4
	v_lshl_add_u32 v4, v15, 11, v4
	v_and_b32_e32 v5, 1, v16
	v_lshl_or_b32 v4, v5, 6, v4
	v_lshl_add_u32 v140, v17, 1, v4
	v_lshlrev_b32_e32 v4, 14, v12
	s_add_i32 s7, s7, 0
	v_and_b32_e32 v4, 0xffff8000, v4
	s_waitcnt vmcnt(6)
	s_add_i32 s7, s7, 0x20000
	v_lshl_add_u32 v4, v13, 11, v4
	v_and_b32_e32 v5, 1, v12
	s_cmpk_lt_u32 s6, 0x100
	v_lshl_or_b32 v4, v5, 6, v4
	v_add_u32_e32 v145, s7, v18
	s_cselect_b64 s[6:7], -1, 0
	v_or_b32_e32 v146, s10, v19
	v_mov_b32_e32 v141, v2
	v_lshl_add_u32 v142, v14, 1, v4
	v_mov_b32_e32 v143, v2
	s_mov_b32 s44, 0
	v_add_u32_e32 v147, 0, v22
	s_mov_b32 s41, 0
	s_barrier
	s_branch .LBB0_2318

; #define PG8_STAGE(bufoff, gbase, voff) do { _Pragma("unroll") for (int _i = 0; _i < 2; ++_i) \
;         __builtin_amdgcn_global_load_lds((const unsigned*)((const char*)(gbase) + (voff)[_i]), (LAS unsigned*)(lds + (bufoff) + ldsw + _i * 8192), 16, 0, 0); } while (0)
; #define PG8_WAIT_V(n) asm volatile("s_waitcnt vmcnt(" #n ")" ::: "memory")
; #define PG8_BAR __builtin_amdgcn_s_barrier()
; template <class Epi, bool ALIGN_EPI>
; DI void gemm_phase(LAS unsigned char* lds, const Sched& S, const Epi& E, int tid) {
;     const int wid = __builtin_amdgcn_readfirstlane(tid >> 6), lane = tid & 63, wr = wid >> 2, wc = wid & 3, fr = lane & 15, fq = lane >> 4;
;     const int lda = S.lda, ldb = S.ldb;
;     unsigned voffA[2], voffB[2];
; #pragma unroll
;     for (int i = 0; i < 2; ++i) { int R, C; stage_rc(tid * 16 + i * 8192, R, C); const int Rb = (R & ~31) + perm32(R & 31);
;         voffA[i] = (unsigned)(R * lda + C) * 2u; voffB[i] = (unsigned)(Rb * ldb + C) * 2u; }
;     const size_t kstep = (size_t)(BK * 2);
;     const size_t hstepA = (size_t)HALF * lda * 2, hstepB = (size_t)HALF * ldb * 2;
;     const unsigned ldsw = (unsigned)wid * 1024u;
;     const int aoff = lds_byte(wr * 64 + fr, fq * 8), boff = lds_byte(wc * 32 + fr, fq * 8);
;     ...
;     PG8_STAGE(PG8_SB(0, 0), cB, voffB); PG8_STAGE(PG8_SB(0, 1), cB + hstepB, voffB); PG8_STAGE(PG8_SA(0, 0), cA, voffA); PG8_STAGE(PG8_SA(0, 1), cA + hstepA, voffA);
;     if (wr == 1) PG8_BAR;
;     PG8_WAIT_V(2); PG8_BAR;
;     PG8_STAGE(PG8_SB(1, 0), cB + kstep, voffB); PG8_STAGE(PG8_SA(1, 0), cA + kstep, voffA); PG8_STAGE(PG8_SB(1, 1), cB + hstepB + kstep, voffB);
;     PG8_WAIT_V(6); PG8_BAR;
.LBB0_2395:
	v_bfe_u32 v21, v0, 4, 2
	v_and_b32_e32 v20, 15, v0
	v_lshlrev_b32_e32 v23, 4, v21
	v_lshl_or_b32 v3, s3, 6, v20
	v_lshl_or_b32 v20, v20, 6, v23
	v_lshlrev_b32_e32 v23, 2, v0
	s_and_b32 s43, s2, 3
	s_lshl_b32 s2, s3, 13
	v_and_b32_e32 v23, 32, v23
	s_add_i32 m0, s39, 0x18000
	v_lshl_add_u64 v[10:11], v[10:11], 0, s[84:85]
	v_bitop3_b32 v24, v20, s2, v23 bitop3:0xde
	s_lshl_b32 s2, s43, 12
	s_waitcnt vmcnt(2)
	s_barrier
	global_load_lds_dwordx4 v[10:11], off
	v_lshl_add_u64 v[8:9], v[8:9], 0, s[84:85]
	s_add_i32 m0, s39, 0x1a000
	s_add_i32 s44, s39, 0x8000
	s_add_i32 s45, s39, 0xa000
	v_bitop3_b32 v161, s2, v20, v23 bitop3:0xf6
	global_load_lds_dwordx4 v[8:9], off
	v_lshl_add_u64 v[4:5], v[4:5], 0, s[84:85]
	s_mov_b32 m0, s44
	s_add_u32 s2, s22, 0x104080
	v_mov_b64_e32 v[230:231], v[4:5]
	global_load_lds_dwordx4 v[4:5], off
	v_lshl_add_u64 v[4:5], v[6:7], 0, s[84:85]
	s_mov_b32 m0, s45
	s_addc_u32 s3, s23, 0
	v_mov_b64_e32 v[232:233], v[4:5]
	global_load_lds_dwordx4 v[4:5], off
	s_add_i32 m0, s39, 0x1c000
	v_lshl_add_u64 v[4:5], s[2:3], 0, v[164:165]
	global_load_lds_dwordx4 v[4:5], off
	v_lshl_add_u64 v[4:5], s[2:3], 0, v[168:169]
	s_add_i32 m0, s39, 0x1e000
	s_movk_i32 s14, 0x1040
	global_load_lds_dwordx4 v[4:5], off
	s_cmpk_lt_u32 s6, 0x100
	v_lshrrev_b32_e32 v5, 1, v12
	v_mul_lo_u32 v4, v14, s14
	s_mov_b32 s15, 0x10400
	s_cselect_b64 s[6:7], -1, 0
	s_add_u32 s47, s96, 0x1ff00000
	v_mad_u64_u32 v[4:5], s[12:13], v5, s15, v[4:5]
	s_addc_u32 s48, s97, 0
	v_or_b32_e32 v4, v4, v13
	s_add_u32 s8, s96, 0xff00000
	v_add_lshl_u32 v4, v4, v15, 1
	v_mov_b32_e32 v5, v2
	s_mov_b64 s[16:17], 0x104080
	s_mul_i32 s10, s90, 0x480000
	s_addc_u32 s9, s97, 0
	v_lshl_add_u64 v[170:171], v[4:5], 0, s[16:17]
	v_lshrrev_b32_e32 v5, 1, v16
	v_mul_lo_u32 v4, v18, s14
	s_add_u32 s10, s96, s10
	v_mad_u64_u32 v[4:5], s[12:13], v5, s15, v[4:5]
	s_waitcnt vmcnt(6)
	s_addc_u32 s11, s97, 0
	v_or_b32_e32 v4, v4, v17
	v_lshlrev_b32_e32 v22, 3, v21
	s_add_u32 s10, s10, 0x24580000
	v_add_lshl_u32 v4, v4, v19, 1
	v_mov_b32_e32 v5, v2
	v_lshl_or_b32 v192, s43, 5, v22
	s_mov_b32 s46, 0
	v_cmp_eq_u32_e64 s[2:3], 0, v21
	s_addc_u32 s11, s11, 0
	v_lshl_add_u64 v[172:173], v[4:5], 0, s[16:17]
	v_add_u32_e32 v193, 0, v24
	s_barrier
	s_branch .LBB0_2398
